# plus: MFMA order per 16-block changed to same-accumulator pairs back to back (k0,k1), accumulate order unchanged
# speedup vs baseline: 1.0064x; 1.0012x over previous
.LBB0_120:
	ds_read_b128 v[128:131], v178
	ds_read_b128 v[132:135], v178 offset:1024
	ds_read_b128 v[154:157], v178 offset:2048
	ds_read_b128 v[158:161], v178 offset:3072
	ds_read_b128 v[162:165], v179
	ds_read_b128 v[166:169], v179 offset:1024
	ds_read_b128 v[182:185], v179 offset:2048
	ds_read_b128 v[186:189], v179 offset:3072
	s_add_u32 s67, s88, 0xfffc0080
	s_addc_u32 s68, s89, -1
	s_cmp_eq_u32 s66, 12
	s_cselect_b32 s93, s52, s68
	s_cselect_b32 s92, s53, s67
	s_cselect_b32 s91, s56, s59
	s_cselect_b32 s90, s57, s58
	v_lshl_add_u64 v[170:171], s[88:89], 0, v[144:145]
	s_add_i32 m0, s17, 0xc000
	ds_read_b128 v[190:193], v180
	ds_read_b128 v[194:197], v180 offset:1024
	ds_read_b128 v[198:201], v180 offset:2048
	ds_read_b128 v[202:205], v180 offset:3072
	ds_read_b128 v[206:209], v180 offset:4096
	ds_read_b128 v[210:213], v180 offset:5120
	ds_read_b128 v[214:217], v180 offset:6144
	ds_read_b128 v[218:221], v180 offset:7168
	global_load_lds_dwordx4 v[170:171], off
	v_lshl_add_u64 v[170:171], s[88:89], 0, v[148:149]
	s_add_i32 m0, s17, 0xe000
	s_nop 0
	global_load_lds_dwordx4 v[170:171], off
	s_waitcnt vmcnt(8)
	s_waitcnt lgkmcnt(0)
	s_barrier
	s_setprio 1
	v_mfma_f32_16x16x32_bf16 v[124:127], v[128:131], v[190:193], v[124:127]
	v_mfma_f32_16x16x32_bf16 v[124:127], v[132:135], v[194:197], v[124:127]
	v_mfma_f32_16x16x32_bf16 v[116:119], v[154:157], v[190:193], v[116:119]
	v_mfma_f32_16x16x32_bf16 v[116:119], v[158:161], v[194:197], v[116:119]
	v_mfma_f32_16x16x32_bf16 v[108:111], v[128:131], v[198:201], v[108:111]
	v_mfma_f32_16x16x32_bf16 v[108:111], v[132:135], v[202:205], v[108:111]
	v_mfma_f32_16x16x32_bf16 v[100:103], v[154:157], v[198:201], v[100:103]
	v_mfma_f32_16x16x32_bf16 v[100:103], v[158:161], v[202:205], v[100:103]
	v_mfma_f32_16x16x32_bf16 v[92:95], v[128:131], v[206:209], v[92:95]
	v_mfma_f32_16x16x32_bf16 v[92:95], v[132:135], v[210:213], v[92:95]
	v_mfma_f32_16x16x32_bf16 v[84:87], v[154:157], v[206:209], v[84:87]
	v_mfma_f32_16x16x32_bf16 v[84:87], v[158:161], v[210:213], v[84:87]
	v_mfma_f32_16x16x32_bf16 v[76:79], v[128:131], v[214:217], v[76:79]
	v_mfma_f32_16x16x32_bf16 v[76:79], v[132:135], v[218:221], v[76:79]
	v_mfma_f32_16x16x32_bf16 v[68:71], v[154:157], v[214:217], v[68:71]
	v_mfma_f32_16x16x32_bf16 v[68:71], v[158:161], v[218:221], v[68:71]
	v_mfma_f32_16x16x32_bf16 v[120:123], v[162:165], v[190:193], v[120:123]
	v_mfma_f32_16x16x32_bf16 v[120:123], v[166:169], v[194:197], v[120:123]
	v_mfma_f32_16x16x32_bf16 v[112:115], v[182:185], v[190:193], v[112:115]
	v_mfma_f32_16x16x32_bf16 v[112:115], v[186:189], v[194:197], v[112:115]
	v_mfma_f32_16x16x32_bf16 v[104:107], v[162:165], v[198:201], v[104:107]
	v_mfma_f32_16x16x32_bf16 v[104:107], v[166:169], v[202:205], v[104:107]
	v_mfma_f32_16x16x32_bf16 v[96:99], v[182:185], v[198:201], v[96:99]
	v_mfma_f32_16x16x32_bf16 v[96:99], v[186:189], v[202:205], v[96:99]
	v_mfma_f32_16x16x32_bf16 v[88:91], v[162:165], v[206:209], v[88:91]
	v_mfma_f32_16x16x32_bf16 v[88:91], v[166:169], v[210:213], v[88:91]
	v_mfma_f32_16x16x32_bf16 v[80:83], v[182:185], v[206:209], v[80:83]
	v_mfma_f32_16x16x32_bf16 v[80:83], v[186:189], v[210:213], v[80:83]
	s_setprio 3
	s_barrier
	v_mfma_f32_16x16x32_bf16 v[72:75], v[162:165], v[214:217], v[72:75]
	v_mfma_f32_16x16x32_bf16 v[72:75], v[166:169], v[218:221], v[72:75]
	v_mfma_f32_16x16x32_bf16 v[64:67], v[182:185], v[214:217], v[64:67]
	v_mfma_f32_16x16x32_bf16 v[64:67], v[186:189], v[218:221], v[64:67]
	s_setprio 0
	s_add_i32 s67, s25, s16
	v_lshl_add_u64 v[170:171], s[90:91], 0, v[140:141]
	s_mov_b32 m0, s67
	ds_read_b128 v[190:193], v180 offset:16384
	ds_read_b128 v[194:197], v180 offset:17408
	ds_read_b128 v[198:201], v180 offset:18432
	ds_read_b128 v[202:205], v180 offset:19456
	ds_read_b128 v[206:209], v180 offset:20480
	ds_read_b128 v[210:213], v180 offset:21504
	ds_read_b128 v[214:217], v180 offset:22528
	ds_read_b128 v[218:221], v180 offset:23552
	global_load_lds_dwordx4 v[170:171], off
	s_add_i32 m0, s67, 0x2000
	s_add_u32 s68, s90, 0x40000
	v_lshl_add_u64 v[222:223], s[90:91], 0, v[136:137]
	s_addc_u32 s69, s91, 0
	s_add_i32 s67, s26, s16
	global_load_lds_dwordx4 v[222:223], off
	v_lshl_add_u64 v[224:225], s[68:69], 0, v[140:141]
	s_mov_b32 m0, s67
	v_lshl_add_u64 v[226:227], s[92:93], 0, v[138:139]
	global_load_lds_dwordx4 v[224:225], off
	v_lshl_add_u64 v[224:225], s[68:69], 0, v[136:137]
	s_add_i32 m0, s67, 0x2000
	s_nop 0
	global_load_lds_dwordx4 v[224:225], off
	v_lshl_add_u64 v[224:225], s[92:93], 0, v[142:143]
	s_mov_b32 m0, s17
	s_nop 0
	global_load_lds_dwordx4 v[224:225], off
	s_mov_b32 m0, s18
	s_nop 0
	global_load_lds_dwordx4 v[226:227], off
	s_waitcnt vmcnt(8)
	s_waitcnt lgkmcnt(0)
	s_barrier
	s_setprio 1
	v_mfma_f32_16x16x32_bf16 v[60:63], v[128:131], v[190:193], v[60:63]
	v_mfma_f32_16x16x32_bf16 v[60:63], v[132:135], v[194:197], v[60:63]
	v_mfma_f32_16x16x32_bf16 v[52:55], v[154:157], v[190:193], v[52:55]
	v_mfma_f32_16x16x32_bf16 v[52:55], v[158:161], v[194:197], v[52:55]
	v_mfma_f32_16x16x32_bf16 v[44:47], v[128:131], v[198:201], v[44:47]
	v_mfma_f32_16x16x32_bf16 v[44:47], v[132:135], v[202:205], v[44:47]
	v_mfma_f32_16x16x32_bf16 v[36:39], v[154:157], v[198:201], v[36:39]
	v_mfma_f32_16x16x32_bf16 v[36:39], v[158:161], v[202:205], v[36:39]
	v_mfma_f32_16x16x32_bf16 v[28:31], v[128:131], v[206:209], v[28:31]
	v_mfma_f32_16x16x32_bf16 v[28:31], v[132:135], v[210:213], v[28:31]
	v_mfma_f32_16x16x32_bf16 v[20:23], v[154:157], v[206:209], v[20:23]
	v_mfma_f32_16x16x32_bf16 v[20:23], v[158:161], v[210:213], v[20:23]
	v_mfma_f32_16x16x32_bf16 v[12:15], v[128:131], v[214:217], v[12:15]
	v_mfma_f32_16x16x32_bf16 v[12:15], v[132:135], v[218:221], v[12:15]
	v_mfma_f32_16x16x32_bf16 v[4:7], v[154:157], v[214:217], v[4:7]
	v_mfma_f32_16x16x32_bf16 v[4:7], v[158:161], v[218:221], v[4:7]
	v_mfma_f32_16x16x32_bf16 v[56:59], v[162:165], v[190:193], v[56:59]
	v_mfma_f32_16x16x32_bf16 v[56:59], v[166:169], v[194:197], v[56:59]
	v_mfma_f32_16x16x32_bf16 v[48:51], v[182:185], v[190:193], v[48:51]
	v_mfma_f32_16x16x32_bf16 v[48:51], v[186:189], v[194:197], v[48:51]
	v_mfma_f32_16x16x32_bf16 v[40:43], v[162:165], v[198:201], v[40:43]
	v_mfma_f32_16x16x32_bf16 v[40:43], v[166:169], v[202:205], v[40:43]
	v_mfma_f32_16x16x32_bf16 v[32:35], v[182:185], v[198:201], v[32:35]
	v_mfma_f32_16x16x32_bf16 v[32:35], v[186:189], v[202:205], v[32:35]
	v_mfma_f32_16x16x32_bf16 v[24:27], v[162:165], v[206:209], v[24:27]
	v_mfma_f32_16x16x32_bf16 v[24:27], v[166:169], v[210:213], v[24:27]
	v_mfma_f32_16x16x32_bf16 v[16:19], v[182:185], v[206:209], v[16:19]
	v_mfma_f32_16x16x32_bf16 v[16:19], v[186:189], v[210:213], v[16:19]
	s_setprio 3
	s_barrier
	v_mfma_f32_16x16x32_bf16 v[8:11], v[162:165], v[214:217], v[8:11]
	v_mfma_f32_16x16x32_bf16 v[8:11], v[166:169], v[218:221], v[8:11]
	v_mfma_f32_16x16x32_bf16 v[0:3], v[182:185], v[214:217], v[0:3]
	v_mfma_f32_16x16x32_bf16 v[0:3], v[186:189], v[218:221], v[0:3]
	s_setprio 0
	s_add_i32 s67, 0, 0x18000
	s_add_i32 s73, 0, 0x1c000
	v_add_u32_e32 v158, s67, v175
	v_add_u32_e32 v186, s73, v175
	ds_read_b128 v[128:131], v158
	ds_read_b128 v[132:135], v158 offset:1024
	ds_read_b128 v[154:157], v158 offset:2048
	ds_read_b128 v[158:161], v158 offset:3072
	ds_read_b128 v[162:165], v186
	ds_read_b128 v[166:169], v186 offset:1024
	ds_read_b128 v[182:185], v186 offset:2048
	ds_read_b128 v[186:189], v186 offset:3072
	s_add_u32 s68, s92, 0x40000
	s_addc_u32 s69, s93, 0
	s_mov_b32 m0, s19
	v_lshl_add_u64 v[228:229], s[68:69], 0, v[142:143]
	ds_read_b128 v[190:193], v180 offset:32768
	ds_read_b128 v[194:197], v180 offset:33792
	ds_read_b128 v[198:201], v180 offset:34816
	ds_read_b128 v[202:205], v180 offset:35840
	ds_read_b128 v[206:209], v180 offset:36864
	ds_read_b128 v[210:213], v180 offset:37888
	ds_read_b128 v[214:217], v180 offset:38912
	ds_read_b128 v[218:221], v180 offset:39936
	global_load_lds_dwordx4 v[228:229], off
	v_lshl_add_u64 v[228:229], s[68:69], 0, v[138:139]
	s_mov_b32 m0, s20
	s_nop 0
	global_load_lds_dwordx4 v[228:229], off
	s_waitcnt vmcnt(8)
	s_waitcnt lgkmcnt(0)
	s_barrier
	s_setprio 1
	v_mfma_f32_16x16x32_bf16 v[124:127], v[128:131], v[190:193], v[124:127]
	v_mfma_f32_16x16x32_bf16 v[124:127], v[132:135], v[194:197], v[124:127]
	v_mfma_f32_16x16x32_bf16 v[116:119], v[154:157], v[190:193], v[116:119]
	v_mfma_f32_16x16x32_bf16 v[116:119], v[158:161], v[194:197], v[116:119]
	v_mfma_f32_16x16x32_bf16 v[108:111], v[128:131], v[198:201], v[108:111]
	v_mfma_f32_16x16x32_bf16 v[108:111], v[132:135], v[202:205], v[108:111]
	v_mfma_f32_16x16x32_bf16 v[100:103], v[154:157], v[198:201], v[100:103]
	v_mfma_f32_16x16x32_bf16 v[100:103], v[158:161], v[202:205], v[100:103]
	v_mfma_f32_16x16x32_bf16 v[92:95], v[128:131], v[206:209], v[92:95]
	v_mfma_f32_16x16x32_bf16 v[92:95], v[132:135], v[210:213], v[92:95]
	v_mfma_f32_16x16x32_bf16 v[84:87], v[154:157], v[206:209], v[84:87]
	v_mfma_f32_16x16x32_bf16 v[84:87], v[158:161], v[210:213], v[84:87]
	v_mfma_f32_16x16x32_bf16 v[76:79], v[128:131], v[214:217], v[76:79]
	v_mfma_f32_16x16x32_bf16 v[76:79], v[132:135], v[218:221], v[76:79]
	v_mfma_f32_16x16x32_bf16 v[68:71], v[154:157], v[214:217], v[68:71]
	v_mfma_f32_16x16x32_bf16 v[68:71], v[158:161], v[218:221], v[68:71]
	v_mfma_f32_16x16x32_bf16 v[120:123], v[162:165], v[190:193], v[120:123]
	v_mfma_f32_16x16x32_bf16 v[120:123], v[166:169], v[194:197], v[120:123]
	v_mfma_f32_16x16x32_bf16 v[112:115], v[182:185], v[190:193], v[112:115]
	v_mfma_f32_16x16x32_bf16 v[112:115], v[186:189], v[194:197], v[112:115]
	v_mfma_f32_16x16x32_bf16 v[104:107], v[162:165], v[198:201], v[104:107]
	v_mfma_f32_16x16x32_bf16 v[104:107], v[166:169], v[202:205], v[104:107]
	v_mfma_f32_16x16x32_bf16 v[96:99], v[182:185], v[198:201], v[96:99]
	v_mfma_f32_16x16x32_bf16 v[96:99], v[186:189], v[202:205], v[96:99]
	v_mfma_f32_16x16x32_bf16 v[88:91], v[162:165], v[206:209], v[88:91]
	v_mfma_f32_16x16x32_bf16 v[88:91], v[166:169], v[210:213], v[88:91]
	v_mfma_f32_16x16x32_bf16 v[80:83], v[182:185], v[206:209], v[80:83]
	v_mfma_f32_16x16x32_bf16 v[80:83], v[186:189], v[210:213], v[80:83]
	s_setprio 3
	s_barrier
	v_mfma_f32_16x16x32_bf16 v[72:75], v[162:165], v[214:217], v[72:75]
	v_mfma_f32_16x16x32_bf16 v[72:75], v[166:169], v[218:221], v[72:75]
	v_mfma_f32_16x16x32_bf16 v[64:67], v[182:185], v[214:217], v[64:67]
	v_mfma_f32_16x16x32_bf16 v[64:67], v[186:189], v[218:221], v[64:67]
	s_setprio 0
	s_add_i32 s67, s67, s16
	v_lshl_add_u64 v[170:171], v[170:171], 0, s[74:75]
	s_mov_b32 m0, s67
	ds_read_b128 v[190:193], v180 offset:49152
	ds_read_b128 v[194:197], v180 offset:50176
	ds_read_b128 v[198:201], v180 offset:51200
	ds_read_b128 v[202:205], v180 offset:52224
	ds_read_b128 v[206:209], v180 offset:53248
	ds_read_b128 v[210:213], v180 offset:54272
	ds_read_b128 v[214:217], v180 offset:55296
	ds_read_b128 v[218:221], v180 offset:56320
	global_load_lds_dwordx4 v[170:171], off
	s_add_i32 m0, s67, 0x2000
	s_add_u32 s68, s90, 0x40080
	v_lshl_add_u64 v[170:171], v[222:223], 0, s[74:75]
	s_addc_u32 s69, s91, 0
	s_add_i32 s67, s73, s16
	global_load_lds_dwordx4 v[170:171], off
	v_lshl_add_u64 v[170:171], s[68:69], 0, v[140:141]
	s_mov_b32 m0, s67
	s_nop 0
	global_load_lds_dwordx4 v[170:171], off
	v_lshl_add_u64 v[170:171], s[68:69], 0, v[136:137]
	s_add_i32 m0, s67, 0x2000
	s_nop 0
	global_load_lds_dwordx4 v[170:171], off
	v_lshl_add_u64 v[170:171], v[224:225], 0, s[74:75]
	s_mov_b32 m0, s23
	s_nop 0
	global_load_lds_dwordx4 v[170:171], off
	v_lshl_add_u64 v[170:171], v[226:227], 0, s[74:75]
	s_mov_b32 m0, s24
	s_nop 0
	global_load_lds_dwordx4 v[170:171], off
	s_waitcnt vmcnt(8)
	s_waitcnt lgkmcnt(0)
	s_barrier
	s_setprio 1
	v_mfma_f32_16x16x32_bf16 v[60:63], v[128:131], v[190:193], v[60:63]
	v_mfma_f32_16x16x32_bf16 v[60:63], v[132:135], v[194:197], v[60:63]
	v_mfma_f32_16x16x32_bf16 v[52:55], v[154:157], v[190:193], v[52:55]
	v_mfma_f32_16x16x32_bf16 v[52:55], v[158:161], v[194:197], v[52:55]
	v_mfma_f32_16x16x32_bf16 v[44:47], v[128:131], v[198:201], v[44:47]
	v_mfma_f32_16x16x32_bf16 v[44:47], v[132:135], v[202:205], v[44:47]
	v_mfma_f32_16x16x32_bf16 v[36:39], v[154:157], v[198:201], v[36:39]
	v_mfma_f32_16x16x32_bf16 v[36:39], v[158:161], v[202:205], v[36:39]
	v_mfma_f32_16x16x32_bf16 v[28:31], v[128:131], v[206:209], v[28:31]
	v_mfma_f32_16x16x32_bf16 v[28:31], v[132:135], v[210:213], v[28:31]
	v_mfma_f32_16x16x32_bf16 v[20:23], v[154:157], v[206:209], v[20:23]
	v_mfma_f32_16x16x32_bf16 v[20:23], v[158:161], v[210:213], v[20:23]
	v_mfma_f32_16x16x32_bf16 v[12:15], v[128:131], v[214:217], v[12:15]
	v_mfma_f32_16x16x32_bf16 v[12:15], v[132:135], v[218:221], v[12:15]
	v_mfma_f32_16x16x32_bf16 v[4:7], v[154:157], v[214:217], v[4:7]
	v_mfma_f32_16x16x32_bf16 v[4:7], v[158:161], v[218:221], v[4:7]
	v_mfma_f32_16x16x32_bf16 v[56:59], v[162:165], v[190:193], v[56:59]
	v_mfma_f32_16x16x32_bf16 v[56:59], v[166:169], v[194:197], v[56:59]
	v_mfma_f32_16x16x32_bf16 v[48:51], v[182:185], v[190:193], v[48:51]
	v_mfma_f32_16x16x32_bf16 v[48:51], v[186:189], v[194:197], v[48:51]
	v_mfma_f32_16x16x32_bf16 v[40:43], v[162:165], v[198:201], v[40:43]
	v_mfma_f32_16x16x32_bf16 v[40:43], v[166:169], v[202:205], v[40:43]
	v_mfma_f32_16x16x32_bf16 v[32:35], v[182:185], v[198:201], v[32:35]
	v_mfma_f32_16x16x32_bf16 v[32:35], v[186:189], v[202:205], v[32:35]
	v_mfma_f32_16x16x32_bf16 v[24:27], v[162:165], v[206:209], v[24:27]
	v_mfma_f32_16x16x32_bf16 v[24:27], v[166:169], v[210:213], v[24:27]
	v_mfma_f32_16x16x32_bf16 v[16:19], v[182:185], v[206:209], v[16:19]
	v_mfma_f32_16x16x32_bf16 v[16:19], v[186:189], v[210:213], v[16:19]
	s_setprio 3
	s_barrier
	v_mfma_f32_16x16x32_bf16 v[8:11], v[162:165], v[214:217], v[8:11]
	v_mfma_f32_16x16x32_bf16 v[8:11], v[166:169], v[218:221], v[8:11]
	v_mfma_f32_16x16x32_bf16 v[0:3], v[182:185], v[214:217], v[0:3]
	v_mfma_f32_16x16x32_bf16 v[0:3], v[186:189], v[218:221], v[0:3]
	s_setprio 0
	s_add_i32 s66, s66, 2
	s_add_u32 s88, s88, 0x100
	s_addc_u32 s89, s89, 0
	s_add_u32 s58, s58, 0x100
	s_addc_u32 s59, s59, 0
	s_cmp_gt_u32 s66, 13
	s_cbranch_scc0 .LBB0_120
	s_and_b64 vcc, exec, s[76:77]
	s_cbranch_vccz .LBB0_123
	s_barrier

.LBB0_272:
	ds_read_b128 v[120:123], v245
	ds_read_b128 v[124:127], v245 offset:1024
	ds_read_b128 v[128:131], v245 offset:2048
	ds_read_b128 v[132:135], v245 offset:3072
	ds_read_b128 v[144:147], v246
	ds_read_b128 v[148:151], v246 offset:1024
	ds_read_b128 v[152:155], v246 offset:2048
	ds_read_b128 v[156:159], v246 offset:3072
	s_add_u32 s59, s86, 0xfff50080
	s_addc_u32 s66, s87, -1
	s_cmp_eq_u32 s58, 40
	s_cselect_b32 s91, s11, s66
	s_cselect_b32 s90, s10, s59
	s_cselect_b32 s89, s85, s57
	s_cselect_b32 s88, s84, s56
	v_lshl_add_u64 v[204:205], s[86:87], 0, v[200:201]
	s_add_i32 m0, s16, 0xc000
	ds_read_b128 v[160:163], v247
	ds_read_b128 v[164:167], v247 offset:1024
	ds_read_b128 v[168:171], v247 offset:2048
	ds_read_b128 v[172:175], v247 offset:3072
	ds_read_b128 v[176:179], v247 offset:4096
	ds_read_b128 v[180:183], v247 offset:5120
	ds_read_b128 v[184:187], v247 offset:6144
	ds_read_b128 v[188:191], v247 offset:7168
	global_load_lds_dwordx4 v[204:205], off
	v_lshl_add_u64 v[204:205], s[86:87], 0, v[202:203]
	s_add_i32 m0, s16, 0xe000
	s_nop 0
	global_load_lds_dwordx4 v[204:205], off
	s_waitcnt vmcnt(8)
	s_waitcnt lgkmcnt(0)
	s_barrier
	s_setprio 1
	v_mfma_f32_16x16x32_bf16 v[140:143], v[120:123], v[160:163], v[140:143]
	v_mfma_f32_16x16x32_bf16 v[140:143], v[124:127], v[164:167], v[140:143]
	v_mfma_f32_16x16x32_bf16 v[136:139], v[128:131], v[160:163], v[136:139]
	v_mfma_f32_16x16x32_bf16 v[136:139], v[132:135], v[164:167], v[136:139]
	v_mfma_f32_16x16x32_bf16 v[108:111], v[120:123], v[168:171], v[108:111]
	v_mfma_f32_16x16x32_bf16 v[108:111], v[124:127], v[172:175], v[108:111]
	v_mfma_f32_16x16x32_bf16 v[104:107], v[128:131], v[168:171], v[104:107]
	v_mfma_f32_16x16x32_bf16 v[104:107], v[132:135], v[172:175], v[104:107]
	v_mfma_f32_16x16x32_bf16 v[92:95], v[120:123], v[176:179], v[92:95]
	v_mfma_f32_16x16x32_bf16 v[92:95], v[124:127], v[180:183], v[92:95]
	v_mfma_f32_16x16x32_bf16 v[88:91], v[128:131], v[176:179], v[88:91]
	v_mfma_f32_16x16x32_bf16 v[88:91], v[132:135], v[180:183], v[88:91]
	v_mfma_f32_16x16x32_bf16 v[76:79], v[120:123], v[184:187], v[76:79]
	v_mfma_f32_16x16x32_bf16 v[76:79], v[124:127], v[188:191], v[76:79]
	v_mfma_f32_16x16x32_bf16 v[72:75], v[128:131], v[184:187], v[72:75]
	v_mfma_f32_16x16x32_bf16 v[72:75], v[132:135], v[188:191], v[72:75]
	v_mfma_f32_16x16x32_bf16 v[116:119], v[144:147], v[160:163], v[116:119]
	v_mfma_f32_16x16x32_bf16 v[116:119], v[148:151], v[164:167], v[116:119]
	v_mfma_f32_16x16x32_bf16 v[112:115], v[152:155], v[160:163], v[112:115]
	v_mfma_f32_16x16x32_bf16 v[112:115], v[156:159], v[164:167], v[112:115]
	v_mfma_f32_16x16x32_bf16 v[100:103], v[144:147], v[168:171], v[100:103]
	v_mfma_f32_16x16x32_bf16 v[100:103], v[148:151], v[172:175], v[100:103]
	v_mfma_f32_16x16x32_bf16 v[96:99], v[152:155], v[168:171], v[96:99]
	v_mfma_f32_16x16x32_bf16 v[96:99], v[156:159], v[172:175], v[96:99]
	v_mfma_f32_16x16x32_bf16 v[84:87], v[144:147], v[176:179], v[84:87]
	v_mfma_f32_16x16x32_bf16 v[84:87], v[148:151], v[180:183], v[84:87]
	v_mfma_f32_16x16x32_bf16 v[80:83], v[152:155], v[176:179], v[80:83]
	v_mfma_f32_16x16x32_bf16 v[80:83], v[156:159], v[180:183], v[80:83]
	s_setprio 3
	s_barrier
	v_mfma_f32_16x16x32_bf16 v[68:71], v[144:147], v[184:187], v[68:71]
	v_mfma_f32_16x16x32_bf16 v[68:71], v[148:151], v[188:191], v[68:71]
	v_mfma_f32_16x16x32_bf16 v[64:67], v[152:155], v[184:187], v[64:67]
	v_mfma_f32_16x16x32_bf16 v[64:67], v[156:159], v[188:191], v[64:67]
	s_setprio 0
	s_add_i32 s59, s26, s15
	v_lshl_add_u64 v[204:205], s[88:89], 0, v[194:195]
	s_mov_b32 m0, s59
	ds_read_b128 v[160:163], v247 offset:16384
	ds_read_b128 v[164:167], v247 offset:17408
	ds_read_b128 v[168:171], v247 offset:18432
	ds_read_b128 v[172:175], v247 offset:19456
	ds_read_b128 v[176:179], v247 offset:20480
	ds_read_b128 v[180:183], v247 offset:21504
	ds_read_b128 v[184:187], v247 offset:22528
	ds_read_b128 v[188:191], v247 offset:23552
	global_load_lds_dwordx4 v[204:205], off
	s_add_i32 m0, s59, 0x2000
	s_add_u32 s66, s88, 0xb0000
	v_lshl_add_u64 v[206:207], s[88:89], 0, v[198:199]
	s_addc_u32 s67, s89, 0
	s_add_i32 s59, s27, s15
	global_load_lds_dwordx4 v[206:207], off
	v_lshl_add_u64 v[208:209], s[66:67], 0, v[194:195]
	s_mov_b32 m0, s59
	v_lshl_add_u64 v[210:211], s[90:91], 0, v[196:197]
	global_load_lds_dwordx4 v[208:209], off
	v_lshl_add_u64 v[208:209], s[66:67], 0, v[198:199]
	s_add_i32 m0, s59, 0x2000
	s_nop 0
	global_load_lds_dwordx4 v[208:209], off
	v_lshl_add_u64 v[208:209], s[90:91], 0, v[192:193]
	s_mov_b32 m0, s16
	s_nop 0
	global_load_lds_dwordx4 v[208:209], off
	s_mov_b32 m0, s17
	s_nop 0
	global_load_lds_dwordx4 v[210:211], off
	s_waitcnt vmcnt(8)
	s_waitcnt lgkmcnt(0)
	s_barrier
	s_setprio 1
	v_mfma_f32_16x16x32_bf16 v[60:63], v[120:123], v[160:163], v[60:63]
	v_mfma_f32_16x16x32_bf16 v[60:63], v[124:127], v[164:167], v[60:63]
	v_mfma_f32_16x16x32_bf16 v[56:59], v[128:131], v[160:163], v[56:59]
	v_mfma_f32_16x16x32_bf16 v[56:59], v[132:135], v[164:167], v[56:59]
	v_mfma_f32_16x16x32_bf16 v[44:47], v[120:123], v[168:171], v[44:47]
	v_mfma_f32_16x16x32_bf16 v[44:47], v[124:127], v[172:175], v[44:47]
	v_mfma_f32_16x16x32_bf16 v[40:43], v[128:131], v[168:171], v[40:43]
	v_mfma_f32_16x16x32_bf16 v[40:43], v[132:135], v[172:175], v[40:43]
	v_mfma_f32_16x16x32_bf16 v[28:31], v[120:123], v[176:179], v[28:31]
	v_mfma_f32_16x16x32_bf16 v[28:31], v[124:127], v[180:183], v[28:31]
	v_mfma_f32_16x16x32_bf16 v[24:27], v[128:131], v[176:179], v[24:27]
	v_mfma_f32_16x16x32_bf16 v[24:27], v[132:135], v[180:183], v[24:27]
	v_mfma_f32_16x16x32_bf16 v[12:15], v[120:123], v[184:187], v[12:15]
	v_mfma_f32_16x16x32_bf16 v[12:15], v[124:127], v[188:191], v[12:15]
	v_mfma_f32_16x16x32_bf16 v[8:11], v[128:131], v[184:187], v[8:11]
	v_mfma_f32_16x16x32_bf16 v[8:11], v[132:135], v[188:191], v[8:11]
	v_mfma_f32_16x16x32_bf16 v[52:55], v[144:147], v[160:163], v[52:55]
	v_mfma_f32_16x16x32_bf16 v[52:55], v[148:151], v[164:167], v[52:55]
	v_mfma_f32_16x16x32_bf16 v[48:51], v[152:155], v[160:163], v[48:51]
	v_mfma_f32_16x16x32_bf16 v[48:51], v[156:159], v[164:167], v[48:51]
	v_mfma_f32_16x16x32_bf16 v[36:39], v[144:147], v[168:171], v[36:39]
	v_mfma_f32_16x16x32_bf16 v[36:39], v[148:151], v[172:175], v[36:39]
	v_mfma_f32_16x16x32_bf16 v[32:35], v[152:155], v[168:171], v[32:35]
	v_mfma_f32_16x16x32_bf16 v[32:35], v[156:159], v[172:175], v[32:35]
	v_mfma_f32_16x16x32_bf16 v[20:23], v[144:147], v[176:179], v[20:23]
	v_mfma_f32_16x16x32_bf16 v[20:23], v[148:151], v[180:183], v[20:23]
	v_mfma_f32_16x16x32_bf16 v[16:19], v[152:155], v[176:179], v[16:19]
	v_mfma_f32_16x16x32_bf16 v[16:19], v[156:159], v[180:183], v[16:19]
	s_setprio 3
	s_barrier
	v_mfma_f32_16x16x32_bf16 v[4:7], v[144:147], v[184:187], v[4:7]
	v_mfma_f32_16x16x32_bf16 v[4:7], v[148:151], v[188:191], v[4:7]
	v_mfma_f32_16x16x32_bf16 v[0:3], v[152:155], v[184:187], v[0:3]
	v_mfma_f32_16x16x32_bf16 v[0:3], v[156:159], v[188:191], v[0:3]
	s_setprio 0
	s_add_i32 s59, 0, 0x18000
	s_add_i32 s68, 0, 0x1c000
	v_add_u32_e32 v132, s59, v243
	v_add_u32_e32 v156, s68, v243
	ds_read_b128 v[120:123], v132
	ds_read_b128 v[124:127], v132 offset:1024
	ds_read_b128 v[128:131], v132 offset:2048
	ds_read_b128 v[132:135], v132 offset:3072
	ds_read_b128 v[144:147], v156
	ds_read_b128 v[148:151], v156 offset:1024
	ds_read_b128 v[152:155], v156 offset:2048
	ds_read_b128 v[156:159], v156 offset:3072
	s_add_u32 s66, s90, 0xb0000
	s_addc_u32 s67, s91, 0
	s_mov_b32 m0, s18
	v_lshl_add_u64 v[212:213], s[66:67], 0, v[192:193]
	ds_read_b128 v[160:163], v247 offset:32768
	ds_read_b128 v[164:167], v247 offset:33792
	ds_read_b128 v[168:171], v247 offset:34816
	ds_read_b128 v[172:175], v247 offset:35840
	ds_read_b128 v[176:179], v247 offset:36864
	ds_read_b128 v[180:183], v247 offset:37888
	ds_read_b128 v[184:187], v247 offset:38912
	ds_read_b128 v[188:191], v247 offset:39936
	global_load_lds_dwordx4 v[212:213], off
	v_lshl_add_u64 v[212:213], s[66:67], 0, v[196:197]
	s_mov_b32 m0, s19
	s_nop 0
	global_load_lds_dwordx4 v[212:213], off
	s_waitcnt vmcnt(8)
	s_waitcnt lgkmcnt(0)
	s_barrier
	s_setprio 1
	v_mfma_f32_16x16x32_bf16 v[140:143], v[120:123], v[160:163], v[140:143]
	v_mfma_f32_16x16x32_bf16 v[140:143], v[124:127], v[164:167], v[140:143]
	v_mfma_f32_16x16x32_bf16 v[136:139], v[128:131], v[160:163], v[136:139]
	v_mfma_f32_16x16x32_bf16 v[136:139], v[132:135], v[164:167], v[136:139]
	v_mfma_f32_16x16x32_bf16 v[108:111], v[120:123], v[168:171], v[108:111]
	v_mfma_f32_16x16x32_bf16 v[108:111], v[124:127], v[172:175], v[108:111]
	v_mfma_f32_16x16x32_bf16 v[104:107], v[128:131], v[168:171], v[104:107]
	v_mfma_f32_16x16x32_bf16 v[104:107], v[132:135], v[172:175], v[104:107]
	v_mfma_f32_16x16x32_bf16 v[92:95], v[120:123], v[176:179], v[92:95]
	v_mfma_f32_16x16x32_bf16 v[92:95], v[124:127], v[180:183], v[92:95]
	v_mfma_f32_16x16x32_bf16 v[88:91], v[128:131], v[176:179], v[88:91]
	v_mfma_f32_16x16x32_bf16 v[88:91], v[132:135], v[180:183], v[88:91]
	v_mfma_f32_16x16x32_bf16 v[76:79], v[120:123], v[184:187], v[76:79]
	v_mfma_f32_16x16x32_bf16 v[76:79], v[124:127], v[188:191], v[76:79]
	v_mfma_f32_16x16x32_bf16 v[72:75], v[128:131], v[184:187], v[72:75]
	v_mfma_f32_16x16x32_bf16 v[72:75], v[132:135], v[188:191], v[72:75]
	v_mfma_f32_16x16x32_bf16 v[116:119], v[144:147], v[160:163], v[116:119]
	v_mfma_f32_16x16x32_bf16 v[116:119], v[148:151], v[164:167], v[116:119]
	v_mfma_f32_16x16x32_bf16 v[112:115], v[152:155], v[160:163], v[112:115]
	v_mfma_f32_16x16x32_bf16 v[112:115], v[156:159], v[164:167], v[112:115]
	v_mfma_f32_16x16x32_bf16 v[100:103], v[144:147], v[168:171], v[100:103]
	v_mfma_f32_16x16x32_bf16 v[100:103], v[148:151], v[172:175], v[100:103]
	v_mfma_f32_16x16x32_bf16 v[96:99], v[152:155], v[168:171], v[96:99]
	v_mfma_f32_16x16x32_bf16 v[96:99], v[156:159], v[172:175], v[96:99]
	v_mfma_f32_16x16x32_bf16 v[84:87], v[144:147], v[176:179], v[84:87]
	v_mfma_f32_16x16x32_bf16 v[84:87], v[148:151], v[180:183], v[84:87]
	v_mfma_f32_16x16x32_bf16 v[80:83], v[152:155], v[176:179], v[80:83]
	v_mfma_f32_16x16x32_bf16 v[80:83], v[156:159], v[180:183], v[80:83]
	s_setprio 3
	s_barrier
	v_mfma_f32_16x16x32_bf16 v[68:71], v[144:147], v[184:187], v[68:71]
	v_mfma_f32_16x16x32_bf16 v[68:71], v[148:151], v[188:191], v[68:71]
	v_mfma_f32_16x16x32_bf16 v[64:67], v[152:155], v[184:187], v[64:67]
	v_mfma_f32_16x16x32_bf16 v[64:67], v[156:159], v[188:191], v[64:67]
	s_setprio 0
	s_add_i32 s59, s59, s15
	v_lshl_add_u64 v[204:205], v[204:205], 0, s[80:81]
	s_mov_b32 m0, s59
	ds_read_b128 v[160:163], v247 offset:49152
	ds_read_b128 v[164:167], v247 offset:50176
	ds_read_b128 v[168:171], v247 offset:51200
	ds_read_b128 v[172:175], v247 offset:52224
	ds_read_b128 v[176:179], v247 offset:53248
	ds_read_b128 v[180:183], v247 offset:54272
	ds_read_b128 v[184:187], v247 offset:55296
	ds_read_b128 v[188:191], v247 offset:56320
	global_load_lds_dwordx4 v[204:205], off
	s_add_i32 m0, s59, 0x2000
	s_add_u32 s66, s88, 0xb0080
	v_lshl_add_u64 v[204:205], v[206:207], 0, s[80:81]
	s_addc_u32 s67, s89, 0
	s_add_i32 s59, s68, s15
	global_load_lds_dwordx4 v[204:205], off
	v_lshl_add_u64 v[204:205], s[66:67], 0, v[194:195]
	s_mov_b32 m0, s59
	s_nop 0
	global_load_lds_dwordx4 v[204:205], off
	v_lshl_add_u64 v[204:205], s[66:67], 0, v[198:199]
	s_add_i32 m0, s59, 0x2000
	s_nop 0
	global_load_lds_dwordx4 v[204:205], off
	v_lshl_add_u64 v[204:205], v[208:209], 0, s[80:81]
	s_mov_b32 m0, s21
	s_nop 0
	global_load_lds_dwordx4 v[204:205], off
	v_lshl_add_u64 v[204:205], v[210:211], 0, s[80:81]
	s_mov_b32 m0, s22
	s_nop 0
	global_load_lds_dwordx4 v[204:205], off
	s_waitcnt vmcnt(8)
	s_waitcnt lgkmcnt(0)
	s_barrier
	s_setprio 1
	v_mfma_f32_16x16x32_bf16 v[60:63], v[120:123], v[160:163], v[60:63]
	v_mfma_f32_16x16x32_bf16 v[60:63], v[124:127], v[164:167], v[60:63]
	v_mfma_f32_16x16x32_bf16 v[56:59], v[128:131], v[160:163], v[56:59]
	v_mfma_f32_16x16x32_bf16 v[56:59], v[132:135], v[164:167], v[56:59]
	v_mfma_f32_16x16x32_bf16 v[44:47], v[120:123], v[168:171], v[44:47]
	v_mfma_f32_16x16x32_bf16 v[44:47], v[124:127], v[172:175], v[44:47]
	v_mfma_f32_16x16x32_bf16 v[40:43], v[128:131], v[168:171], v[40:43]
	v_mfma_f32_16x16x32_bf16 v[40:43], v[132:135], v[172:175], v[40:43]
	v_mfma_f32_16x16x32_bf16 v[28:31], v[120:123], v[176:179], v[28:31]
	v_mfma_f32_16x16x32_bf16 v[28:31], v[124:127], v[180:183], v[28:31]
	v_mfma_f32_16x16x32_bf16 v[24:27], v[128:131], v[176:179], v[24:27]
	v_mfma_f32_16x16x32_bf16 v[24:27], v[132:135], v[180:183], v[24:27]
	v_mfma_f32_16x16x32_bf16 v[12:15], v[120:123], v[184:187], v[12:15]
	v_mfma_f32_16x16x32_bf16 v[12:15], v[124:127], v[188:191], v[12:15]
	v_mfma_f32_16x16x32_bf16 v[8:11], v[128:131], v[184:187], v[8:11]
	v_mfma_f32_16x16x32_bf16 v[8:11], v[132:135], v[188:191], v[8:11]
	v_mfma_f32_16x16x32_bf16 v[52:55], v[144:147], v[160:163], v[52:55]
	v_mfma_f32_16x16x32_bf16 v[52:55], v[148:151], v[164:167], v[52:55]
	v_mfma_f32_16x16x32_bf16 v[48:51], v[152:155], v[160:163], v[48:51]
	v_mfma_f32_16x16x32_bf16 v[48:51], v[156:159], v[164:167], v[48:51]
	v_mfma_f32_16x16x32_bf16 v[36:39], v[144:147], v[168:171], v[36:39]
	v_mfma_f32_16x16x32_bf16 v[36:39], v[148:151], v[172:175], v[36:39]
	v_mfma_f32_16x16x32_bf16 v[32:35], v[152:155], v[168:171], v[32:35]
	v_mfma_f32_16x16x32_bf16 v[32:35], v[156:159], v[172:175], v[32:35]
	v_mfma_f32_16x16x32_bf16 v[20:23], v[144:147], v[176:179], v[20:23]
	v_mfma_f32_16x16x32_bf16 v[20:23], v[148:151], v[180:183], v[20:23]
	v_mfma_f32_16x16x32_bf16 v[16:19], v[152:155], v[176:179], v[16:19]
	v_mfma_f32_16x16x32_bf16 v[16:19], v[156:159], v[180:183], v[16:19]
	s_setprio 3
	s_barrier
	v_mfma_f32_16x16x32_bf16 v[4:7], v[144:147], v[184:187], v[4:7]
	v_mfma_f32_16x16x32_bf16 v[4:7], v[148:151], v[188:191], v[4:7]
	v_mfma_f32_16x16x32_bf16 v[0:3], v[152:155], v[184:187], v[0:3]
	v_mfma_f32_16x16x32_bf16 v[0:3], v[156:159], v[188:191], v[0:3]
	s_setprio 0
	s_add_i32 s58, s58, 2
	s_add_u32 s86, s86, 0x100
	s_addc_u32 s87, s87, 0
	s_add_u32 s56, s56, 0x100
	s_addc_u32 s57, s57, 0
	s_cmp_gt_u32 s58, 41
	s_cbranch_scc0 .LBB0_272
	s_and_b64 vcc, exec, s[82:83]
	s_cbranch_vccz .LBB0_275
	s_barrier

.LBB0_429:
	ds_read_b128 v[128:131], v203
	ds_read_b128 v[132:135], v203 offset:1024
	ds_read_b128 v[136:139], v203 offset:2048
	ds_read_b128 v[164:167], v203 offset:3072
	ds_read_b128 v[168:171], v204
	ds_read_b128 v[172:175], v204 offset:1024
	ds_read_b128 v[176:179], v204 offset:2048
	ds_read_b128 v[180:183], v204 offset:3072
	s_add_u32 s6, s88, 0xfffc0080
	s_addc_u32 s7, s89, -1
	s_cmp_eq_u32 s21, 12
	s_cselect_b32 vcc_hi, s15, s7
	s_cselect_b32 vcc_lo, s16, s6
	s_cselect_b32 s7, s17, s20
	s_cselect_b32 s6, s18, s19
	v_lshl_add_u64 v[196:197], s[88:89], 0, v[156:157]
	s_add_i32 m0, s58, 0xc000
	ds_read_b128 v[184:187], v205
	ds_read_b128 v[188:191], v205 offset:1024
	ds_read_b128 v[192:195], v205 offset:2048
	ds_read_b128 v[212:215], v205 offset:3072
	ds_read_b128 v[216:219], v205 offset:4096
	ds_read_b128 v[220:223], v205 offset:5120
	ds_read_b128 v[224:227], v205 offset:6144
	ds_read_b128 v[228:231], v205 offset:7168
	global_load_lds_dwordx4 v[196:197], off
	v_lshl_add_u64 v[196:197], s[88:89], 0, v[158:159]
	s_add_i32 m0, s58, 0xe000
	s_nop 0
	global_load_lds_dwordx4 v[196:197], off
	s_waitcnt vmcnt(8)
	s_waitcnt lgkmcnt(0)
	s_barrier
	s_setprio 1
	v_mfma_f32_16x16x32_bf16 v[124:127], v[128:131], v[184:187], v[124:127]
	v_mfma_f32_16x16x32_bf16 v[124:127], v[132:135], v[188:191], v[124:127]
	v_mfma_f32_16x16x32_bf16 v[116:119], v[136:139], v[184:187], v[116:119]
	v_mfma_f32_16x16x32_bf16 v[116:119], v[164:167], v[188:191], v[116:119]
	v_mfma_f32_16x16x32_bf16 v[108:111], v[128:131], v[192:195], v[108:111]
	v_mfma_f32_16x16x32_bf16 v[108:111], v[132:135], v[212:215], v[108:111]
	v_mfma_f32_16x16x32_bf16 v[100:103], v[136:139], v[192:195], v[100:103]
	v_mfma_f32_16x16x32_bf16 v[100:103], v[164:167], v[212:215], v[100:103]
	v_mfma_f32_16x16x32_bf16 v[92:95], v[128:131], v[216:219], v[92:95]
	v_mfma_f32_16x16x32_bf16 v[92:95], v[132:135], v[220:223], v[92:95]
	v_mfma_f32_16x16x32_bf16 v[84:87], v[136:139], v[216:219], v[84:87]
	v_mfma_f32_16x16x32_bf16 v[84:87], v[164:167], v[220:223], v[84:87]
	v_mfma_f32_16x16x32_bf16 v[76:79], v[128:131], v[224:227], v[76:79]
	v_mfma_f32_16x16x32_bf16 v[76:79], v[132:135], v[228:231], v[76:79]
	v_mfma_f32_16x16x32_bf16 v[68:71], v[136:139], v[224:227], v[68:71]
	v_mfma_f32_16x16x32_bf16 v[68:71], v[164:167], v[228:231], v[68:71]
	v_mfma_f32_16x16x32_bf16 v[120:123], v[168:171], v[184:187], v[120:123]
	v_mfma_f32_16x16x32_bf16 v[120:123], v[172:175], v[188:191], v[120:123]
	v_mfma_f32_16x16x32_bf16 v[112:115], v[176:179], v[184:187], v[112:115]
	v_mfma_f32_16x16x32_bf16 v[112:115], v[180:183], v[188:191], v[112:115]
	v_mfma_f32_16x16x32_bf16 v[104:107], v[168:171], v[192:195], v[104:107]
	v_mfma_f32_16x16x32_bf16 v[104:107], v[172:175], v[212:215], v[104:107]
	v_mfma_f32_16x16x32_bf16 v[96:99], v[176:179], v[192:195], v[96:99]
	v_mfma_f32_16x16x32_bf16 v[96:99], v[180:183], v[212:215], v[96:99]
	v_mfma_f32_16x16x32_bf16 v[88:91], v[168:171], v[216:219], v[88:91]
	v_mfma_f32_16x16x32_bf16 v[88:91], v[172:175], v[220:223], v[88:91]
	v_mfma_f32_16x16x32_bf16 v[80:83], v[176:179], v[216:219], v[80:83]
	v_mfma_f32_16x16x32_bf16 v[80:83], v[180:183], v[220:223], v[80:83]
	s_setprio 3
	s_barrier
	v_mfma_f32_16x16x32_bf16 v[72:75], v[168:171], v[224:227], v[72:75]
	v_mfma_f32_16x16x32_bf16 v[72:75], v[172:175], v[228:231], v[72:75]
	v_mfma_f32_16x16x32_bf16 v[64:67], v[176:179], v[224:227], v[64:67]
	v_mfma_f32_16x16x32_bf16 v[64:67], v[180:183], v[228:231], v[64:67]
	s_setprio 0
	s_add_i32 s22, s76, s57
	v_lshl_add_u64 v[196:197], s[6:7], 0, v[142:143]
	s_mov_b32 m0, s22
	ds_read_b128 v[184:187], v205 offset:16384
	ds_read_b128 v[188:191], v205 offset:17408
	ds_read_b128 v[192:195], v205 offset:18432
	ds_read_b128 v[212:215], v205 offset:19456
	ds_read_b128 v[216:219], v205 offset:20480
	ds_read_b128 v[220:223], v205 offset:21504
	ds_read_b128 v[224:227], v205 offset:22528
	ds_read_b128 v[228:231], v205 offset:23552
	global_load_lds_dwordx4 v[196:197], off
	s_add_i32 m0, s22, 0x2000
	s_add_u32 s22, s6, 0x40000
	v_lshl_add_u64 v[232:233], s[6:7], 0, v[146:147]
	s_addc_u32 s23, s7, 0
	s_add_i32 s24, s77, s57
	global_load_lds_dwordx4 v[232:233], off
	v_lshl_add_u64 v[234:235], s[22:23], 0, v[142:143]
	s_mov_b32 m0, s24
	v_lshl_add_u64 v[236:237], vcc, 0, v[144:145]
	global_load_lds_dwordx4 v[234:235], off
	v_lshl_add_u64 v[234:235], s[22:23], 0, v[146:147]
	s_add_i32 m0, s24, 0x2000
	s_nop 0
	global_load_lds_dwordx4 v[234:235], off
	v_lshl_add_u64 v[234:235], vcc, 0, v[140:141]
	s_mov_b32 m0, s58
	s_nop 0
	global_load_lds_dwordx4 v[234:235], off
	s_mov_b32 m0, s59
	s_nop 0
	global_load_lds_dwordx4 v[236:237], off
	s_waitcnt vmcnt(8)
	s_waitcnt lgkmcnt(0)
	s_barrier
	s_setprio 1
	v_mfma_f32_16x16x32_bf16 v[60:63], v[128:131], v[184:187], v[60:63]
	v_mfma_f32_16x16x32_bf16 v[60:63], v[132:135], v[188:191], v[60:63]
	v_mfma_f32_16x16x32_bf16 v[52:55], v[136:139], v[184:187], v[52:55]
	v_mfma_f32_16x16x32_bf16 v[52:55], v[164:167], v[188:191], v[52:55]
	v_mfma_f32_16x16x32_bf16 v[44:47], v[128:131], v[192:195], v[44:47]
	v_mfma_f32_16x16x32_bf16 v[44:47], v[132:135], v[212:215], v[44:47]
	v_mfma_f32_16x16x32_bf16 v[36:39], v[136:139], v[192:195], v[36:39]
	v_mfma_f32_16x16x32_bf16 v[36:39], v[164:167], v[212:215], v[36:39]
	v_mfma_f32_16x16x32_bf16 v[28:31], v[128:131], v[216:219], v[28:31]
	v_mfma_f32_16x16x32_bf16 v[28:31], v[132:135], v[220:223], v[28:31]
	v_mfma_f32_16x16x32_bf16 v[20:23], v[136:139], v[216:219], v[20:23]
	v_mfma_f32_16x16x32_bf16 v[20:23], v[164:167], v[220:223], v[20:23]
	v_mfma_f32_16x16x32_bf16 v[12:15], v[128:131], v[224:227], v[12:15]
	v_mfma_f32_16x16x32_bf16 v[12:15], v[132:135], v[228:231], v[12:15]
	v_mfma_f32_16x16x32_bf16 v[4:7], v[136:139], v[224:227], v[4:7]
	v_mfma_f32_16x16x32_bf16 v[4:7], v[164:167], v[228:231], v[4:7]
	v_mfma_f32_16x16x32_bf16 v[56:59], v[168:171], v[184:187], v[56:59]
	v_mfma_f32_16x16x32_bf16 v[56:59], v[172:175], v[188:191], v[56:59]
	v_mfma_f32_16x16x32_bf16 v[48:51], v[176:179], v[184:187], v[48:51]
	v_mfma_f32_16x16x32_bf16 v[48:51], v[180:183], v[188:191], v[48:51]
	v_mfma_f32_16x16x32_bf16 v[40:43], v[168:171], v[192:195], v[40:43]
	v_mfma_f32_16x16x32_bf16 v[40:43], v[172:175], v[212:215], v[40:43]
	v_mfma_f32_16x16x32_bf16 v[32:35], v[176:179], v[192:195], v[32:35]
	v_mfma_f32_16x16x32_bf16 v[32:35], v[180:183], v[212:215], v[32:35]
	v_mfma_f32_16x16x32_bf16 v[24:27], v[168:171], v[216:219], v[24:27]
	v_mfma_f32_16x16x32_bf16 v[24:27], v[172:175], v[220:223], v[24:27]
	v_mfma_f32_16x16x32_bf16 v[16:19], v[176:179], v[216:219], v[16:19]
	v_mfma_f32_16x16x32_bf16 v[16:19], v[180:183], v[220:223], v[16:19]
	s_setprio 3
	s_barrier
	v_mfma_f32_16x16x32_bf16 v[8:11], v[168:171], v[224:227], v[8:11]
	v_mfma_f32_16x16x32_bf16 v[8:11], v[172:175], v[228:231], v[8:11]
	v_mfma_f32_16x16x32_bf16 v[0:3], v[176:179], v[224:227], v[0:3]
	v_mfma_f32_16x16x32_bf16 v[0:3], v[180:183], v[228:231], v[0:3]
	s_setprio 0
	s_add_i32 s24, 0, 0x18000
	v_add_u32_e32 v150, s24, v200
	s_add_i32 s25, 0, 0x1c000
	ds_read_b128 v[128:131], v150
	ds_read_b128 v[132:135], v150 offset:1024
	ds_read_b128 v[136:139], v150 offset:2048
	ds_read_b128 v[164:167], v150 offset:3072
	v_add_u32_e32 v150, s25, v200
	ds_read_b128 v[168:171], v150
	ds_read_b128 v[172:175], v150 offset:1024
	ds_read_b128 v[176:179], v150 offset:2048
	ds_read_b128 v[180:183], v150 offset:3072
	s_add_u32 s22, vcc_lo, 0x40000
	s_addc_u32 s23, vcc_hi, 0
	s_mov_b32 m0, s66
	v_lshl_add_u64 v[238:239], s[22:23], 0, v[140:141]
	ds_read_b128 v[184:187], v205 offset:32768
	ds_read_b128 v[188:191], v205 offset:33792
	ds_read_b128 v[192:195], v205 offset:34816
	ds_read_b128 v[212:215], v205 offset:35840
	ds_read_b128 v[216:219], v205 offset:36864
	ds_read_b128 v[220:223], v205 offset:37888
	ds_read_b128 v[224:227], v205 offset:38912
	ds_read_b128 v[228:231], v205 offset:39936
	global_load_lds_dwordx4 v[238:239], off
	v_lshl_add_u64 v[238:239], s[22:23], 0, v[144:145]
	s_mov_b32 m0, s67
	s_nop 0
	global_load_lds_dwordx4 v[238:239], off
	s_waitcnt vmcnt(8)
	s_waitcnt lgkmcnt(0)
	s_barrier
	s_setprio 1
	v_mfma_f32_16x16x32_bf16 v[124:127], v[128:131], v[184:187], v[124:127]
	v_mfma_f32_16x16x32_bf16 v[124:127], v[132:135], v[188:191], v[124:127]
	v_mfma_f32_16x16x32_bf16 v[116:119], v[136:139], v[184:187], v[116:119]
	v_mfma_f32_16x16x32_bf16 v[116:119], v[164:167], v[188:191], v[116:119]
	v_mfma_f32_16x16x32_bf16 v[108:111], v[128:131], v[192:195], v[108:111]
	v_mfma_f32_16x16x32_bf16 v[108:111], v[132:135], v[212:215], v[108:111]
	v_mfma_f32_16x16x32_bf16 v[100:103], v[136:139], v[192:195], v[100:103]
	v_mfma_f32_16x16x32_bf16 v[100:103], v[164:167], v[212:215], v[100:103]
	v_mfma_f32_16x16x32_bf16 v[92:95], v[128:131], v[216:219], v[92:95]
	v_mfma_f32_16x16x32_bf16 v[92:95], v[132:135], v[220:223], v[92:95]
	v_mfma_f32_16x16x32_bf16 v[84:87], v[136:139], v[216:219], v[84:87]
	v_mfma_f32_16x16x32_bf16 v[84:87], v[164:167], v[220:223], v[84:87]
	v_mfma_f32_16x16x32_bf16 v[76:79], v[128:131], v[224:227], v[76:79]
	v_mfma_f32_16x16x32_bf16 v[76:79], v[132:135], v[228:231], v[76:79]
	v_mfma_f32_16x16x32_bf16 v[68:71], v[136:139], v[224:227], v[68:71]
	v_mfma_f32_16x16x32_bf16 v[68:71], v[164:167], v[228:231], v[68:71]
	v_mfma_f32_16x16x32_bf16 v[120:123], v[168:171], v[184:187], v[120:123]
	v_mfma_f32_16x16x32_bf16 v[120:123], v[172:175], v[188:191], v[120:123]
	v_mfma_f32_16x16x32_bf16 v[112:115], v[176:179], v[184:187], v[112:115]
	v_mfma_f32_16x16x32_bf16 v[112:115], v[180:183], v[188:191], v[112:115]
	v_mfma_f32_16x16x32_bf16 v[104:107], v[168:171], v[192:195], v[104:107]
	v_mfma_f32_16x16x32_bf16 v[104:107], v[172:175], v[212:215], v[104:107]
	v_mfma_f32_16x16x32_bf16 v[96:99], v[176:179], v[192:195], v[96:99]
	v_mfma_f32_16x16x32_bf16 v[96:99], v[180:183], v[212:215], v[96:99]
	v_mfma_f32_16x16x32_bf16 v[88:91], v[168:171], v[216:219], v[88:91]
	v_mfma_f32_16x16x32_bf16 v[88:91], v[172:175], v[220:223], v[88:91]
	v_mfma_f32_16x16x32_bf16 v[80:83], v[176:179], v[216:219], v[80:83]
	v_mfma_f32_16x16x32_bf16 v[80:83], v[180:183], v[220:223], v[80:83]
	s_setprio 3
	s_barrier
	v_mfma_f32_16x16x32_bf16 v[72:75], v[168:171], v[224:227], v[72:75]
	v_mfma_f32_16x16x32_bf16 v[72:75], v[172:175], v[228:231], v[72:75]
	v_mfma_f32_16x16x32_bf16 v[64:67], v[176:179], v[224:227], v[64:67]
	v_mfma_f32_16x16x32_bf16 v[64:67], v[180:183], v[228:231], v[64:67]
	s_setprio 0
	s_add_i32 s22, s24, s57
	v_lshl_add_u64 v[196:197], v[196:197], 0, s[80:81]
	s_mov_b32 m0, s22
	ds_read_b128 v[184:187], v205 offset:49152
	ds_read_b128 v[188:191], v205 offset:50176
	ds_read_b128 v[192:195], v205 offset:51200
	ds_read_b128 v[212:215], v205 offset:52224
	ds_read_b128 v[216:219], v205 offset:53248
	ds_read_b128 v[220:223], v205 offset:54272
	ds_read_b128 v[224:227], v205 offset:55296
	ds_read_b128 v[228:231], v205 offset:56320
	global_load_lds_dwordx4 v[196:197], off
	s_add_i32 m0, s22, 0x2000
	s_add_u32 s6, s6, 0x40080
	v_lshl_add_u64 v[196:197], v[232:233], 0, s[80:81]
	s_addc_u32 s7, s7, 0
	s_add_i32 s22, s25, s57
	global_load_lds_dwordx4 v[196:197], off
	v_lshl_add_u64 v[196:197], s[6:7], 0, v[142:143]
	s_mov_b32 m0, s22
	s_nop 0
	global_load_lds_dwordx4 v[196:197], off
	v_lshl_add_u64 v[196:197], s[6:7], 0, v[146:147]
	s_add_i32 m0, s22, 0x2000
	s_nop 0
	global_load_lds_dwordx4 v[196:197], off
	v_lshl_add_u64 v[196:197], v[234:235], 0, s[80:81]
	s_mov_b32 m0, s93
	s_nop 0
	global_load_lds_dwordx4 v[196:197], off
	v_lshl_add_u64 v[196:197], v[236:237], 0, s[80:81]
	s_mov_b32 m0, s69
	s_nop 0
	global_load_lds_dwordx4 v[196:197], off
	s_waitcnt vmcnt(8)
	s_waitcnt lgkmcnt(0)
	s_barrier
	s_setprio 1
	v_mfma_f32_16x16x32_bf16 v[60:63], v[128:131], v[184:187], v[60:63]
	v_mfma_f32_16x16x32_bf16 v[60:63], v[132:135], v[188:191], v[60:63]
	v_mfma_f32_16x16x32_bf16 v[52:55], v[136:139], v[184:187], v[52:55]
	v_mfma_f32_16x16x32_bf16 v[52:55], v[164:167], v[188:191], v[52:55]
	v_mfma_f32_16x16x32_bf16 v[44:47], v[128:131], v[192:195], v[44:47]
	v_mfma_f32_16x16x32_bf16 v[44:47], v[132:135], v[212:215], v[44:47]
	v_mfma_f32_16x16x32_bf16 v[36:39], v[136:139], v[192:195], v[36:39]
	v_mfma_f32_16x16x32_bf16 v[36:39], v[164:167], v[212:215], v[36:39]
	v_mfma_f32_16x16x32_bf16 v[28:31], v[128:131], v[216:219], v[28:31]
	v_mfma_f32_16x16x32_bf16 v[28:31], v[132:135], v[220:223], v[28:31]
	v_mfma_f32_16x16x32_bf16 v[20:23], v[136:139], v[216:219], v[20:23]
	v_mfma_f32_16x16x32_bf16 v[20:23], v[164:167], v[220:223], v[20:23]
	v_mfma_f32_16x16x32_bf16 v[12:15], v[128:131], v[224:227], v[12:15]
	v_mfma_f32_16x16x32_bf16 v[12:15], v[132:135], v[228:231], v[12:15]
	v_mfma_f32_16x16x32_bf16 v[4:7], v[136:139], v[224:227], v[4:7]
	v_mfma_f32_16x16x32_bf16 v[4:7], v[164:167], v[228:231], v[4:7]
	v_mfma_f32_16x16x32_bf16 v[56:59], v[168:171], v[184:187], v[56:59]
	v_mfma_f32_16x16x32_bf16 v[56:59], v[172:175], v[188:191], v[56:59]
	v_mfma_f32_16x16x32_bf16 v[48:51], v[176:179], v[184:187], v[48:51]
	v_mfma_f32_16x16x32_bf16 v[48:51], v[180:183], v[188:191], v[48:51]
	v_mfma_f32_16x16x32_bf16 v[40:43], v[168:171], v[192:195], v[40:43]
	v_mfma_f32_16x16x32_bf16 v[40:43], v[172:175], v[212:215], v[40:43]
	v_mfma_f32_16x16x32_bf16 v[32:35], v[176:179], v[192:195], v[32:35]
	v_mfma_f32_16x16x32_bf16 v[32:35], v[180:183], v[212:215], v[32:35]
	v_mfma_f32_16x16x32_bf16 v[24:27], v[168:171], v[216:219], v[24:27]
	v_mfma_f32_16x16x32_bf16 v[24:27], v[172:175], v[220:223], v[24:27]
	v_mfma_f32_16x16x32_bf16 v[16:19], v[176:179], v[216:219], v[16:19]
	v_mfma_f32_16x16x32_bf16 v[16:19], v[180:183], v[220:223], v[16:19]
	s_setprio 3
	s_barrier
	v_mfma_f32_16x16x32_bf16 v[8:11], v[168:171], v[224:227], v[8:11]
	v_mfma_f32_16x16x32_bf16 v[8:11], v[172:175], v[228:231], v[8:11]
	v_mfma_f32_16x16x32_bf16 v[0:3], v[176:179], v[224:227], v[0:3]
	v_mfma_f32_16x16x32_bf16 v[0:3], v[180:183], v[228:231], v[0:3]
	s_setprio 0
	s_add_i32 s21, s21, 2
	s_add_u32 s88, s88, 0x100
	s_addc_u32 s89, s89, 0
	s_add_u32 s19, s19, 0x100
	s_addc_u32 s20, s20, 0
	s_cmp_gt_u32 s21, 13
	s_cbranch_scc0 .LBB0_429
	s_and_b64 vcc, exec, s[82:83]
	s_cbranch_vccz .LBB0_432
	s_barrier

.LBB0_993:
	ds_read_b128 v[120:123], v245
	ds_read_b128 v[124:127], v245 offset:1024
	ds_read_b128 v[128:131], v245 offset:2048
	ds_read_b128 v[132:135], v245 offset:3072
	ds_read_b128 v[144:147], v246
	ds_read_b128 v[148:151], v246 offset:1024
	ds_read_b128 v[152:155], v246 offset:2048
	ds_read_b128 v[156:159], v246 offset:3072
	s_add_u32 s59, s82, 0xfffc0080
	s_addc_u32 s66, s83, -1
	s_cmp_eq_u32 s58, 12
	s_cselect_b32 s87, s53, s66
	s_cselect_b32 s86, s54, s59
	s_cselect_b32 s85, s51, s57
	s_cselect_b32 s84, s55, s56
	v_lshl_add_u64 v[204:205], s[82:83], 0, v[200:201]
	s_add_i32 m0, s16, 0xc000
	ds_read_b128 v[160:163], v247
	ds_read_b128 v[164:167], v247 offset:1024
	ds_read_b128 v[168:171], v247 offset:2048
	ds_read_b128 v[172:175], v247 offset:3072
	ds_read_b128 v[176:179], v247 offset:4096
	ds_read_b128 v[180:183], v247 offset:5120
	ds_read_b128 v[184:187], v247 offset:6144
	ds_read_b128 v[188:191], v247 offset:7168
	global_load_lds_dwordx4 v[204:205], off
	v_lshl_add_u64 v[204:205], s[82:83], 0, v[202:203]
	s_add_i32 m0, s16, 0xe000
	s_nop 0
	global_load_lds_dwordx4 v[204:205], off
	s_waitcnt vmcnt(8)
	s_waitcnt lgkmcnt(0)
	s_barrier
	s_setprio 1
	v_mfma_f32_16x16x32_bf16 v[140:143], v[120:123], v[160:163], v[140:143]
	v_mfma_f32_16x16x32_bf16 v[140:143], v[124:127], v[164:167], v[140:143]
	v_mfma_f32_16x16x32_bf16 v[136:139], v[128:131], v[160:163], v[136:139]
	v_mfma_f32_16x16x32_bf16 v[136:139], v[132:135], v[164:167], v[136:139]
	v_mfma_f32_16x16x32_bf16 v[108:111], v[120:123], v[168:171], v[108:111]
	v_mfma_f32_16x16x32_bf16 v[108:111], v[124:127], v[172:175], v[108:111]
	v_mfma_f32_16x16x32_bf16 v[104:107], v[128:131], v[168:171], v[104:107]
	v_mfma_f32_16x16x32_bf16 v[104:107], v[132:135], v[172:175], v[104:107]
	v_mfma_f32_16x16x32_bf16 v[92:95], v[120:123], v[176:179], v[92:95]
	v_mfma_f32_16x16x32_bf16 v[92:95], v[124:127], v[180:183], v[92:95]
	v_mfma_f32_16x16x32_bf16 v[88:91], v[128:131], v[176:179], v[88:91]
	v_mfma_f32_16x16x32_bf16 v[88:91], v[132:135], v[180:183], v[88:91]
	v_mfma_f32_16x16x32_bf16 v[76:79], v[120:123], v[184:187], v[76:79]
	v_mfma_f32_16x16x32_bf16 v[76:79], v[124:127], v[188:191], v[76:79]
	v_mfma_f32_16x16x32_bf16 v[72:75], v[128:131], v[184:187], v[72:75]
	v_mfma_f32_16x16x32_bf16 v[72:75], v[132:135], v[188:191], v[72:75]
	v_mfma_f32_16x16x32_bf16 v[116:119], v[144:147], v[160:163], v[116:119]
	v_mfma_f32_16x16x32_bf16 v[116:119], v[148:151], v[164:167], v[116:119]
	v_mfma_f32_16x16x32_bf16 v[112:115], v[152:155], v[160:163], v[112:115]
	v_mfma_f32_16x16x32_bf16 v[112:115], v[156:159], v[164:167], v[112:115]
	v_mfma_f32_16x16x32_bf16 v[100:103], v[144:147], v[168:171], v[100:103]
	v_mfma_f32_16x16x32_bf16 v[100:103], v[148:151], v[172:175], v[100:103]
	v_mfma_f32_16x16x32_bf16 v[96:99], v[152:155], v[168:171], v[96:99]
	v_mfma_f32_16x16x32_bf16 v[96:99], v[156:159], v[172:175], v[96:99]
	v_mfma_f32_16x16x32_bf16 v[84:87], v[144:147], v[176:179], v[84:87]
	v_mfma_f32_16x16x32_bf16 v[84:87], v[148:151], v[180:183], v[84:87]
	v_mfma_f32_16x16x32_bf16 v[80:83], v[152:155], v[176:179], v[80:83]
	v_mfma_f32_16x16x32_bf16 v[80:83], v[156:159], v[180:183], v[80:83]
	s_setprio 3
	s_barrier
	v_mfma_f32_16x16x32_bf16 v[68:71], v[144:147], v[184:187], v[68:71]
	v_mfma_f32_16x16x32_bf16 v[68:71], v[148:151], v[188:191], v[68:71]
	v_mfma_f32_16x16x32_bf16 v[64:67], v[152:155], v[184:187], v[64:67]
	v_mfma_f32_16x16x32_bf16 v[64:67], v[156:159], v[188:191], v[64:67]
	s_setprio 0
	s_add_i32 s59, s26, s15
	v_lshl_add_u64 v[204:205], s[84:85], 0, v[194:195]
	s_mov_b32 m0, s59
	ds_read_b128 v[160:163], v247 offset:16384
	ds_read_b128 v[164:167], v247 offset:17408
	ds_read_b128 v[168:171], v247 offset:18432
	ds_read_b128 v[172:175], v247 offset:19456
	ds_read_b128 v[176:179], v247 offset:20480
	ds_read_b128 v[180:183], v247 offset:21504
	ds_read_b128 v[184:187], v247 offset:22528
	ds_read_b128 v[188:191], v247 offset:23552
	global_load_lds_dwordx4 v[204:205], off
	s_add_i32 m0, s59, 0x2000
	s_add_u32 s66, s84, 0x40000
	v_lshl_add_u64 v[206:207], s[84:85], 0, v[198:199]
	s_addc_u32 s67, s85, 0
	s_add_i32 s59, s27, s15
	global_load_lds_dwordx4 v[206:207], off
	v_lshl_add_u64 v[208:209], s[66:67], 0, v[194:195]
	s_mov_b32 m0, s59
	v_lshl_add_u64 v[210:211], s[86:87], 0, v[196:197]
	global_load_lds_dwordx4 v[208:209], off
	v_lshl_add_u64 v[208:209], s[66:67], 0, v[198:199]
	s_add_i32 m0, s59, 0x2000
	s_nop 0
	global_load_lds_dwordx4 v[208:209], off
	v_lshl_add_u64 v[208:209], s[86:87], 0, v[192:193]
	s_mov_b32 m0, s16
	s_nop 0
	global_load_lds_dwordx4 v[208:209], off
	s_mov_b32 m0, s17
	s_nop 0
	global_load_lds_dwordx4 v[210:211], off
	s_waitcnt vmcnt(8)
	s_waitcnt lgkmcnt(0)
	s_barrier
	s_setprio 1
	v_mfma_f32_16x16x32_bf16 v[60:63], v[120:123], v[160:163], v[60:63]
	v_mfma_f32_16x16x32_bf16 v[60:63], v[124:127], v[164:167], v[60:63]
	v_mfma_f32_16x16x32_bf16 v[56:59], v[128:131], v[160:163], v[56:59]
	v_mfma_f32_16x16x32_bf16 v[56:59], v[132:135], v[164:167], v[56:59]
	v_mfma_f32_16x16x32_bf16 v[44:47], v[120:123], v[168:171], v[44:47]
	v_mfma_f32_16x16x32_bf16 v[44:47], v[124:127], v[172:175], v[44:47]
	v_mfma_f32_16x16x32_bf16 v[40:43], v[128:131], v[168:171], v[40:43]
	v_mfma_f32_16x16x32_bf16 v[40:43], v[132:135], v[172:175], v[40:43]
	v_mfma_f32_16x16x32_bf16 v[28:31], v[120:123], v[176:179], v[28:31]
	v_mfma_f32_16x16x32_bf16 v[28:31], v[124:127], v[180:183], v[28:31]
	v_mfma_f32_16x16x32_bf16 v[24:27], v[128:131], v[176:179], v[24:27]
	v_mfma_f32_16x16x32_bf16 v[24:27], v[132:135], v[180:183], v[24:27]
	v_mfma_f32_16x16x32_bf16 v[12:15], v[120:123], v[184:187], v[12:15]
	v_mfma_f32_16x16x32_bf16 v[12:15], v[124:127], v[188:191], v[12:15]
	v_mfma_f32_16x16x32_bf16 v[8:11], v[128:131], v[184:187], v[8:11]
	v_mfma_f32_16x16x32_bf16 v[8:11], v[132:135], v[188:191], v[8:11]
	v_mfma_f32_16x16x32_bf16 v[52:55], v[144:147], v[160:163], v[52:55]
	v_mfma_f32_16x16x32_bf16 v[52:55], v[148:151], v[164:167], v[52:55]
	v_mfma_f32_16x16x32_bf16 v[48:51], v[152:155], v[160:163], v[48:51]
	v_mfma_f32_16x16x32_bf16 v[48:51], v[156:159], v[164:167], v[48:51]
	v_mfma_f32_16x16x32_bf16 v[36:39], v[144:147], v[168:171], v[36:39]
	v_mfma_f32_16x16x32_bf16 v[36:39], v[148:151], v[172:175], v[36:39]
	v_mfma_f32_16x16x32_bf16 v[32:35], v[152:155], v[168:171], v[32:35]
	v_mfma_f32_16x16x32_bf16 v[32:35], v[156:159], v[172:175], v[32:35]
	v_mfma_f32_16x16x32_bf16 v[20:23], v[144:147], v[176:179], v[20:23]
	v_mfma_f32_16x16x32_bf16 v[20:23], v[148:151], v[180:183], v[20:23]
	v_mfma_f32_16x16x32_bf16 v[16:19], v[152:155], v[176:179], v[16:19]
	v_mfma_f32_16x16x32_bf16 v[16:19], v[156:159], v[180:183], v[16:19]
	s_setprio 3
	s_barrier
	v_mfma_f32_16x16x32_bf16 v[4:7], v[144:147], v[184:187], v[4:7]
	v_mfma_f32_16x16x32_bf16 v[4:7], v[148:151], v[188:191], v[4:7]
	v_mfma_f32_16x16x32_bf16 v[0:3], v[152:155], v[184:187], v[0:3]
	v_mfma_f32_16x16x32_bf16 v[0:3], v[156:159], v[188:191], v[0:3]
	s_setprio 0
	s_add_i32 s59, 0, 0x18000
	s_add_i32 s68, 0, 0x1c000
	v_add_u32_e32 v132, s59, v243
	v_add_u32_e32 v156, s68, v243
	ds_read_b128 v[120:123], v132
	ds_read_b128 v[124:127], v132 offset:1024
	ds_read_b128 v[128:131], v132 offset:2048
	ds_read_b128 v[132:135], v132 offset:3072
	ds_read_b128 v[144:147], v156
	ds_read_b128 v[148:151], v156 offset:1024
	ds_read_b128 v[152:155], v156 offset:2048
	ds_read_b128 v[156:159], v156 offset:3072
	s_add_u32 s66, s86, 0x40000
	s_addc_u32 s67, s87, 0
	s_mov_b32 m0, s18
	v_lshl_add_u64 v[212:213], s[66:67], 0, v[192:193]
	ds_read_b128 v[160:163], v247 offset:32768
	ds_read_b128 v[164:167], v247 offset:33792
	ds_read_b128 v[168:171], v247 offset:34816
	ds_read_b128 v[172:175], v247 offset:35840
	ds_read_b128 v[176:179], v247 offset:36864
	ds_read_b128 v[180:183], v247 offset:37888
	ds_read_b128 v[184:187], v247 offset:38912
	ds_read_b128 v[188:191], v247 offset:39936
	global_load_lds_dwordx4 v[212:213], off
	v_lshl_add_u64 v[212:213], s[66:67], 0, v[196:197]
	s_mov_b32 m0, s19
	s_nop 0
	global_load_lds_dwordx4 v[212:213], off
	s_waitcnt vmcnt(8)
	s_waitcnt lgkmcnt(0)
	s_barrier
	s_setprio 1
	v_mfma_f32_16x16x32_bf16 v[140:143], v[120:123], v[160:163], v[140:143]
	v_mfma_f32_16x16x32_bf16 v[140:143], v[124:127], v[164:167], v[140:143]
	v_mfma_f32_16x16x32_bf16 v[136:139], v[128:131], v[160:163], v[136:139]
	v_mfma_f32_16x16x32_bf16 v[136:139], v[132:135], v[164:167], v[136:139]
	v_mfma_f32_16x16x32_bf16 v[108:111], v[120:123], v[168:171], v[108:111]
	v_mfma_f32_16x16x32_bf16 v[108:111], v[124:127], v[172:175], v[108:111]
	v_mfma_f32_16x16x32_bf16 v[104:107], v[128:131], v[168:171], v[104:107]
	v_mfma_f32_16x16x32_bf16 v[104:107], v[132:135], v[172:175], v[104:107]
	v_mfma_f32_16x16x32_bf16 v[92:95], v[120:123], v[176:179], v[92:95]
	v_mfma_f32_16x16x32_bf16 v[92:95], v[124:127], v[180:183], v[92:95]
	v_mfma_f32_16x16x32_bf16 v[88:91], v[128:131], v[176:179], v[88:91]
	v_mfma_f32_16x16x32_bf16 v[88:91], v[132:135], v[180:183], v[88:91]
	v_mfma_f32_16x16x32_bf16 v[76:79], v[120:123], v[184:187], v[76:79]
	v_mfma_f32_16x16x32_bf16 v[76:79], v[124:127], v[188:191], v[76:79]
	v_mfma_f32_16x16x32_bf16 v[72:75], v[128:131], v[184:187], v[72:75]
	v_mfma_f32_16x16x32_bf16 v[72:75], v[132:135], v[188:191], v[72:75]
	v_mfma_f32_16x16x32_bf16 v[116:119], v[144:147], v[160:163], v[116:119]
	v_mfma_f32_16x16x32_bf16 v[116:119], v[148:151], v[164:167], v[116:119]
	v_mfma_f32_16x16x32_bf16 v[112:115], v[152:155], v[160:163], v[112:115]
	v_mfma_f32_16x16x32_bf16 v[112:115], v[156:159], v[164:167], v[112:115]
	v_mfma_f32_16x16x32_bf16 v[100:103], v[144:147], v[168:171], v[100:103]
	v_mfma_f32_16x16x32_bf16 v[100:103], v[148:151], v[172:175], v[100:103]
	v_mfma_f32_16x16x32_bf16 v[96:99], v[152:155], v[168:171], v[96:99]
	v_mfma_f32_16x16x32_bf16 v[96:99], v[156:159], v[172:175], v[96:99]
	v_mfma_f32_16x16x32_bf16 v[84:87], v[144:147], v[176:179], v[84:87]
	v_mfma_f32_16x16x32_bf16 v[84:87], v[148:151], v[180:183], v[84:87]
	v_mfma_f32_16x16x32_bf16 v[80:83], v[152:155], v[176:179], v[80:83]
	v_mfma_f32_16x16x32_bf16 v[80:83], v[156:159], v[180:183], v[80:83]
	s_setprio 3
	s_barrier
	v_mfma_f32_16x16x32_bf16 v[68:71], v[144:147], v[184:187], v[68:71]
	v_mfma_f32_16x16x32_bf16 v[68:71], v[148:151], v[188:191], v[68:71]
	v_mfma_f32_16x16x32_bf16 v[64:67], v[152:155], v[184:187], v[64:67]
	v_mfma_f32_16x16x32_bf16 v[64:67], v[156:159], v[188:191], v[64:67]
	s_setprio 0
	s_add_i32 s59, s59, s15
	v_lshl_add_u64 v[204:205], v[204:205], 0, s[46:47]
	s_mov_b32 m0, s59
	ds_read_b128 v[160:163], v247 offset:49152
	ds_read_b128 v[164:167], v247 offset:50176
	ds_read_b128 v[168:171], v247 offset:51200
	ds_read_b128 v[172:175], v247 offset:52224
	ds_read_b128 v[176:179], v247 offset:53248
	ds_read_b128 v[180:183], v247 offset:54272
	ds_read_b128 v[184:187], v247 offset:55296
	ds_read_b128 v[188:191], v247 offset:56320
	global_load_lds_dwordx4 v[204:205], off
	s_add_i32 m0, s59, 0x2000
	s_add_u32 s66, s84, 0x40080
	v_lshl_add_u64 v[204:205], v[206:207], 0, s[46:47]
	s_addc_u32 s67, s85, 0
	s_add_i32 s59, s68, s15
	global_load_lds_dwordx4 v[204:205], off
	v_lshl_add_u64 v[204:205], s[66:67], 0, v[194:195]
	s_mov_b32 m0, s59
	s_nop 0
	global_load_lds_dwordx4 v[204:205], off
	v_lshl_add_u64 v[204:205], s[66:67], 0, v[198:199]
	s_add_i32 m0, s59, 0x2000
	s_nop 0
	global_load_lds_dwordx4 v[204:205], off
	v_lshl_add_u64 v[204:205], v[208:209], 0, s[46:47]
	s_mov_b32 m0, s21
	s_nop 0
	global_load_lds_dwordx4 v[204:205], off
	v_lshl_add_u64 v[204:205], v[210:211], 0, s[46:47]
	s_mov_b32 m0, s22
	s_nop 0
	global_load_lds_dwordx4 v[204:205], off
	s_waitcnt vmcnt(8)
	s_waitcnt lgkmcnt(0)
	s_barrier
	s_setprio 1
	v_mfma_f32_16x16x32_bf16 v[60:63], v[120:123], v[160:163], v[60:63]
	v_mfma_f32_16x16x32_bf16 v[60:63], v[124:127], v[164:167], v[60:63]
	v_mfma_f32_16x16x32_bf16 v[56:59], v[128:131], v[160:163], v[56:59]
	v_mfma_f32_16x16x32_bf16 v[56:59], v[132:135], v[164:167], v[56:59]
	v_mfma_f32_16x16x32_bf16 v[44:47], v[120:123], v[168:171], v[44:47]
	v_mfma_f32_16x16x32_bf16 v[44:47], v[124:127], v[172:175], v[44:47]
	v_mfma_f32_16x16x32_bf16 v[40:43], v[128:131], v[168:171], v[40:43]
	v_mfma_f32_16x16x32_bf16 v[40:43], v[132:135], v[172:175], v[40:43]
	v_mfma_f32_16x16x32_bf16 v[28:31], v[120:123], v[176:179], v[28:31]
	v_mfma_f32_16x16x32_bf16 v[28:31], v[124:127], v[180:183], v[28:31]
	v_mfma_f32_16x16x32_bf16 v[24:27], v[128:131], v[176:179], v[24:27]
	v_mfma_f32_16x16x32_bf16 v[24:27], v[132:135], v[180:183], v[24:27]
	v_mfma_f32_16x16x32_bf16 v[12:15], v[120:123], v[184:187], v[12:15]
	v_mfma_f32_16x16x32_bf16 v[12:15], v[124:127], v[188:191], v[12:15]
	v_mfma_f32_16x16x32_bf16 v[8:11], v[128:131], v[184:187], v[8:11]
	v_mfma_f32_16x16x32_bf16 v[8:11], v[132:135], v[188:191], v[8:11]
	v_mfma_f32_16x16x32_bf16 v[52:55], v[144:147], v[160:163], v[52:55]
	v_mfma_f32_16x16x32_bf16 v[52:55], v[148:151], v[164:167], v[52:55]
	v_mfma_f32_16x16x32_bf16 v[48:51], v[152:155], v[160:163], v[48:51]
	v_mfma_f32_16x16x32_bf16 v[48:51], v[156:159], v[164:167], v[48:51]
	v_mfma_f32_16x16x32_bf16 v[36:39], v[144:147], v[168:171], v[36:39]
	v_mfma_f32_16x16x32_bf16 v[36:39], v[148:151], v[172:175], v[36:39]
	v_mfma_f32_16x16x32_bf16 v[32:35], v[152:155], v[168:171], v[32:35]
	v_mfma_f32_16x16x32_bf16 v[32:35], v[156:159], v[172:175], v[32:35]
	v_mfma_f32_16x16x32_bf16 v[20:23], v[144:147], v[176:179], v[20:23]
	v_mfma_f32_16x16x32_bf16 v[20:23], v[148:151], v[180:183], v[20:23]
	v_mfma_f32_16x16x32_bf16 v[16:19], v[152:155], v[176:179], v[16:19]
	v_mfma_f32_16x16x32_bf16 v[16:19], v[156:159], v[180:183], v[16:19]
	s_setprio 3
	s_barrier
	v_mfma_f32_16x16x32_bf16 v[4:7], v[144:147], v[184:187], v[4:7]
	v_mfma_f32_16x16x32_bf16 v[4:7], v[148:151], v[188:191], v[4:7]
	v_mfma_f32_16x16x32_bf16 v[0:3], v[152:155], v[184:187], v[0:3]
	v_mfma_f32_16x16x32_bf16 v[0:3], v[156:159], v[188:191], v[0:3]
	s_setprio 0
	s_add_i32 s58, s58, 2
	s_add_u32 s82, s82, 0x100
	s_addc_u32 s83, s83, 0
	s_add_u32 s56, s56, 0x100
	s_addc_u32 s57, s57, 0
	s_cmp_gt_u32 s58, 13
	s_cbranch_scc0 .LBB0_993
	s_and_b64 vcc, exec, s[48:49]
	s_cbranch_vccz .LBB0_996
	s_barrier

.LBB0_1148:
	ds_read_b128 v[146:149], v174
	ds_read_b128 v[150:153], v174 offset:1024
	ds_read_b128 v[154:157], v174 offset:2048
	ds_read_b128 v[158:161], v174 offset:3072
	ds_read_b128 v[162:165], v175
	ds_read_b128 v[178:181], v175 offset:1024
	ds_read_b128 v[182:185], v175 offset:2048
	ds_read_b128 v[186:189], v175 offset:3072
	s_add_u32 s67, s78, 0xfffc0080
	s_addc_u32 s68, s79, -1
	s_cmp_eq_u32 s66, 12
	s_cselect_b32 s83, s49, s68
	s_cselect_b32 s82, s54, s67
	s_cselect_b32 s81, s47, s59
	s_cselect_b32 s80, s55, s58
	v_lshl_add_u64 v[166:167], s[78:79], 0, v[136:137]
	s_add_i32 m0, s17, 0xc000
	ds_read_b128 v[190:193], v176
	ds_read_b128 v[194:197], v176 offset:1024
	ds_read_b128 v[198:201], v176 offset:2048
	ds_read_b128 v[202:205], v176 offset:3072
	ds_read_b128 v[206:209], v176 offset:4096
	ds_read_b128 v[210:213], v176 offset:5120
	ds_read_b128 v[214:217], v176 offset:6144
	ds_read_b128 v[218:221], v176 offset:7168
	global_load_lds_dwordx4 v[166:167], off
	v_lshl_add_u64 v[166:167], s[78:79], 0, v[140:141]
	s_add_i32 m0, s17, 0xe000
	s_nop 0
	global_load_lds_dwordx4 v[166:167], off
	s_waitcnt vmcnt(8)
	s_waitcnt lgkmcnt(0)
	s_barrier
	s_setprio 1
	v_mfma_f32_16x16x32_bf16 v[124:127], v[146:149], v[190:193], v[124:127]
	v_mfma_f32_16x16x32_bf16 v[124:127], v[150:153], v[194:197], v[124:127]
	v_mfma_f32_16x16x32_bf16 v[116:119], v[154:157], v[190:193], v[116:119]
	v_mfma_f32_16x16x32_bf16 v[116:119], v[158:161], v[194:197], v[116:119]
	v_mfma_f32_16x16x32_bf16 v[108:111], v[146:149], v[198:201], v[108:111]
	v_mfma_f32_16x16x32_bf16 v[108:111], v[150:153], v[202:205], v[108:111]
	v_mfma_f32_16x16x32_bf16 v[100:103], v[154:157], v[198:201], v[100:103]
	v_mfma_f32_16x16x32_bf16 v[100:103], v[158:161], v[202:205], v[100:103]
	v_mfma_f32_16x16x32_bf16 v[92:95], v[146:149], v[206:209], v[92:95]
	v_mfma_f32_16x16x32_bf16 v[92:95], v[150:153], v[210:213], v[92:95]
	v_mfma_f32_16x16x32_bf16 v[84:87], v[154:157], v[206:209], v[84:87]
	v_mfma_f32_16x16x32_bf16 v[84:87], v[158:161], v[210:213], v[84:87]
	v_mfma_f32_16x16x32_bf16 v[76:79], v[146:149], v[214:217], v[76:79]
	v_mfma_f32_16x16x32_bf16 v[76:79], v[150:153], v[218:221], v[76:79]
	v_mfma_f32_16x16x32_bf16 v[68:71], v[154:157], v[214:217], v[68:71]
	v_mfma_f32_16x16x32_bf16 v[68:71], v[158:161], v[218:221], v[68:71]
	v_mfma_f32_16x16x32_bf16 v[120:123], v[162:165], v[190:193], v[120:123]
	v_mfma_f32_16x16x32_bf16 v[120:123], v[178:181], v[194:197], v[120:123]
	v_mfma_f32_16x16x32_bf16 v[112:115], v[182:185], v[190:193], v[112:115]
	v_mfma_f32_16x16x32_bf16 v[112:115], v[186:189], v[194:197], v[112:115]
	v_mfma_f32_16x16x32_bf16 v[104:107], v[162:165], v[198:201], v[104:107]
	v_mfma_f32_16x16x32_bf16 v[104:107], v[178:181], v[202:205], v[104:107]
	v_mfma_f32_16x16x32_bf16 v[96:99], v[182:185], v[198:201], v[96:99]
	v_mfma_f32_16x16x32_bf16 v[96:99], v[186:189], v[202:205], v[96:99]
	v_mfma_f32_16x16x32_bf16 v[88:91], v[162:165], v[206:209], v[88:91]
	v_mfma_f32_16x16x32_bf16 v[88:91], v[178:181], v[210:213], v[88:91]
	v_mfma_f32_16x16x32_bf16 v[80:83], v[182:185], v[206:209], v[80:83]
	v_mfma_f32_16x16x32_bf16 v[80:83], v[186:189], v[210:213], v[80:83]
	s_setprio 3
	s_barrier
	v_mfma_f32_16x16x32_bf16 v[72:75], v[162:165], v[214:217], v[72:75]
	v_mfma_f32_16x16x32_bf16 v[72:75], v[178:181], v[218:221], v[72:75]
	v_mfma_f32_16x16x32_bf16 v[64:67], v[182:185], v[214:217], v[64:67]
	v_mfma_f32_16x16x32_bf16 v[64:67], v[186:189], v[218:221], v[64:67]
	s_setprio 0
	s_add_i32 s67, s25, s16
	v_lshl_add_u64 v[166:167], s[80:81], 0, v[132:133]
	s_mov_b32 m0, s67
	ds_read_b128 v[190:193], v176 offset:16384
	ds_read_b128 v[194:197], v176 offset:17408
	ds_read_b128 v[198:201], v176 offset:18432
	ds_read_b128 v[202:205], v176 offset:19456
	ds_read_b128 v[206:209], v176 offset:20480
	ds_read_b128 v[210:213], v176 offset:21504
	ds_read_b128 v[214:217], v176 offset:22528
	ds_read_b128 v[218:221], v176 offset:23552
	global_load_lds_dwordx4 v[166:167], off
	s_add_i32 m0, s67, 0x2000
	s_add_u32 s68, s80, 0x40000
	v_lshl_add_u64 v[222:223], s[80:81], 0, v[128:129]
	s_addc_u32 s69, s81, 0
	s_add_i32 s67, s26, s16
	global_load_lds_dwordx4 v[222:223], off
	v_lshl_add_u64 v[224:225], s[68:69], 0, v[132:133]
	s_mov_b32 m0, s67
	v_lshl_add_u64 v[226:227], s[82:83], 0, v[130:131]
	global_load_lds_dwordx4 v[224:225], off
	v_lshl_add_u64 v[224:225], s[68:69], 0, v[128:129]
	s_add_i32 m0, s67, 0x2000
	s_nop 0
	global_load_lds_dwordx4 v[224:225], off
	v_lshl_add_u64 v[224:225], s[82:83], 0, v[134:135]
	s_mov_b32 m0, s17
	s_nop 0
	global_load_lds_dwordx4 v[224:225], off
	s_mov_b32 m0, s18
	s_nop 0
	global_load_lds_dwordx4 v[226:227], off
	s_waitcnt vmcnt(8)
	s_waitcnt lgkmcnt(0)
	s_barrier
	s_setprio 1
	v_mfma_f32_16x16x32_bf16 v[60:63], v[146:149], v[190:193], v[60:63]
	v_mfma_f32_16x16x32_bf16 v[60:63], v[150:153], v[194:197], v[60:63]
	v_mfma_f32_16x16x32_bf16 v[52:55], v[154:157], v[190:193], v[52:55]
	v_mfma_f32_16x16x32_bf16 v[52:55], v[158:161], v[194:197], v[52:55]
	v_mfma_f32_16x16x32_bf16 v[44:47], v[146:149], v[198:201], v[44:47]
	v_mfma_f32_16x16x32_bf16 v[44:47], v[150:153], v[202:205], v[44:47]
	v_mfma_f32_16x16x32_bf16 v[36:39], v[154:157], v[198:201], v[36:39]
	v_mfma_f32_16x16x32_bf16 v[36:39], v[158:161], v[202:205], v[36:39]
	v_mfma_f32_16x16x32_bf16 v[28:31], v[146:149], v[206:209], v[28:31]
	v_mfma_f32_16x16x32_bf16 v[28:31], v[150:153], v[210:213], v[28:31]
	v_mfma_f32_16x16x32_bf16 v[20:23], v[154:157], v[206:209], v[20:23]
	v_mfma_f32_16x16x32_bf16 v[20:23], v[158:161], v[210:213], v[20:23]
	v_mfma_f32_16x16x32_bf16 v[12:15], v[146:149], v[214:217], v[12:15]
	v_mfma_f32_16x16x32_bf16 v[12:15], v[150:153], v[218:221], v[12:15]
	v_mfma_f32_16x16x32_bf16 v[4:7], v[154:157], v[214:217], v[4:7]
	v_mfma_f32_16x16x32_bf16 v[4:7], v[158:161], v[218:221], v[4:7]
	v_mfma_f32_16x16x32_bf16 v[56:59], v[162:165], v[190:193], v[56:59]
	v_mfma_f32_16x16x32_bf16 v[56:59], v[178:181], v[194:197], v[56:59]
	v_mfma_f32_16x16x32_bf16 v[48:51], v[182:185], v[190:193], v[48:51]
	v_mfma_f32_16x16x32_bf16 v[48:51], v[186:189], v[194:197], v[48:51]
	v_mfma_f32_16x16x32_bf16 v[40:43], v[162:165], v[198:201], v[40:43]
	v_mfma_f32_16x16x32_bf16 v[40:43], v[178:181], v[202:205], v[40:43]
	v_mfma_f32_16x16x32_bf16 v[32:35], v[182:185], v[198:201], v[32:35]
	v_mfma_f32_16x16x32_bf16 v[32:35], v[186:189], v[202:205], v[32:35]
	v_mfma_f32_16x16x32_bf16 v[24:27], v[162:165], v[206:209], v[24:27]
	v_mfma_f32_16x16x32_bf16 v[24:27], v[178:181], v[210:213], v[24:27]
	v_mfma_f32_16x16x32_bf16 v[16:19], v[182:185], v[206:209], v[16:19]
	v_mfma_f32_16x16x32_bf16 v[16:19], v[186:189], v[210:213], v[16:19]
	s_setprio 3
	s_barrier
	v_mfma_f32_16x16x32_bf16 v[8:11], v[162:165], v[214:217], v[8:11]
	v_mfma_f32_16x16x32_bf16 v[8:11], v[178:181], v[218:221], v[8:11]
	v_mfma_f32_16x16x32_bf16 v[0:3], v[182:185], v[214:217], v[0:3]
	v_mfma_f32_16x16x32_bf16 v[0:3], v[186:189], v[218:221], v[0:3]
	s_setprio 0
	s_add_i32 s67, 0, 0x18000
	s_add_i32 s73, 0, 0x1c000
	v_add_u32_e32 v158, s67, v171
	v_add_u32_e32 v186, s73, v171
	ds_read_b128 v[146:149], v158
	ds_read_b128 v[150:153], v158 offset:1024
	ds_read_b128 v[154:157], v158 offset:2048
	ds_read_b128 v[158:161], v158 offset:3072
	ds_read_b128 v[162:165], v186
	ds_read_b128 v[178:181], v186 offset:1024
	ds_read_b128 v[182:185], v186 offset:2048
	ds_read_b128 v[186:189], v186 offset:3072
	s_add_u32 s68, s82, 0x40000
	s_addc_u32 s69, s83, 0
	s_mov_b32 m0, s19
	v_lshl_add_u64 v[228:229], s[68:69], 0, v[134:135]
	ds_read_b128 v[190:193], v176 offset:32768
	ds_read_b128 v[194:197], v176 offset:33792
	ds_read_b128 v[198:201], v176 offset:34816
	ds_read_b128 v[202:205], v176 offset:35840
	ds_read_b128 v[206:209], v176 offset:36864
	ds_read_b128 v[210:213], v176 offset:37888
	ds_read_b128 v[214:217], v176 offset:38912
	ds_read_b128 v[218:221], v176 offset:39936
	global_load_lds_dwordx4 v[228:229], off
	v_lshl_add_u64 v[228:229], s[68:69], 0, v[130:131]
	s_mov_b32 m0, s20
	s_nop 0
	global_load_lds_dwordx4 v[228:229], off
	s_waitcnt vmcnt(8)
	s_waitcnt lgkmcnt(0)
	s_barrier
	s_setprio 1
	v_mfma_f32_16x16x32_bf16 v[124:127], v[146:149], v[190:193], v[124:127]
	v_mfma_f32_16x16x32_bf16 v[124:127], v[150:153], v[194:197], v[124:127]
	v_mfma_f32_16x16x32_bf16 v[116:119], v[154:157], v[190:193], v[116:119]
	v_mfma_f32_16x16x32_bf16 v[116:119], v[158:161], v[194:197], v[116:119]
	v_mfma_f32_16x16x32_bf16 v[108:111], v[146:149], v[198:201], v[108:111]
	v_mfma_f32_16x16x32_bf16 v[108:111], v[150:153], v[202:205], v[108:111]
	v_mfma_f32_16x16x32_bf16 v[100:103], v[154:157], v[198:201], v[100:103]
	v_mfma_f32_16x16x32_bf16 v[100:103], v[158:161], v[202:205], v[100:103]
	v_mfma_f32_16x16x32_bf16 v[92:95], v[146:149], v[206:209], v[92:95]
	v_mfma_f32_16x16x32_bf16 v[92:95], v[150:153], v[210:213], v[92:95]
	v_mfma_f32_16x16x32_bf16 v[84:87], v[154:157], v[206:209], v[84:87]
	v_mfma_f32_16x16x32_bf16 v[84:87], v[158:161], v[210:213], v[84:87]
	v_mfma_f32_16x16x32_bf16 v[76:79], v[146:149], v[214:217], v[76:79]
	v_mfma_f32_16x16x32_bf16 v[76:79], v[150:153], v[218:221], v[76:79]
	v_mfma_f32_16x16x32_bf16 v[68:71], v[154:157], v[214:217], v[68:71]
	v_mfma_f32_16x16x32_bf16 v[68:71], v[158:161], v[218:221], v[68:71]
	v_mfma_f32_16x16x32_bf16 v[120:123], v[162:165], v[190:193], v[120:123]
	v_mfma_f32_16x16x32_bf16 v[120:123], v[178:181], v[194:197], v[120:123]
	v_mfma_f32_16x16x32_bf16 v[112:115], v[182:185], v[190:193], v[112:115]
	v_mfma_f32_16x16x32_bf16 v[112:115], v[186:189], v[194:197], v[112:115]
	v_mfma_f32_16x16x32_bf16 v[104:107], v[162:165], v[198:201], v[104:107]
	v_mfma_f32_16x16x32_bf16 v[104:107], v[178:181], v[202:205], v[104:107]
	v_mfma_f32_16x16x32_bf16 v[96:99], v[182:185], v[198:201], v[96:99]
	v_mfma_f32_16x16x32_bf16 v[96:99], v[186:189], v[202:205], v[96:99]
	v_mfma_f32_16x16x32_bf16 v[88:91], v[162:165], v[206:209], v[88:91]
	v_mfma_f32_16x16x32_bf16 v[88:91], v[178:181], v[210:213], v[88:91]
	v_mfma_f32_16x16x32_bf16 v[80:83], v[182:185], v[206:209], v[80:83]
	v_mfma_f32_16x16x32_bf16 v[80:83], v[186:189], v[210:213], v[80:83]
	s_setprio 3
	s_barrier
	v_mfma_f32_16x16x32_bf16 v[72:75], v[162:165], v[214:217], v[72:75]
	v_mfma_f32_16x16x32_bf16 v[72:75], v[178:181], v[218:221], v[72:75]
	v_mfma_f32_16x16x32_bf16 v[64:67], v[182:185], v[214:217], v[64:67]
	v_mfma_f32_16x16x32_bf16 v[64:67], v[186:189], v[218:221], v[64:67]
	s_setprio 0
	s_add_i32 s67, s67, s16
	v_lshl_add_u64 v[166:167], v[166:167], 0, s[10:11]
	s_mov_b32 m0, s67
	ds_read_b128 v[190:193], v176 offset:49152
	ds_read_b128 v[194:197], v176 offset:50176
	ds_read_b128 v[198:201], v176 offset:51200
	ds_read_b128 v[202:205], v176 offset:52224
	ds_read_b128 v[206:209], v176 offset:53248
	ds_read_b128 v[210:213], v176 offset:54272
	ds_read_b128 v[214:217], v176 offset:55296
	ds_read_b128 v[218:221], v176 offset:56320
	global_load_lds_dwordx4 v[166:167], off
	s_add_i32 m0, s67, 0x2000
	s_add_u32 s68, s80, 0x40080
	v_lshl_add_u64 v[166:167], v[222:223], 0, s[10:11]
	s_addc_u32 s69, s81, 0
	s_add_i32 s67, s73, s16
	global_load_lds_dwordx4 v[166:167], off
	v_lshl_add_u64 v[166:167], s[68:69], 0, v[132:133]
	s_mov_b32 m0, s67
	s_nop 0
	global_load_lds_dwordx4 v[166:167], off
	v_lshl_add_u64 v[166:167], s[68:69], 0, v[128:129]
	s_add_i32 m0, s67, 0x2000
	s_nop 0
	global_load_lds_dwordx4 v[166:167], off
	v_lshl_add_u64 v[166:167], v[224:225], 0, s[10:11]
	s_mov_b32 m0, s23
	s_nop 0
	global_load_lds_dwordx4 v[166:167], off
	v_lshl_add_u64 v[166:167], v[226:227], 0, s[10:11]
	s_mov_b32 m0, s24
	s_nop 0
	global_load_lds_dwordx4 v[166:167], off
	s_waitcnt vmcnt(8)
	s_waitcnt lgkmcnt(0)
	s_barrier
	s_setprio 1
	v_mfma_f32_16x16x32_bf16 v[60:63], v[146:149], v[190:193], v[60:63]
	v_mfma_f32_16x16x32_bf16 v[60:63], v[150:153], v[194:197], v[60:63]
	v_mfma_f32_16x16x32_bf16 v[52:55], v[154:157], v[190:193], v[52:55]
	v_mfma_f32_16x16x32_bf16 v[52:55], v[158:161], v[194:197], v[52:55]
	v_mfma_f32_16x16x32_bf16 v[44:47], v[146:149], v[198:201], v[44:47]
	v_mfma_f32_16x16x32_bf16 v[44:47], v[150:153], v[202:205], v[44:47]
	v_mfma_f32_16x16x32_bf16 v[36:39], v[154:157], v[198:201], v[36:39]
	v_mfma_f32_16x16x32_bf16 v[36:39], v[158:161], v[202:205], v[36:39]
	v_mfma_f32_16x16x32_bf16 v[28:31], v[146:149], v[206:209], v[28:31]
	v_mfma_f32_16x16x32_bf16 v[28:31], v[150:153], v[210:213], v[28:31]
	v_mfma_f32_16x16x32_bf16 v[20:23], v[154:157], v[206:209], v[20:23]
	v_mfma_f32_16x16x32_bf16 v[20:23], v[158:161], v[210:213], v[20:23]
	v_mfma_f32_16x16x32_bf16 v[12:15], v[146:149], v[214:217], v[12:15]
	v_mfma_f32_16x16x32_bf16 v[12:15], v[150:153], v[218:221], v[12:15]
	v_mfma_f32_16x16x32_bf16 v[4:7], v[154:157], v[214:217], v[4:7]
	v_mfma_f32_16x16x32_bf16 v[4:7], v[158:161], v[218:221], v[4:7]
	v_mfma_f32_16x16x32_bf16 v[56:59], v[162:165], v[190:193], v[56:59]
	v_mfma_f32_16x16x32_bf16 v[56:59], v[178:181], v[194:197], v[56:59]
	v_mfma_f32_16x16x32_bf16 v[48:51], v[182:185], v[190:193], v[48:51]
	v_mfma_f32_16x16x32_bf16 v[48:51], v[186:189], v[194:197], v[48:51]
	v_mfma_f32_16x16x32_bf16 v[40:43], v[162:165], v[198:201], v[40:43]
	v_mfma_f32_16x16x32_bf16 v[40:43], v[178:181], v[202:205], v[40:43]
	v_mfma_f32_16x16x32_bf16 v[32:35], v[182:185], v[198:201], v[32:35]
	v_mfma_f32_16x16x32_bf16 v[32:35], v[186:189], v[202:205], v[32:35]
	v_mfma_f32_16x16x32_bf16 v[24:27], v[162:165], v[206:209], v[24:27]
	v_mfma_f32_16x16x32_bf16 v[24:27], v[178:181], v[210:213], v[24:27]
	v_mfma_f32_16x16x32_bf16 v[16:19], v[182:185], v[206:209], v[16:19]
	v_mfma_f32_16x16x32_bf16 v[16:19], v[186:189], v[210:213], v[16:19]
	s_setprio 3
	s_barrier
	v_mfma_f32_16x16x32_bf16 v[8:11], v[162:165], v[214:217], v[8:11]
	v_mfma_f32_16x16x32_bf16 v[8:11], v[178:181], v[218:221], v[8:11]
	v_mfma_f32_16x16x32_bf16 v[0:3], v[182:185], v[214:217], v[0:3]
	v_mfma_f32_16x16x32_bf16 v[0:3], v[186:189], v[218:221], v[0:3]
	s_setprio 0
	s_add_i32 s66, s66, 2
	s_add_u32 s78, s78, 0x100
	s_addc_u32 s79, s79, 0
	s_add_u32 s58, s58, 0x100
	s_addc_u32 s59, s59, 0
	s_cmp_gt_u32 s66, 13
	s_cbranch_scc0 .LBB0_1148
	s_and_b64 vcc, exec, s[44:45]
	s_cbranch_vccz .LBB0_1151
	s_barrier

.LBB0_1299:
	ds_read_b128 v[120:123], v245
	ds_read_b128 v[124:127], v245 offset:1024
	ds_read_b128 v[128:131], v245 offset:2048
	ds_read_b128 v[132:135], v245 offset:3072
	ds_read_b128 v[144:147], v246
	ds_read_b128 v[148:151], v246 offset:1024
	ds_read_b128 v[152:155], v246 offset:2048
	ds_read_b128 v[156:159], v246 offset:3072
	s_add_u32 s66, s76, 0xfff50080
	s_addc_u32 s67, s77, -1
	s_cmp_eq_u32 s59, 40
	s_cselect_b32 s81, s9, s67
	s_cselect_b32 s80, s8, s66
	s_cselect_b32 s79, s53, s58
	s_cselect_b32 s78, s52, s55
	v_lshl_add_u64 v[204:205], s[76:77], 0, v[200:201]
	s_add_i32 m0, s16, 0xc000
	ds_read_b128 v[160:163], v247
	ds_read_b128 v[164:167], v247 offset:1024
	ds_read_b128 v[168:171], v247 offset:2048
	ds_read_b128 v[172:175], v247 offset:3072
	ds_read_b128 v[176:179], v247 offset:4096
	ds_read_b128 v[180:183], v247 offset:5120
	ds_read_b128 v[184:187], v247 offset:6144
	ds_read_b128 v[188:191], v247 offset:7168
	global_load_lds_dwordx4 v[204:205], off
	v_lshl_add_u64 v[204:205], s[76:77], 0, v[202:203]
	s_add_i32 m0, s16, 0xe000
	s_nop 0
	global_load_lds_dwordx4 v[204:205], off
	s_waitcnt vmcnt(8)
	s_waitcnt lgkmcnt(0)
	s_barrier
	s_setprio 1
	v_mfma_f32_16x16x32_bf16 v[140:143], v[120:123], v[160:163], v[140:143]
	v_mfma_f32_16x16x32_bf16 v[140:143], v[124:127], v[164:167], v[140:143]
	v_mfma_f32_16x16x32_bf16 v[136:139], v[128:131], v[160:163], v[136:139]
	v_mfma_f32_16x16x32_bf16 v[136:139], v[132:135], v[164:167], v[136:139]
	v_mfma_f32_16x16x32_bf16 v[108:111], v[120:123], v[168:171], v[108:111]
	v_mfma_f32_16x16x32_bf16 v[108:111], v[124:127], v[172:175], v[108:111]
	v_mfma_f32_16x16x32_bf16 v[104:107], v[128:131], v[168:171], v[104:107]
	v_mfma_f32_16x16x32_bf16 v[104:107], v[132:135], v[172:175], v[104:107]
	v_mfma_f32_16x16x32_bf16 v[92:95], v[120:123], v[176:179], v[92:95]
	v_mfma_f32_16x16x32_bf16 v[92:95], v[124:127], v[180:183], v[92:95]
	v_mfma_f32_16x16x32_bf16 v[88:91], v[128:131], v[176:179], v[88:91]
	v_mfma_f32_16x16x32_bf16 v[88:91], v[132:135], v[180:183], v[88:91]
	v_mfma_f32_16x16x32_bf16 v[76:79], v[120:123], v[184:187], v[76:79]
	v_mfma_f32_16x16x32_bf16 v[76:79], v[124:127], v[188:191], v[76:79]
	v_mfma_f32_16x16x32_bf16 v[72:75], v[128:131], v[184:187], v[72:75]
	v_mfma_f32_16x16x32_bf16 v[72:75], v[132:135], v[188:191], v[72:75]
	v_mfma_f32_16x16x32_bf16 v[116:119], v[144:147], v[160:163], v[116:119]
	v_mfma_f32_16x16x32_bf16 v[116:119], v[148:151], v[164:167], v[116:119]
	v_mfma_f32_16x16x32_bf16 v[112:115], v[152:155], v[160:163], v[112:115]
	v_mfma_f32_16x16x32_bf16 v[112:115], v[156:159], v[164:167], v[112:115]
	v_mfma_f32_16x16x32_bf16 v[100:103], v[144:147], v[168:171], v[100:103]
	v_mfma_f32_16x16x32_bf16 v[100:103], v[148:151], v[172:175], v[100:103]
	v_mfma_f32_16x16x32_bf16 v[96:99], v[152:155], v[168:171], v[96:99]
	v_mfma_f32_16x16x32_bf16 v[96:99], v[156:159], v[172:175], v[96:99]
	v_mfma_f32_16x16x32_bf16 v[84:87], v[144:147], v[176:179], v[84:87]
	v_mfma_f32_16x16x32_bf16 v[84:87], v[148:151], v[180:183], v[84:87]
	v_mfma_f32_16x16x32_bf16 v[80:83], v[152:155], v[176:179], v[80:83]
	v_mfma_f32_16x16x32_bf16 v[80:83], v[156:159], v[180:183], v[80:83]
	s_setprio 3
	s_barrier
	v_mfma_f32_16x16x32_bf16 v[68:71], v[144:147], v[184:187], v[68:71]
	v_mfma_f32_16x16x32_bf16 v[68:71], v[148:151], v[188:191], v[68:71]
	v_mfma_f32_16x16x32_bf16 v[64:67], v[152:155], v[184:187], v[64:67]
	v_mfma_f32_16x16x32_bf16 v[64:67], v[156:159], v[188:191], v[64:67]
	s_setprio 0
	s_add_i32 s66, s26, s15
	v_lshl_add_u64 v[204:205], s[78:79], 0, v[194:195]
	s_mov_b32 m0, s66
	ds_read_b128 v[160:163], v247 offset:16384
	ds_read_b128 v[164:167], v247 offset:17408
	ds_read_b128 v[168:171], v247 offset:18432
	ds_read_b128 v[172:175], v247 offset:19456
	ds_read_b128 v[176:179], v247 offset:20480
	ds_read_b128 v[180:183], v247 offset:21504
	ds_read_b128 v[184:187], v247 offset:22528
	ds_read_b128 v[188:191], v247 offset:23552
	global_load_lds_dwordx4 v[204:205], off
	s_add_i32 m0, s66, 0x2000
	s_add_u32 s66, s78, 0xb0000
	v_lshl_add_u64 v[206:207], s[78:79], 0, v[198:199]
	s_addc_u32 s67, s79, 0
	s_add_i32 s68, s27, s15
	global_load_lds_dwordx4 v[206:207], off
	v_lshl_add_u64 v[208:209], s[66:67], 0, v[194:195]
	s_mov_b32 m0, s68
	v_lshl_add_u64 v[210:211], s[80:81], 0, v[196:197]
	global_load_lds_dwordx4 v[208:209], off
	v_lshl_add_u64 v[208:209], s[66:67], 0, v[198:199]
	s_add_i32 m0, s68, 0x2000
	s_nop 0
	global_load_lds_dwordx4 v[208:209], off
	v_lshl_add_u64 v[208:209], s[80:81], 0, v[192:193]
	s_mov_b32 m0, s16
	s_nop 0
	global_load_lds_dwordx4 v[208:209], off
	s_mov_b32 m0, s17
	s_nop 0
	global_load_lds_dwordx4 v[210:211], off
	s_waitcnt vmcnt(8)
	s_waitcnt lgkmcnt(0)
	s_barrier
	s_setprio 1
	v_mfma_f32_16x16x32_bf16 v[60:63], v[120:123], v[160:163], v[60:63]
	v_mfma_f32_16x16x32_bf16 v[60:63], v[124:127], v[164:167], v[60:63]
	v_mfma_f32_16x16x32_bf16 v[56:59], v[128:131], v[160:163], v[56:59]
	v_mfma_f32_16x16x32_bf16 v[56:59], v[132:135], v[164:167], v[56:59]
	v_mfma_f32_16x16x32_bf16 v[44:47], v[120:123], v[168:171], v[44:47]
	v_mfma_f32_16x16x32_bf16 v[44:47], v[124:127], v[172:175], v[44:47]
	v_mfma_f32_16x16x32_bf16 v[40:43], v[128:131], v[168:171], v[40:43]
	v_mfma_f32_16x16x32_bf16 v[40:43], v[132:135], v[172:175], v[40:43]
	v_mfma_f32_16x16x32_bf16 v[28:31], v[120:123], v[176:179], v[28:31]
	v_mfma_f32_16x16x32_bf16 v[28:31], v[124:127], v[180:183], v[28:31]
	v_mfma_f32_16x16x32_bf16 v[24:27], v[128:131], v[176:179], v[24:27]
	v_mfma_f32_16x16x32_bf16 v[24:27], v[132:135], v[180:183], v[24:27]
	v_mfma_f32_16x16x32_bf16 v[12:15], v[120:123], v[184:187], v[12:15]
	v_mfma_f32_16x16x32_bf16 v[12:15], v[124:127], v[188:191], v[12:15]
	v_mfma_f32_16x16x32_bf16 v[8:11], v[128:131], v[184:187], v[8:11]
	v_mfma_f32_16x16x32_bf16 v[8:11], v[132:135], v[188:191], v[8:11]
	v_mfma_f32_16x16x32_bf16 v[52:55], v[144:147], v[160:163], v[52:55]
	v_mfma_f32_16x16x32_bf16 v[52:55], v[148:151], v[164:167], v[52:55]
	v_mfma_f32_16x16x32_bf16 v[48:51], v[152:155], v[160:163], v[48:51]
	v_mfma_f32_16x16x32_bf16 v[48:51], v[156:159], v[164:167], v[48:51]
	v_mfma_f32_16x16x32_bf16 v[36:39], v[144:147], v[168:171], v[36:39]
	v_mfma_f32_16x16x32_bf16 v[36:39], v[148:151], v[172:175], v[36:39]
	v_mfma_f32_16x16x32_bf16 v[32:35], v[152:155], v[168:171], v[32:35]
	v_mfma_f32_16x16x32_bf16 v[32:35], v[156:159], v[172:175], v[32:35]
	v_mfma_f32_16x16x32_bf16 v[20:23], v[144:147], v[176:179], v[20:23]
	v_mfma_f32_16x16x32_bf16 v[20:23], v[148:151], v[180:183], v[20:23]
	v_mfma_f32_16x16x32_bf16 v[16:19], v[152:155], v[176:179], v[16:19]
	v_mfma_f32_16x16x32_bf16 v[16:19], v[156:159], v[180:183], v[16:19]
	s_setprio 3
	s_barrier
	v_mfma_f32_16x16x32_bf16 v[4:7], v[144:147], v[184:187], v[4:7]
	v_mfma_f32_16x16x32_bf16 v[4:7], v[148:151], v[188:191], v[4:7]
	v_mfma_f32_16x16x32_bf16 v[0:3], v[152:155], v[184:187], v[0:3]
	v_mfma_f32_16x16x32_bf16 v[0:3], v[156:159], v[188:191], v[0:3]
	s_setprio 0
	s_add_i32 s68, 0, 0x18000
	s_add_i32 s69, 0, 0x1c000
	v_add_u32_e32 v132, s68, v243
	v_add_u32_e32 v156, s69, v243
	ds_read_b128 v[120:123], v132
	ds_read_b128 v[124:127], v132 offset:1024
	ds_read_b128 v[128:131], v132 offset:2048
	ds_read_b128 v[132:135], v132 offset:3072
	ds_read_b128 v[144:147], v156
	ds_read_b128 v[148:151], v156 offset:1024
	ds_read_b128 v[152:155], v156 offset:2048
	ds_read_b128 v[156:159], v156 offset:3072
	s_add_u32 s66, s80, 0xb0000
	s_addc_u32 s67, s81, 0
	s_mov_b32 m0, s18
	v_lshl_add_u64 v[212:213], s[66:67], 0, v[192:193]
	ds_read_b128 v[160:163], v247 offset:32768
	ds_read_b128 v[164:167], v247 offset:33792
	ds_read_b128 v[168:171], v247 offset:34816
	ds_read_b128 v[172:175], v247 offset:35840
	ds_read_b128 v[176:179], v247 offset:36864
	ds_read_b128 v[180:183], v247 offset:37888
	ds_read_b128 v[184:187], v247 offset:38912
	ds_read_b128 v[188:191], v247 offset:39936
	global_load_lds_dwordx4 v[212:213], off
	v_lshl_add_u64 v[212:213], s[66:67], 0, v[196:197]
	s_mov_b32 m0, s19
	s_nop 0
	global_load_lds_dwordx4 v[212:213], off
	s_waitcnt vmcnt(8)
	s_waitcnt lgkmcnt(0)
	s_barrier
	s_setprio 1
	v_mfma_f32_16x16x32_bf16 v[140:143], v[120:123], v[160:163], v[140:143]
	v_mfma_f32_16x16x32_bf16 v[140:143], v[124:127], v[164:167], v[140:143]
	v_mfma_f32_16x16x32_bf16 v[136:139], v[128:131], v[160:163], v[136:139]
	v_mfma_f32_16x16x32_bf16 v[136:139], v[132:135], v[164:167], v[136:139]
	v_mfma_f32_16x16x32_bf16 v[108:111], v[120:123], v[168:171], v[108:111]
	v_mfma_f32_16x16x32_bf16 v[108:111], v[124:127], v[172:175], v[108:111]
	v_mfma_f32_16x16x32_bf16 v[104:107], v[128:131], v[168:171], v[104:107]
	v_mfma_f32_16x16x32_bf16 v[104:107], v[132:135], v[172:175], v[104:107]
	v_mfma_f32_16x16x32_bf16 v[92:95], v[120:123], v[176:179], v[92:95]
	v_mfma_f32_16x16x32_bf16 v[92:95], v[124:127], v[180:183], v[92:95]
	v_mfma_f32_16x16x32_bf16 v[88:91], v[128:131], v[176:179], v[88:91]
	v_mfma_f32_16x16x32_bf16 v[88:91], v[132:135], v[180:183], v[88:91]
	v_mfma_f32_16x16x32_bf16 v[76:79], v[120:123], v[184:187], v[76:79]
	v_mfma_f32_16x16x32_bf16 v[76:79], v[124:127], v[188:191], v[76:79]
	v_mfma_f32_16x16x32_bf16 v[72:75], v[128:131], v[184:187], v[72:75]
	v_mfma_f32_16x16x32_bf16 v[72:75], v[132:135], v[188:191], v[72:75]
	v_mfma_f32_16x16x32_bf16 v[116:119], v[144:147], v[160:163], v[116:119]
	v_mfma_f32_16x16x32_bf16 v[116:119], v[148:151], v[164:167], v[116:119]
	v_mfma_f32_16x16x32_bf16 v[112:115], v[152:155], v[160:163], v[112:115]
	v_mfma_f32_16x16x32_bf16 v[112:115], v[156:159], v[164:167], v[112:115]
	v_mfma_f32_16x16x32_bf16 v[100:103], v[144:147], v[168:171], v[100:103]
	v_mfma_f32_16x16x32_bf16 v[100:103], v[148:151], v[172:175], v[100:103]
	v_mfma_f32_16x16x32_bf16 v[96:99], v[152:155], v[168:171], v[96:99]
	v_mfma_f32_16x16x32_bf16 v[96:99], v[156:159], v[172:175], v[96:99]
	v_mfma_f32_16x16x32_bf16 v[84:87], v[144:147], v[176:179], v[84:87]
	v_mfma_f32_16x16x32_bf16 v[84:87], v[148:151], v[180:183], v[84:87]
	v_mfma_f32_16x16x32_bf16 v[80:83], v[152:155], v[176:179], v[80:83]
	v_mfma_f32_16x16x32_bf16 v[80:83], v[156:159], v[180:183], v[80:83]
	s_setprio 3
	s_barrier
	v_mfma_f32_16x16x32_bf16 v[68:71], v[144:147], v[184:187], v[68:71]
	v_mfma_f32_16x16x32_bf16 v[68:71], v[148:151], v[188:191], v[68:71]
	v_mfma_f32_16x16x32_bf16 v[64:67], v[152:155], v[184:187], v[64:67]
	v_mfma_f32_16x16x32_bf16 v[64:67], v[156:159], v[188:191], v[64:67]
	s_setprio 0
	s_add_i32 s66, s68, s15
	v_lshl_add_u64 v[204:205], v[204:205], 0, s[48:49]
	s_mov_b32 m0, s66
	ds_read_b128 v[160:163], v247 offset:49152
	ds_read_b128 v[164:167], v247 offset:50176
	ds_read_b128 v[168:171], v247 offset:51200
	ds_read_b128 v[172:175], v247 offset:52224
	ds_read_b128 v[176:179], v247 offset:53248
	ds_read_b128 v[180:183], v247 offset:54272
	ds_read_b128 v[184:187], v247 offset:55296
	ds_read_b128 v[188:191], v247 offset:56320
	global_load_lds_dwordx4 v[204:205], off
	s_add_i32 m0, s66, 0x2000
	s_add_u32 s66, s78, 0xb0080
	v_lshl_add_u64 v[204:205], v[206:207], 0, s[48:49]
	s_addc_u32 s67, s79, 0
	s_add_i32 s68, s69, s15
	global_load_lds_dwordx4 v[204:205], off
	v_lshl_add_u64 v[204:205], s[66:67], 0, v[194:195]
	s_mov_b32 m0, s68
	s_nop 0
	global_load_lds_dwordx4 v[204:205], off
	v_lshl_add_u64 v[204:205], s[66:67], 0, v[198:199]
	s_add_i32 m0, s68, 0x2000
	s_nop 0
	global_load_lds_dwordx4 v[204:205], off
	v_lshl_add_u64 v[204:205], v[208:209], 0, s[48:49]
	s_mov_b32 m0, s21
	s_nop 0
	global_load_lds_dwordx4 v[204:205], off
	v_lshl_add_u64 v[204:205], v[210:211], 0, s[48:49]
	s_mov_b32 m0, s22
	s_nop 0
	global_load_lds_dwordx4 v[204:205], off
	s_waitcnt vmcnt(8)
	s_waitcnt lgkmcnt(0)
	s_barrier
	s_setprio 1
	v_mfma_f32_16x16x32_bf16 v[60:63], v[120:123], v[160:163], v[60:63]
	v_mfma_f32_16x16x32_bf16 v[60:63], v[124:127], v[164:167], v[60:63]
	v_mfma_f32_16x16x32_bf16 v[56:59], v[128:131], v[160:163], v[56:59]
	v_mfma_f32_16x16x32_bf16 v[56:59], v[132:135], v[164:167], v[56:59]
	v_mfma_f32_16x16x32_bf16 v[44:47], v[120:123], v[168:171], v[44:47]
	v_mfma_f32_16x16x32_bf16 v[44:47], v[124:127], v[172:175], v[44:47]
	v_mfma_f32_16x16x32_bf16 v[40:43], v[128:131], v[168:171], v[40:43]
	v_mfma_f32_16x16x32_bf16 v[40:43], v[132:135], v[172:175], v[40:43]
	v_mfma_f32_16x16x32_bf16 v[28:31], v[120:123], v[176:179], v[28:31]
	v_mfma_f32_16x16x32_bf16 v[28:31], v[124:127], v[180:183], v[28:31]
	v_mfma_f32_16x16x32_bf16 v[24:27], v[128:131], v[176:179], v[24:27]
	v_mfma_f32_16x16x32_bf16 v[24:27], v[132:135], v[180:183], v[24:27]
	v_mfma_f32_16x16x32_bf16 v[12:15], v[120:123], v[184:187], v[12:15]
	v_mfma_f32_16x16x32_bf16 v[12:15], v[124:127], v[188:191], v[12:15]
	v_mfma_f32_16x16x32_bf16 v[8:11], v[128:131], v[184:187], v[8:11]
	v_mfma_f32_16x16x32_bf16 v[8:11], v[132:135], v[188:191], v[8:11]
	v_mfma_f32_16x16x32_bf16 v[52:55], v[144:147], v[160:163], v[52:55]
	v_mfma_f32_16x16x32_bf16 v[52:55], v[148:151], v[164:167], v[52:55]
	v_mfma_f32_16x16x32_bf16 v[48:51], v[152:155], v[160:163], v[48:51]
	v_mfma_f32_16x16x32_bf16 v[48:51], v[156:159], v[164:167], v[48:51]
	v_mfma_f32_16x16x32_bf16 v[36:39], v[144:147], v[168:171], v[36:39]
	v_mfma_f32_16x16x32_bf16 v[36:39], v[148:151], v[172:175], v[36:39]
	v_mfma_f32_16x16x32_bf16 v[32:35], v[152:155], v[168:171], v[32:35]
	v_mfma_f32_16x16x32_bf16 v[32:35], v[156:159], v[172:175], v[32:35]
	v_mfma_f32_16x16x32_bf16 v[20:23], v[144:147], v[176:179], v[20:23]
	v_mfma_f32_16x16x32_bf16 v[20:23], v[148:151], v[180:183], v[20:23]
	v_mfma_f32_16x16x32_bf16 v[16:19], v[152:155], v[176:179], v[16:19]
	v_mfma_f32_16x16x32_bf16 v[16:19], v[156:159], v[180:183], v[16:19]
	s_setprio 3
	s_barrier
	v_mfma_f32_16x16x32_bf16 v[4:7], v[144:147], v[184:187], v[4:7]
	v_mfma_f32_16x16x32_bf16 v[4:7], v[148:151], v[188:191], v[4:7]
	v_mfma_f32_16x16x32_bf16 v[0:3], v[152:155], v[184:187], v[0:3]
	v_mfma_f32_16x16x32_bf16 v[0:3], v[156:159], v[188:191], v[0:3]
	s_setprio 0
	s_add_i32 s59, s59, 2
	s_add_u32 s76, s76, 0x100
	s_addc_u32 s77, s77, 0
	s_add_u32 s55, s55, 0x100
	s_addc_u32 s58, s58, 0
	s_cmp_gt_u32 s59, 41
	s_cbranch_scc0 .LBB0_1299
	s_and_b64 vcc, exec, s[50:51]
	s_cbranch_vccz .LBB0_1302
	s_barrier

.LBB0_1760:
	ds_read_b128 v[128:131], v181
	ds_read_b128 v[132:135], v181 offset:1024
	ds_read_b128 v[136:139], v181 offset:2048
	ds_read_b128 v[160:163], v181 offset:3072
	ds_read_b128 v[164:167], v182
	ds_read_b128 v[168:171], v182 offset:1024
	ds_read_b128 v[186:189], v182 offset:2048
	ds_read_b128 v[190:193], v182 offset:3072
	s_add_u32 s69, s78, 0xfffc0080
	s_addc_u32 s73, s79, -1
	s_cmp_eq_u32 s68, 12
	s_cselect_b32 s83, s49, s73
	s_cselect_b32 s82, s54, s69
	s_cselect_b32 s81, s47, s67
	s_cselect_b32 s80, s55, s66
	v_lshl_add_u64 v[172:173], s[78:79], 0, v[152:153]
	s_add_i32 m0, s18, 0xc000
	ds_read_b128 v[194:197], v183
	ds_read_b128 v[198:201], v183 offset:1024
	ds_read_b128 v[202:205], v183 offset:2048
	ds_read_b128 v[206:209], v183 offset:3072
	ds_read_b128 v[210:213], v183 offset:4096
	ds_read_b128 v[214:217], v183 offset:5120
	ds_read_b128 v[218:221], v183 offset:6144
	ds_read_b128 v[222:225], v183 offset:7168
	global_load_lds_dwordx4 v[172:173], off
	v_lshl_add_u64 v[172:173], s[78:79], 0, v[154:155]
	s_add_i32 m0, s18, 0xe000
	s_nop 0
	global_load_lds_dwordx4 v[172:173], off
	s_waitcnt vmcnt(8)
	s_waitcnt lgkmcnt(0)
	s_barrier
	s_setprio 1
	v_mfma_f32_16x16x32_bf16 v[124:127], v[128:131], v[194:197], v[124:127]
	v_mfma_f32_16x16x32_bf16 v[124:127], v[132:135], v[198:201], v[124:127]
	v_mfma_f32_16x16x32_bf16 v[120:123], v[136:139], v[194:197], v[120:123]
	v_mfma_f32_16x16x32_bf16 v[120:123], v[160:163], v[198:201], v[120:123]
	v_mfma_f32_16x16x32_bf16 v[108:111], v[128:131], v[202:205], v[108:111]
	v_mfma_f32_16x16x32_bf16 v[108:111], v[132:135], v[206:209], v[108:111]
	v_mfma_f32_16x16x32_bf16 v[104:107], v[136:139], v[202:205], v[104:107]
	v_mfma_f32_16x16x32_bf16 v[104:107], v[160:163], v[206:209], v[104:107]
	v_mfma_f32_16x16x32_bf16 v[92:95], v[128:131], v[210:213], v[92:95]
	v_mfma_f32_16x16x32_bf16 v[92:95], v[132:135], v[214:217], v[92:95]
	v_mfma_f32_16x16x32_bf16 v[88:91], v[136:139], v[210:213], v[88:91]
	v_mfma_f32_16x16x32_bf16 v[88:91], v[160:163], v[214:217], v[88:91]
	v_mfma_f32_16x16x32_bf16 v[76:79], v[128:131], v[218:221], v[76:79]
	v_mfma_f32_16x16x32_bf16 v[76:79], v[132:135], v[222:225], v[76:79]
	v_mfma_f32_16x16x32_bf16 v[72:75], v[136:139], v[218:221], v[72:75]
	v_mfma_f32_16x16x32_bf16 v[72:75], v[160:163], v[222:225], v[72:75]
	v_mfma_f32_16x16x32_bf16 v[116:119], v[164:167], v[194:197], v[116:119]
	v_mfma_f32_16x16x32_bf16 v[116:119], v[168:171], v[198:201], v[116:119]
	v_mfma_f32_16x16x32_bf16 v[112:115], v[186:189], v[194:197], v[112:115]
	v_mfma_f32_16x16x32_bf16 v[112:115], v[190:193], v[198:201], v[112:115]
	v_mfma_f32_16x16x32_bf16 v[100:103], v[164:167], v[202:205], v[100:103]
	v_mfma_f32_16x16x32_bf16 v[100:103], v[168:171], v[206:209], v[100:103]
	v_mfma_f32_16x16x32_bf16 v[96:99], v[186:189], v[202:205], v[96:99]
	v_mfma_f32_16x16x32_bf16 v[96:99], v[190:193], v[206:209], v[96:99]
	v_mfma_f32_16x16x32_bf16 v[84:87], v[164:167], v[210:213], v[84:87]
	v_mfma_f32_16x16x32_bf16 v[84:87], v[168:171], v[214:217], v[84:87]
	v_mfma_f32_16x16x32_bf16 v[80:83], v[186:189], v[210:213], v[80:83]
	v_mfma_f32_16x16x32_bf16 v[80:83], v[190:193], v[214:217], v[80:83]
	s_setprio 3
	s_barrier
	v_mfma_f32_16x16x32_bf16 v[68:71], v[164:167], v[218:221], v[68:71]
	v_mfma_f32_16x16x32_bf16 v[68:71], v[168:171], v[222:225], v[68:71]
	v_mfma_f32_16x16x32_bf16 v[64:67], v[186:189], v[218:221], v[64:67]
	v_mfma_f32_16x16x32_bf16 v[64:67], v[190:193], v[222:225], v[64:67]
	s_setprio 0
	s_add_i32 s69, s25, s17
	v_lshl_add_u64 v[172:173], s[80:81], 0, v[142:143]
	s_mov_b32 m0, s69
	ds_read_b128 v[194:197], v183 offset:16384
	ds_read_b128 v[198:201], v183 offset:17408
	ds_read_b128 v[202:205], v183 offset:18432
	ds_read_b128 v[206:209], v183 offset:19456
	ds_read_b128 v[210:213], v183 offset:20480
	ds_read_b128 v[214:217], v183 offset:21504
	ds_read_b128 v[218:221], v183 offset:22528
	ds_read_b128 v[222:225], v183 offset:23552
	global_load_lds_dwordx4 v[172:173], off
	s_add_i32 m0, s69, 0x2000
	s_add_u32 s84, s80, 0x40000
	v_lshl_add_u64 v[226:227], s[80:81], 0, v[146:147]
	s_addc_u32 s85, s81, 0
	s_add_i32 s69, s26, s17
	global_load_lds_dwordx4 v[226:227], off
	v_lshl_add_u64 v[228:229], s[84:85], 0, v[142:143]
	s_mov_b32 m0, s69
	v_lshl_add_u64 v[230:231], s[82:83], 0, v[144:145]
	global_load_lds_dwordx4 v[228:229], off
	v_lshl_add_u64 v[228:229], s[84:85], 0, v[146:147]
	s_add_i32 m0, s69, 0x2000
	s_nop 0
	global_load_lds_dwordx4 v[228:229], off
	v_lshl_add_u64 v[228:229], s[82:83], 0, v[140:141]
	s_mov_b32 m0, s18
	s_nop 0
	global_load_lds_dwordx4 v[228:229], off
	s_mov_b32 m0, s19
	s_nop 0
	global_load_lds_dwordx4 v[230:231], off
	s_waitcnt vmcnt(8)
	s_waitcnt lgkmcnt(0)
	s_barrier
	s_setprio 1
	v_mfma_f32_16x16x32_bf16 v[60:63], v[128:131], v[194:197], v[60:63]
	v_mfma_f32_16x16x32_bf16 v[60:63], v[132:135], v[198:201], v[60:63]
	v_mfma_f32_16x16x32_bf16 v[56:59], v[136:139], v[194:197], v[56:59]
	v_mfma_f32_16x16x32_bf16 v[56:59], v[160:163], v[198:201], v[56:59]
	v_mfma_f32_16x16x32_bf16 v[44:47], v[128:131], v[202:205], v[44:47]
	v_mfma_f32_16x16x32_bf16 v[44:47], v[132:135], v[206:209], v[44:47]
	v_mfma_f32_16x16x32_bf16 v[40:43], v[136:139], v[202:205], v[40:43]
	v_mfma_f32_16x16x32_bf16 v[40:43], v[160:163], v[206:209], v[40:43]
	v_mfma_f32_16x16x32_bf16 v[28:31], v[128:131], v[210:213], v[28:31]
	v_mfma_f32_16x16x32_bf16 v[28:31], v[132:135], v[214:217], v[28:31]
	v_mfma_f32_16x16x32_bf16 v[24:27], v[136:139], v[210:213], v[24:27]
	v_mfma_f32_16x16x32_bf16 v[24:27], v[160:163], v[214:217], v[24:27]
	v_mfma_f32_16x16x32_bf16 v[12:15], v[128:131], v[218:221], v[12:15]
	v_mfma_f32_16x16x32_bf16 v[12:15], v[132:135], v[222:225], v[12:15]
	v_mfma_f32_16x16x32_bf16 v[8:11], v[136:139], v[218:221], v[8:11]
	v_mfma_f32_16x16x32_bf16 v[8:11], v[160:163], v[222:225], v[8:11]
	v_mfma_f32_16x16x32_bf16 v[52:55], v[164:167], v[194:197], v[52:55]
	v_mfma_f32_16x16x32_bf16 v[52:55], v[168:171], v[198:201], v[52:55]
	v_mfma_f32_16x16x32_bf16 v[48:51], v[186:189], v[194:197], v[48:51]
	v_mfma_f32_16x16x32_bf16 v[48:51], v[190:193], v[198:201], v[48:51]
	v_mfma_f32_16x16x32_bf16 v[36:39], v[164:167], v[202:205], v[36:39]
	v_mfma_f32_16x16x32_bf16 v[36:39], v[168:171], v[206:209], v[36:39]
	v_mfma_f32_16x16x32_bf16 v[32:35], v[186:189], v[202:205], v[32:35]
	v_mfma_f32_16x16x32_bf16 v[32:35], v[190:193], v[206:209], v[32:35]
	v_mfma_f32_16x16x32_bf16 v[20:23], v[164:167], v[210:213], v[20:23]
	v_mfma_f32_16x16x32_bf16 v[20:23], v[168:171], v[214:217], v[20:23]
	v_mfma_f32_16x16x32_bf16 v[16:19], v[186:189], v[210:213], v[16:19]
	v_mfma_f32_16x16x32_bf16 v[16:19], v[190:193], v[214:217], v[16:19]
	s_setprio 3
	s_barrier
	v_mfma_f32_16x16x32_bf16 v[4:7], v[164:167], v[218:221], v[4:7]
	v_mfma_f32_16x16x32_bf16 v[4:7], v[168:171], v[222:225], v[4:7]
	v_mfma_f32_16x16x32_bf16 v[0:3], v[186:189], v[218:221], v[0:3]
	v_mfma_f32_16x16x32_bf16 v[0:3], v[190:193], v[222:225], v[0:3]
	s_setprio 0
	s_add_i32 s69, 0, 0x18000
	v_add_u32_e32 v148, s69, v177
	s_add_i32 s73, 0, 0x1c000
	ds_read_b128 v[128:131], v148
	ds_read_b128 v[132:135], v148 offset:1024
	ds_read_b128 v[136:139], v148 offset:2048
	ds_read_b128 v[160:163], v148 offset:3072
	v_add_u32_e32 v148, s73, v177
	ds_read_b128 v[164:167], v148
	ds_read_b128 v[168:171], v148 offset:1024
	ds_read_b128 v[186:189], v148 offset:2048
	ds_read_b128 v[190:193], v148 offset:3072
	s_add_u32 s82, s82, 0x40000
	s_addc_u32 s83, s83, 0
	s_mov_b32 m0, s20
	v_lshl_add_u64 v[232:233], s[82:83], 0, v[140:141]
	ds_read_b128 v[194:197], v183 offset:32768
	ds_read_b128 v[198:201], v183 offset:33792
	ds_read_b128 v[202:205], v183 offset:34816
	ds_read_b128 v[206:209], v183 offset:35840
	ds_read_b128 v[210:213], v183 offset:36864
	ds_read_b128 v[214:217], v183 offset:37888
	ds_read_b128 v[218:221], v183 offset:38912
	ds_read_b128 v[222:225], v183 offset:39936
	global_load_lds_dwordx4 v[232:233], off
	v_lshl_add_u64 v[232:233], s[82:83], 0, v[144:145]
	s_mov_b32 m0, s21
	s_nop 0
	global_load_lds_dwordx4 v[232:233], off
	s_waitcnt vmcnt(8)
	s_waitcnt lgkmcnt(0)
	s_barrier
	s_setprio 1
	v_mfma_f32_16x16x32_bf16 v[124:127], v[128:131], v[194:197], v[124:127]
	v_mfma_f32_16x16x32_bf16 v[124:127], v[132:135], v[198:201], v[124:127]
	v_mfma_f32_16x16x32_bf16 v[120:123], v[136:139], v[194:197], v[120:123]
	v_mfma_f32_16x16x32_bf16 v[120:123], v[160:163], v[198:201], v[120:123]
	v_mfma_f32_16x16x32_bf16 v[108:111], v[128:131], v[202:205], v[108:111]
	v_mfma_f32_16x16x32_bf16 v[108:111], v[132:135], v[206:209], v[108:111]
	v_mfma_f32_16x16x32_bf16 v[104:107], v[136:139], v[202:205], v[104:107]
	v_mfma_f32_16x16x32_bf16 v[104:107], v[160:163], v[206:209], v[104:107]
	v_mfma_f32_16x16x32_bf16 v[92:95], v[128:131], v[210:213], v[92:95]
	v_mfma_f32_16x16x32_bf16 v[92:95], v[132:135], v[214:217], v[92:95]
	v_mfma_f32_16x16x32_bf16 v[88:91], v[136:139], v[210:213], v[88:91]
	v_mfma_f32_16x16x32_bf16 v[88:91], v[160:163], v[214:217], v[88:91]
	v_mfma_f32_16x16x32_bf16 v[76:79], v[128:131], v[218:221], v[76:79]
	v_mfma_f32_16x16x32_bf16 v[76:79], v[132:135], v[222:225], v[76:79]
	v_mfma_f32_16x16x32_bf16 v[72:75], v[136:139], v[218:221], v[72:75]
	v_mfma_f32_16x16x32_bf16 v[72:75], v[160:163], v[222:225], v[72:75]
	v_mfma_f32_16x16x32_bf16 v[116:119], v[164:167], v[194:197], v[116:119]
	v_mfma_f32_16x16x32_bf16 v[116:119], v[168:171], v[198:201], v[116:119]
	v_mfma_f32_16x16x32_bf16 v[112:115], v[186:189], v[194:197], v[112:115]
	v_mfma_f32_16x16x32_bf16 v[112:115], v[190:193], v[198:201], v[112:115]
	v_mfma_f32_16x16x32_bf16 v[100:103], v[164:167], v[202:205], v[100:103]
	v_mfma_f32_16x16x32_bf16 v[100:103], v[168:171], v[206:209], v[100:103]
	v_mfma_f32_16x16x32_bf16 v[96:99], v[186:189], v[202:205], v[96:99]
	v_mfma_f32_16x16x32_bf16 v[96:99], v[190:193], v[206:209], v[96:99]
	v_mfma_f32_16x16x32_bf16 v[84:87], v[164:167], v[210:213], v[84:87]
	v_mfma_f32_16x16x32_bf16 v[84:87], v[168:171], v[214:217], v[84:87]
	v_mfma_f32_16x16x32_bf16 v[80:83], v[186:189], v[210:213], v[80:83]
	v_mfma_f32_16x16x32_bf16 v[80:83], v[190:193], v[214:217], v[80:83]
	s_setprio 3
	s_barrier
	v_mfma_f32_16x16x32_bf16 v[68:71], v[164:167], v[218:221], v[68:71]
	v_mfma_f32_16x16x32_bf16 v[68:71], v[168:171], v[222:225], v[68:71]
	v_mfma_f32_16x16x32_bf16 v[64:67], v[186:189], v[218:221], v[64:67]
	v_mfma_f32_16x16x32_bf16 v[64:67], v[190:193], v[222:225], v[64:67]
	s_setprio 0
	s_add_i32 s69, s69, s17
	v_lshl_add_u64 v[172:173], v[172:173], 0, s[10:11]
	s_mov_b32 m0, s69
	ds_read_b128 v[194:197], v183 offset:49152
	ds_read_b128 v[198:201], v183 offset:50176
	ds_read_b128 v[202:205], v183 offset:51200
	ds_read_b128 v[206:209], v183 offset:52224
	ds_read_b128 v[210:213], v183 offset:53248
	ds_read_b128 v[214:217], v183 offset:54272
	ds_read_b128 v[218:221], v183 offset:55296
	ds_read_b128 v[222:225], v183 offset:56320
	global_load_lds_dwordx4 v[172:173], off
	s_add_i32 m0, s69, 0x2000
	s_add_u32 s80, s80, 0x40080
	v_lshl_add_u64 v[172:173], v[226:227], 0, s[10:11]
	s_addc_u32 s81, s81, 0
	s_add_i32 s69, s73, s17
	global_load_lds_dwordx4 v[172:173], off
	v_lshl_add_u64 v[172:173], s[80:81], 0, v[142:143]
	s_mov_b32 m0, s69
	s_nop 0
	global_load_lds_dwordx4 v[172:173], off
	v_lshl_add_u64 v[172:173], s[80:81], 0, v[146:147]
	s_add_i32 m0, s69, 0x2000
	s_nop 0
	global_load_lds_dwordx4 v[172:173], off
	v_lshl_add_u64 v[172:173], v[228:229], 0, s[10:11]
	s_mov_b32 m0, s23
	s_nop 0
	global_load_lds_dwordx4 v[172:173], off
	v_lshl_add_u64 v[172:173], v[230:231], 0, s[10:11]
	s_mov_b32 m0, s24
	s_nop 0
	global_load_lds_dwordx4 v[172:173], off
	s_waitcnt vmcnt(8)
	s_waitcnt lgkmcnt(0)
	s_barrier
	s_setprio 1
	v_mfma_f32_16x16x32_bf16 v[60:63], v[128:131], v[194:197], v[60:63]
	v_mfma_f32_16x16x32_bf16 v[60:63], v[132:135], v[198:201], v[60:63]
	v_mfma_f32_16x16x32_bf16 v[56:59], v[136:139], v[194:197], v[56:59]
	v_mfma_f32_16x16x32_bf16 v[56:59], v[160:163], v[198:201], v[56:59]
	v_mfma_f32_16x16x32_bf16 v[44:47], v[128:131], v[202:205], v[44:47]
	v_mfma_f32_16x16x32_bf16 v[44:47], v[132:135], v[206:209], v[44:47]
	v_mfma_f32_16x16x32_bf16 v[40:43], v[136:139], v[202:205], v[40:43]
	v_mfma_f32_16x16x32_bf16 v[40:43], v[160:163], v[206:209], v[40:43]
	v_mfma_f32_16x16x32_bf16 v[28:31], v[128:131], v[210:213], v[28:31]
	v_mfma_f32_16x16x32_bf16 v[28:31], v[132:135], v[214:217], v[28:31]
	v_mfma_f32_16x16x32_bf16 v[24:27], v[136:139], v[210:213], v[24:27]
	v_mfma_f32_16x16x32_bf16 v[24:27], v[160:163], v[214:217], v[24:27]
	v_mfma_f32_16x16x32_bf16 v[12:15], v[128:131], v[218:221], v[12:15]
	v_mfma_f32_16x16x32_bf16 v[12:15], v[132:135], v[222:225], v[12:15]
	v_mfma_f32_16x16x32_bf16 v[8:11], v[136:139], v[218:221], v[8:11]
	v_mfma_f32_16x16x32_bf16 v[8:11], v[160:163], v[222:225], v[8:11]
	v_mfma_f32_16x16x32_bf16 v[52:55], v[164:167], v[194:197], v[52:55]
	v_mfma_f32_16x16x32_bf16 v[52:55], v[168:171], v[198:201], v[52:55]
	v_mfma_f32_16x16x32_bf16 v[48:51], v[186:189], v[194:197], v[48:51]
	v_mfma_f32_16x16x32_bf16 v[48:51], v[190:193], v[198:201], v[48:51]
	v_mfma_f32_16x16x32_bf16 v[36:39], v[164:167], v[202:205], v[36:39]
	v_mfma_f32_16x16x32_bf16 v[36:39], v[168:171], v[206:209], v[36:39]
	v_mfma_f32_16x16x32_bf16 v[32:35], v[186:189], v[202:205], v[32:35]
	v_mfma_f32_16x16x32_bf16 v[32:35], v[190:193], v[206:209], v[32:35]
	v_mfma_f32_16x16x32_bf16 v[20:23], v[164:167], v[210:213], v[20:23]
	v_mfma_f32_16x16x32_bf16 v[20:23], v[168:171], v[214:217], v[20:23]
	v_mfma_f32_16x16x32_bf16 v[16:19], v[186:189], v[210:213], v[16:19]
	v_mfma_f32_16x16x32_bf16 v[16:19], v[190:193], v[214:217], v[16:19]
	s_setprio 3
	s_barrier
	v_mfma_f32_16x16x32_bf16 v[4:7], v[164:167], v[218:221], v[4:7]
	v_mfma_f32_16x16x32_bf16 v[4:7], v[168:171], v[222:225], v[4:7]
	v_mfma_f32_16x16x32_bf16 v[0:3], v[186:189], v[218:221], v[0:3]
	v_mfma_f32_16x16x32_bf16 v[0:3], v[190:193], v[222:225], v[0:3]
	s_setprio 0
	s_add_i32 s68, s68, 2
	s_add_u32 s78, s78, 0x100
	s_addc_u32 s79, s79, 0
	s_add_u32 s66, s66, 0x100
	s_addc_u32 s67, s67, 0
	s_cmp_gt_u32 s68, 13
	s_cbranch_scc0 .LBB0_1760
	s_and_b64 vcc, exec, s[44:45]
	s_cbranch_vccz .LBB0_1763
	s_barrier

.LBB0_2037:
	ds_read_b128 v[120:123], v245
	ds_read_b128 v[124:127], v245 offset:1024
	ds_read_b128 v[128:131], v245 offset:2048
	ds_read_b128 v[132:135], v245 offset:3072
	ds_read_b128 v[144:147], v246
	ds_read_b128 v[148:151], v246 offset:1024
	ds_read_b128 v[152:155], v246 offset:2048
	ds_read_b128 v[156:159], v246 offset:3072
	s_add_u32 s67, s76, 0xfffc0080
	s_addc_u32 s68, s77, -1
	s_cmp_eq_u32 s66, 12
	s_cselect_b32 s81, s53, s68
	s_cselect_b32 s80, s54, s67
	s_cselect_b32 s79, s51, s57
	s_cselect_b32 s78, s55, s56
	v_lshl_add_u64 v[204:205], s[76:77], 0, v[200:201]
	s_add_i32 m0, s16, 0xc000
	ds_read_b128 v[160:163], v247
	ds_read_b128 v[164:167], v247 offset:1024
	ds_read_b128 v[168:171], v247 offset:2048
	ds_read_b128 v[172:175], v247 offset:3072
	ds_read_b128 v[176:179], v247 offset:4096
	ds_read_b128 v[180:183], v247 offset:5120
	ds_read_b128 v[184:187], v247 offset:6144
	ds_read_b128 v[188:191], v247 offset:7168
	global_load_lds_dwordx4 v[204:205], off
	v_lshl_add_u64 v[204:205], s[76:77], 0, v[202:203]
	s_add_i32 m0, s16, 0xe000
	s_nop 0
	global_load_lds_dwordx4 v[204:205], off
	s_waitcnt vmcnt(8)
	s_waitcnt lgkmcnt(0)
	s_barrier
	s_setprio 1
	v_mfma_f32_16x16x32_bf16 v[140:143], v[120:123], v[160:163], v[140:143]
	v_mfma_f32_16x16x32_bf16 v[140:143], v[124:127], v[164:167], v[140:143]
	v_mfma_f32_16x16x32_bf16 v[136:139], v[128:131], v[160:163], v[136:139]
	v_mfma_f32_16x16x32_bf16 v[136:139], v[132:135], v[164:167], v[136:139]
	v_mfma_f32_16x16x32_bf16 v[108:111], v[120:123], v[168:171], v[108:111]
	v_mfma_f32_16x16x32_bf16 v[108:111], v[124:127], v[172:175], v[108:111]
	v_mfma_f32_16x16x32_bf16 v[104:107], v[128:131], v[168:171], v[104:107]
	v_mfma_f32_16x16x32_bf16 v[104:107], v[132:135], v[172:175], v[104:107]
	v_mfma_f32_16x16x32_bf16 v[92:95], v[120:123], v[176:179], v[92:95]
	v_mfma_f32_16x16x32_bf16 v[92:95], v[124:127], v[180:183], v[92:95]
	v_mfma_f32_16x16x32_bf16 v[88:91], v[128:131], v[176:179], v[88:91]
	v_mfma_f32_16x16x32_bf16 v[88:91], v[132:135], v[180:183], v[88:91]
	v_mfma_f32_16x16x32_bf16 v[76:79], v[120:123], v[184:187], v[76:79]
	v_mfma_f32_16x16x32_bf16 v[76:79], v[124:127], v[188:191], v[76:79]
	v_mfma_f32_16x16x32_bf16 v[72:75], v[128:131], v[184:187], v[72:75]
	v_mfma_f32_16x16x32_bf16 v[72:75], v[132:135], v[188:191], v[72:75]
	v_mfma_f32_16x16x32_bf16 v[116:119], v[144:147], v[160:163], v[116:119]
	v_mfma_f32_16x16x32_bf16 v[116:119], v[148:151], v[164:167], v[116:119]
	v_mfma_f32_16x16x32_bf16 v[112:115], v[152:155], v[160:163], v[112:115]
	v_mfma_f32_16x16x32_bf16 v[112:115], v[156:159], v[164:167], v[112:115]
	v_mfma_f32_16x16x32_bf16 v[100:103], v[144:147], v[168:171], v[100:103]
	v_mfma_f32_16x16x32_bf16 v[100:103], v[148:151], v[172:175], v[100:103]
	v_mfma_f32_16x16x32_bf16 v[96:99], v[152:155], v[168:171], v[96:99]
	v_mfma_f32_16x16x32_bf16 v[96:99], v[156:159], v[172:175], v[96:99]
	v_mfma_f32_16x16x32_bf16 v[84:87], v[144:147], v[176:179], v[84:87]
	v_mfma_f32_16x16x32_bf16 v[84:87], v[148:151], v[180:183], v[84:87]
	v_mfma_f32_16x16x32_bf16 v[80:83], v[152:155], v[176:179], v[80:83]
	v_mfma_f32_16x16x32_bf16 v[80:83], v[156:159], v[180:183], v[80:83]
	s_setprio 3
	s_barrier
	v_mfma_f32_16x16x32_bf16 v[68:71], v[144:147], v[184:187], v[68:71]
	v_mfma_f32_16x16x32_bf16 v[68:71], v[148:151], v[188:191], v[68:71]
	v_mfma_f32_16x16x32_bf16 v[64:67], v[152:155], v[184:187], v[64:67]
	v_mfma_f32_16x16x32_bf16 v[64:67], v[156:159], v[188:191], v[64:67]
	s_setprio 0
	s_add_i32 s67, s26, s15
	v_lshl_add_u64 v[204:205], s[78:79], 0, v[194:195]
	s_mov_b32 m0, s67
	ds_read_b128 v[160:163], v247 offset:16384
	ds_read_b128 v[164:167], v247 offset:17408
	ds_read_b128 v[168:171], v247 offset:18432
	ds_read_b128 v[172:175], v247 offset:19456
	ds_read_b128 v[176:179], v247 offset:20480
	ds_read_b128 v[180:183], v247 offset:21504
	ds_read_b128 v[184:187], v247 offset:22528
	ds_read_b128 v[188:191], v247 offset:23552
	global_load_lds_dwordx4 v[204:205], off
	s_add_i32 m0, s67, 0x2000
	s_add_u32 s68, s78, 0x40000
	v_lshl_add_u64 v[206:207], s[78:79], 0, v[198:199]
	s_addc_u32 s69, s79, 0
	s_add_i32 s67, s27, s15
	global_load_lds_dwordx4 v[206:207], off
	v_lshl_add_u64 v[208:209], s[68:69], 0, v[194:195]
	s_mov_b32 m0, s67
	v_lshl_add_u64 v[210:211], s[80:81], 0, v[196:197]
	global_load_lds_dwordx4 v[208:209], off
	v_lshl_add_u64 v[208:209], s[68:69], 0, v[198:199]
	s_add_i32 m0, s67, 0x2000
	s_nop 0
	global_load_lds_dwordx4 v[208:209], off
	v_lshl_add_u64 v[208:209], s[80:81], 0, v[192:193]
	s_mov_b32 m0, s16
	s_nop 0
	global_load_lds_dwordx4 v[208:209], off
	s_mov_b32 m0, s17
	s_nop 0
	global_load_lds_dwordx4 v[210:211], off
	s_waitcnt vmcnt(8)
	s_waitcnt lgkmcnt(0)
	s_barrier
	s_setprio 1
	v_mfma_f32_16x16x32_bf16 v[60:63], v[120:123], v[160:163], v[60:63]
	v_mfma_f32_16x16x32_bf16 v[60:63], v[124:127], v[164:167], v[60:63]
	v_mfma_f32_16x16x32_bf16 v[56:59], v[128:131], v[160:163], v[56:59]
	v_mfma_f32_16x16x32_bf16 v[56:59], v[132:135], v[164:167], v[56:59]
	v_mfma_f32_16x16x32_bf16 v[44:47], v[120:123], v[168:171], v[44:47]
	v_mfma_f32_16x16x32_bf16 v[44:47], v[124:127], v[172:175], v[44:47]
	v_mfma_f32_16x16x32_bf16 v[40:43], v[128:131], v[168:171], v[40:43]
	v_mfma_f32_16x16x32_bf16 v[40:43], v[132:135], v[172:175], v[40:43]
	v_mfma_f32_16x16x32_bf16 v[28:31], v[120:123], v[176:179], v[28:31]
	v_mfma_f32_16x16x32_bf16 v[28:31], v[124:127], v[180:183], v[28:31]
	v_mfma_f32_16x16x32_bf16 v[24:27], v[128:131], v[176:179], v[24:27]
	v_mfma_f32_16x16x32_bf16 v[24:27], v[132:135], v[180:183], v[24:27]
	v_mfma_f32_16x16x32_bf16 v[12:15], v[120:123], v[184:187], v[12:15]
	v_mfma_f32_16x16x32_bf16 v[12:15], v[124:127], v[188:191], v[12:15]
	v_mfma_f32_16x16x32_bf16 v[8:11], v[128:131], v[184:187], v[8:11]
	v_mfma_f32_16x16x32_bf16 v[8:11], v[132:135], v[188:191], v[8:11]
	v_mfma_f32_16x16x32_bf16 v[52:55], v[144:147], v[160:163], v[52:55]
	v_mfma_f32_16x16x32_bf16 v[52:55], v[148:151], v[164:167], v[52:55]
	v_mfma_f32_16x16x32_bf16 v[48:51], v[152:155], v[160:163], v[48:51]
	v_mfma_f32_16x16x32_bf16 v[48:51], v[156:159], v[164:167], v[48:51]
	v_mfma_f32_16x16x32_bf16 v[36:39], v[144:147], v[168:171], v[36:39]
	v_mfma_f32_16x16x32_bf16 v[36:39], v[148:151], v[172:175], v[36:39]
	v_mfma_f32_16x16x32_bf16 v[32:35], v[152:155], v[168:171], v[32:35]
	v_mfma_f32_16x16x32_bf16 v[32:35], v[156:159], v[172:175], v[32:35]
	v_mfma_f32_16x16x32_bf16 v[20:23], v[144:147], v[176:179], v[20:23]
	v_mfma_f32_16x16x32_bf16 v[20:23], v[148:151], v[180:183], v[20:23]
	v_mfma_f32_16x16x32_bf16 v[16:19], v[152:155], v[176:179], v[16:19]
	v_mfma_f32_16x16x32_bf16 v[16:19], v[156:159], v[180:183], v[16:19]
	s_setprio 3
	s_barrier
	v_mfma_f32_16x16x32_bf16 v[4:7], v[144:147], v[184:187], v[4:7]
	v_mfma_f32_16x16x32_bf16 v[4:7], v[148:151], v[188:191], v[4:7]
	v_mfma_f32_16x16x32_bf16 v[0:3], v[152:155], v[184:187], v[0:3]
	v_mfma_f32_16x16x32_bf16 v[0:3], v[156:159], v[188:191], v[0:3]
	s_setprio 0
	s_add_i32 s67, 0, 0x18000
	s_add_i32 s75, 0, 0x1c000
	v_add_u32_e32 v132, s67, v243
	v_add_u32_e32 v156, s75, v243
	ds_read_b128 v[120:123], v132
	ds_read_b128 v[124:127], v132 offset:1024
	ds_read_b128 v[128:131], v132 offset:2048
	ds_read_b128 v[132:135], v132 offset:3072
	ds_read_b128 v[144:147], v156
	ds_read_b128 v[148:151], v156 offset:1024
	ds_read_b128 v[152:155], v156 offset:2048
	ds_read_b128 v[156:159], v156 offset:3072
	s_add_u32 s68, s80, 0x40000
	s_addc_u32 s69, s81, 0
	s_mov_b32 m0, s18
	v_lshl_add_u64 v[212:213], s[68:69], 0, v[192:193]
	ds_read_b128 v[160:163], v247 offset:32768
	ds_read_b128 v[164:167], v247 offset:33792
	ds_read_b128 v[168:171], v247 offset:34816
	ds_read_b128 v[172:175], v247 offset:35840
	ds_read_b128 v[176:179], v247 offset:36864
	ds_read_b128 v[180:183], v247 offset:37888
	ds_read_b128 v[184:187], v247 offset:38912
	ds_read_b128 v[188:191], v247 offset:39936
	global_load_lds_dwordx4 v[212:213], off
	v_lshl_add_u64 v[212:213], s[68:69], 0, v[196:197]
	s_mov_b32 m0, s19
	s_nop 0
	global_load_lds_dwordx4 v[212:213], off
	s_waitcnt vmcnt(8)
	s_waitcnt lgkmcnt(0)
	s_barrier
	s_setprio 1
	v_mfma_f32_16x16x32_bf16 v[140:143], v[120:123], v[160:163], v[140:143]
	v_mfma_f32_16x16x32_bf16 v[140:143], v[124:127], v[164:167], v[140:143]
	v_mfma_f32_16x16x32_bf16 v[136:139], v[128:131], v[160:163], v[136:139]
	v_mfma_f32_16x16x32_bf16 v[136:139], v[132:135], v[164:167], v[136:139]
	v_mfma_f32_16x16x32_bf16 v[108:111], v[120:123], v[168:171], v[108:111]
	v_mfma_f32_16x16x32_bf16 v[108:111], v[124:127], v[172:175], v[108:111]
	v_mfma_f32_16x16x32_bf16 v[104:107], v[128:131], v[168:171], v[104:107]
	v_mfma_f32_16x16x32_bf16 v[104:107], v[132:135], v[172:175], v[104:107]
	v_mfma_f32_16x16x32_bf16 v[92:95], v[120:123], v[176:179], v[92:95]
	v_mfma_f32_16x16x32_bf16 v[92:95], v[124:127], v[180:183], v[92:95]
	v_mfma_f32_16x16x32_bf16 v[88:91], v[128:131], v[176:179], v[88:91]
	v_mfma_f32_16x16x32_bf16 v[88:91], v[132:135], v[180:183], v[88:91]
	v_mfma_f32_16x16x32_bf16 v[76:79], v[120:123], v[184:187], v[76:79]
	v_mfma_f32_16x16x32_bf16 v[76:79], v[124:127], v[188:191], v[76:79]
	v_mfma_f32_16x16x32_bf16 v[72:75], v[128:131], v[184:187], v[72:75]
	v_mfma_f32_16x16x32_bf16 v[72:75], v[132:135], v[188:191], v[72:75]
	v_mfma_f32_16x16x32_bf16 v[116:119], v[144:147], v[160:163], v[116:119]
	v_mfma_f32_16x16x32_bf16 v[116:119], v[148:151], v[164:167], v[116:119]
	v_mfma_f32_16x16x32_bf16 v[112:115], v[152:155], v[160:163], v[112:115]
	v_mfma_f32_16x16x32_bf16 v[112:115], v[156:159], v[164:167], v[112:115]
	v_mfma_f32_16x16x32_bf16 v[100:103], v[144:147], v[168:171], v[100:103]
	v_mfma_f32_16x16x32_bf16 v[100:103], v[148:151], v[172:175], v[100:103]
	v_mfma_f32_16x16x32_bf16 v[96:99], v[152:155], v[168:171], v[96:99]
	v_mfma_f32_16x16x32_bf16 v[96:99], v[156:159], v[172:175], v[96:99]
	v_mfma_f32_16x16x32_bf16 v[84:87], v[144:147], v[176:179], v[84:87]
	v_mfma_f32_16x16x32_bf16 v[84:87], v[148:151], v[180:183], v[84:87]
	v_mfma_f32_16x16x32_bf16 v[80:83], v[152:155], v[176:179], v[80:83]
	v_mfma_f32_16x16x32_bf16 v[80:83], v[156:159], v[180:183], v[80:83]
	s_setprio 3
	s_barrier
	v_mfma_f32_16x16x32_bf16 v[68:71], v[144:147], v[184:187], v[68:71]
	v_mfma_f32_16x16x32_bf16 v[68:71], v[148:151], v[188:191], v[68:71]
	v_mfma_f32_16x16x32_bf16 v[64:67], v[152:155], v[184:187], v[64:67]
	v_mfma_f32_16x16x32_bf16 v[64:67], v[156:159], v[188:191], v[64:67]
	s_setprio 0
	s_add_i32 s67, s67, s15
	v_lshl_add_u64 v[204:205], v[204:205], 0, s[46:47]
	s_mov_b32 m0, s67
	ds_read_b128 v[160:163], v247 offset:49152
	ds_read_b128 v[164:167], v247 offset:50176
	ds_read_b128 v[168:171], v247 offset:51200
	ds_read_b128 v[172:175], v247 offset:52224
	ds_read_b128 v[176:179], v247 offset:53248
	ds_read_b128 v[180:183], v247 offset:54272
	ds_read_b128 v[184:187], v247 offset:55296
	ds_read_b128 v[188:191], v247 offset:56320
	global_load_lds_dwordx4 v[204:205], off
	s_add_i32 m0, s67, 0x2000
	s_add_u32 s68, s78, 0x40080
	v_lshl_add_u64 v[204:205], v[206:207], 0, s[46:47]
	s_addc_u32 s69, s79, 0
	s_add_i32 s67, s75, s15
	global_load_lds_dwordx4 v[204:205], off
	v_lshl_add_u64 v[204:205], s[68:69], 0, v[194:195]
	s_mov_b32 m0, s67
	s_nop 0
	global_load_lds_dwordx4 v[204:205], off
	v_lshl_add_u64 v[204:205], s[68:69], 0, v[198:199]
	s_add_i32 m0, s67, 0x2000
	s_nop 0
	global_load_lds_dwordx4 v[204:205], off
	v_lshl_add_u64 v[204:205], v[208:209], 0, s[46:47]
	s_mov_b32 m0, s21
	s_nop 0
	global_load_lds_dwordx4 v[204:205], off
	v_lshl_add_u64 v[204:205], v[210:211], 0, s[46:47]
	s_mov_b32 m0, s22
	s_nop 0
	global_load_lds_dwordx4 v[204:205], off
	s_waitcnt vmcnt(8)
	s_waitcnt lgkmcnt(0)
	s_barrier
	s_setprio 1
	v_mfma_f32_16x16x32_bf16 v[60:63], v[120:123], v[160:163], v[60:63]
	v_mfma_f32_16x16x32_bf16 v[60:63], v[124:127], v[164:167], v[60:63]
	v_mfma_f32_16x16x32_bf16 v[56:59], v[128:131], v[160:163], v[56:59]
	v_mfma_f32_16x16x32_bf16 v[56:59], v[132:135], v[164:167], v[56:59]
	v_mfma_f32_16x16x32_bf16 v[44:47], v[120:123], v[168:171], v[44:47]
	v_mfma_f32_16x16x32_bf16 v[44:47], v[124:127], v[172:175], v[44:47]
	v_mfma_f32_16x16x32_bf16 v[40:43], v[128:131], v[168:171], v[40:43]
	v_mfma_f32_16x16x32_bf16 v[40:43], v[132:135], v[172:175], v[40:43]
	v_mfma_f32_16x16x32_bf16 v[28:31], v[120:123], v[176:179], v[28:31]
	v_mfma_f32_16x16x32_bf16 v[28:31], v[124:127], v[180:183], v[28:31]
	v_mfma_f32_16x16x32_bf16 v[24:27], v[128:131], v[176:179], v[24:27]
	v_mfma_f32_16x16x32_bf16 v[24:27], v[132:135], v[180:183], v[24:27]
	v_mfma_f32_16x16x32_bf16 v[12:15], v[120:123], v[184:187], v[12:15]
	v_mfma_f32_16x16x32_bf16 v[12:15], v[124:127], v[188:191], v[12:15]
	v_mfma_f32_16x16x32_bf16 v[8:11], v[128:131], v[184:187], v[8:11]
	v_mfma_f32_16x16x32_bf16 v[8:11], v[132:135], v[188:191], v[8:11]
	v_mfma_f32_16x16x32_bf16 v[52:55], v[144:147], v[160:163], v[52:55]
	v_mfma_f32_16x16x32_bf16 v[52:55], v[148:151], v[164:167], v[52:55]
	v_mfma_f32_16x16x32_bf16 v[48:51], v[152:155], v[160:163], v[48:51]
	v_mfma_f32_16x16x32_bf16 v[48:51], v[156:159], v[164:167], v[48:51]
	v_mfma_f32_16x16x32_bf16 v[36:39], v[144:147], v[168:171], v[36:39]
	v_mfma_f32_16x16x32_bf16 v[36:39], v[148:151], v[172:175], v[36:39]
	v_mfma_f32_16x16x32_bf16 v[32:35], v[152:155], v[168:171], v[32:35]
	v_mfma_f32_16x16x32_bf16 v[32:35], v[156:159], v[172:175], v[32:35]
	v_mfma_f32_16x16x32_bf16 v[20:23], v[144:147], v[176:179], v[20:23]
	v_mfma_f32_16x16x32_bf16 v[20:23], v[148:151], v[180:183], v[20:23]
	v_mfma_f32_16x16x32_bf16 v[16:19], v[152:155], v[176:179], v[16:19]
	v_mfma_f32_16x16x32_bf16 v[16:19], v[156:159], v[180:183], v[16:19]
	s_setprio 3
	s_barrier
	v_mfma_f32_16x16x32_bf16 v[4:7], v[144:147], v[184:187], v[4:7]
	v_mfma_f32_16x16x32_bf16 v[4:7], v[148:151], v[188:191], v[4:7]
	v_mfma_f32_16x16x32_bf16 v[0:3], v[152:155], v[184:187], v[0:3]
	v_mfma_f32_16x16x32_bf16 v[0:3], v[156:159], v[188:191], v[0:3]
	s_setprio 0
	s_add_i32 s66, s66, 2
	s_add_u32 s76, s76, 0x100
	s_addc_u32 s77, s77, 0
	s_add_u32 s56, s56, 0x100
	s_addc_u32 s57, s57, 0
	s_cmp_gt_u32 s66, 13
	s_cbranch_scc0 .LBB0_2037
	s_and_b64 vcc, exec, s[48:49]
	s_cbranch_vccz .LBB0_2040
	s_barrier

.LBB0_2192:
	ds_read_b128 v[146:149], v174
	ds_read_b128 v[150:153], v174 offset:1024
	ds_read_b128 v[154:157], v174 offset:2048
	ds_read_b128 v[158:161], v174 offset:3072
	ds_read_b128 v[162:165], v175
	ds_read_b128 v[178:181], v175 offset:1024
	ds_read_b128 v[182:185], v175 offset:2048
	ds_read_b128 v[186:189], v175 offset:3072
	s_add_u32 s70, s58, 0xfffc0080
	s_addc_u32 s71, s59, -1
	s_cmp_eq_u32 s69, 12
	s_cselect_b32 s73, s47, s71
	s_cselect_b32 s72, s53, s70
	s_cselect_b32 s71, s45, s68
	s_cselect_b32 s70, s66, s67
	v_lshl_add_u64 v[166:167], s[58:59], 0, v[136:137]
	s_add_i32 m0, s17, 0xc000
	ds_read_b128 v[190:193], v176
	ds_read_b128 v[194:197], v176 offset:1024
	ds_read_b128 v[198:201], v176 offset:2048
	ds_read_b128 v[202:205], v176 offset:3072
	ds_read_b128 v[206:209], v176 offset:4096
	ds_read_b128 v[210:213], v176 offset:5120
	ds_read_b128 v[214:217], v176 offset:6144
	ds_read_b128 v[218:221], v176 offset:7168
	global_load_lds_dwordx4 v[166:167], off
	v_lshl_add_u64 v[166:167], s[58:59], 0, v[140:141]
	s_add_i32 m0, s17, 0xe000
	s_nop 0
	global_load_lds_dwordx4 v[166:167], off
	s_waitcnt vmcnt(8)
	s_waitcnt lgkmcnt(0)
	s_barrier
	s_setprio 1
	v_mfma_f32_16x16x32_bf16 v[124:127], v[146:149], v[190:193], v[124:127]
	v_mfma_f32_16x16x32_bf16 v[124:127], v[150:153], v[194:197], v[124:127]
	v_mfma_f32_16x16x32_bf16 v[116:119], v[154:157], v[190:193], v[116:119]
	v_mfma_f32_16x16x32_bf16 v[116:119], v[158:161], v[194:197], v[116:119]
	v_mfma_f32_16x16x32_bf16 v[108:111], v[146:149], v[198:201], v[108:111]
	v_mfma_f32_16x16x32_bf16 v[108:111], v[150:153], v[202:205], v[108:111]
	v_mfma_f32_16x16x32_bf16 v[100:103], v[154:157], v[198:201], v[100:103]
	v_mfma_f32_16x16x32_bf16 v[100:103], v[158:161], v[202:205], v[100:103]
	v_mfma_f32_16x16x32_bf16 v[92:95], v[146:149], v[206:209], v[92:95]
	v_mfma_f32_16x16x32_bf16 v[92:95], v[150:153], v[210:213], v[92:95]
	v_mfma_f32_16x16x32_bf16 v[84:87], v[154:157], v[206:209], v[84:87]
	v_mfma_f32_16x16x32_bf16 v[84:87], v[158:161], v[210:213], v[84:87]
	v_mfma_f32_16x16x32_bf16 v[76:79], v[146:149], v[214:217], v[76:79]
	v_mfma_f32_16x16x32_bf16 v[76:79], v[150:153], v[218:221], v[76:79]
	v_mfma_f32_16x16x32_bf16 v[68:71], v[154:157], v[214:217], v[68:71]
	v_mfma_f32_16x16x32_bf16 v[68:71], v[158:161], v[218:221], v[68:71]
	v_mfma_f32_16x16x32_bf16 v[120:123], v[162:165], v[190:193], v[120:123]
	v_mfma_f32_16x16x32_bf16 v[120:123], v[178:181], v[194:197], v[120:123]
	v_mfma_f32_16x16x32_bf16 v[112:115], v[182:185], v[190:193], v[112:115]
	v_mfma_f32_16x16x32_bf16 v[112:115], v[186:189], v[194:197], v[112:115]
	v_mfma_f32_16x16x32_bf16 v[104:107], v[162:165], v[198:201], v[104:107]
	v_mfma_f32_16x16x32_bf16 v[104:107], v[178:181], v[202:205], v[104:107]
	v_mfma_f32_16x16x32_bf16 v[96:99], v[182:185], v[198:201], v[96:99]
	v_mfma_f32_16x16x32_bf16 v[96:99], v[186:189], v[202:205], v[96:99]
	v_mfma_f32_16x16x32_bf16 v[88:91], v[162:165], v[206:209], v[88:91]
	v_mfma_f32_16x16x32_bf16 v[88:91], v[178:181], v[210:213], v[88:91]
	v_mfma_f32_16x16x32_bf16 v[80:83], v[182:185], v[206:209], v[80:83]
	v_mfma_f32_16x16x32_bf16 v[80:83], v[186:189], v[210:213], v[80:83]
	s_setprio 3
	s_barrier
	v_mfma_f32_16x16x32_bf16 v[72:75], v[162:165], v[214:217], v[72:75]
	v_mfma_f32_16x16x32_bf16 v[72:75], v[178:181], v[218:221], v[72:75]
	v_mfma_f32_16x16x32_bf16 v[64:67], v[182:185], v[214:217], v[64:67]
	v_mfma_f32_16x16x32_bf16 v[64:67], v[186:189], v[218:221], v[64:67]
	s_setprio 0
	s_add_i32 s74, s26, s16
	v_lshl_add_u64 v[166:167], s[70:71], 0, v[132:133]
	s_mov_b32 m0, s74
	ds_read_b128 v[190:193], v176 offset:16384
	ds_read_b128 v[194:197], v176 offset:17408
	ds_read_b128 v[198:201], v176 offset:18432
	ds_read_b128 v[202:205], v176 offset:19456
	ds_read_b128 v[206:209], v176 offset:20480
	ds_read_b128 v[210:213], v176 offset:21504
	ds_read_b128 v[214:217], v176 offset:22528
	ds_read_b128 v[218:221], v176 offset:23552
	global_load_lds_dwordx4 v[166:167], off
	s_add_i32 m0, s74, 0x2000
	s_add_u32 s74, s70, 0x40000
	v_lshl_add_u64 v[222:223], s[70:71], 0, v[128:129]
	s_addc_u32 s75, s71, 0
	s_add_i32 s76, s27, s16
	global_load_lds_dwordx4 v[222:223], off
	v_lshl_add_u64 v[224:225], s[74:75], 0, v[132:133]
	s_mov_b32 m0, s76
	v_lshl_add_u64 v[226:227], s[72:73], 0, v[130:131]
	global_load_lds_dwordx4 v[224:225], off
	v_lshl_add_u64 v[224:225], s[74:75], 0, v[128:129]
	s_add_i32 m0, s76, 0x2000
	s_nop 0
	global_load_lds_dwordx4 v[224:225], off
	v_lshl_add_u64 v[224:225], s[72:73], 0, v[134:135]
	s_mov_b32 m0, s17
	s_nop 0
	global_load_lds_dwordx4 v[224:225], off
	s_mov_b32 m0, s18
	s_nop 0
	global_load_lds_dwordx4 v[226:227], off
	s_waitcnt vmcnt(8)
	s_waitcnt lgkmcnt(0)
	s_barrier
	s_setprio 1
	v_mfma_f32_16x16x32_bf16 v[60:63], v[146:149], v[190:193], v[60:63]
	v_mfma_f32_16x16x32_bf16 v[60:63], v[150:153], v[194:197], v[60:63]
	v_mfma_f32_16x16x32_bf16 v[52:55], v[154:157], v[190:193], v[52:55]
	v_mfma_f32_16x16x32_bf16 v[52:55], v[158:161], v[194:197], v[52:55]
	v_mfma_f32_16x16x32_bf16 v[44:47], v[146:149], v[198:201], v[44:47]
	v_mfma_f32_16x16x32_bf16 v[44:47], v[150:153], v[202:205], v[44:47]
	v_mfma_f32_16x16x32_bf16 v[36:39], v[154:157], v[198:201], v[36:39]
	v_mfma_f32_16x16x32_bf16 v[36:39], v[158:161], v[202:205], v[36:39]
	v_mfma_f32_16x16x32_bf16 v[28:31], v[146:149], v[206:209], v[28:31]
	v_mfma_f32_16x16x32_bf16 v[28:31], v[150:153], v[210:213], v[28:31]
	v_mfma_f32_16x16x32_bf16 v[20:23], v[154:157], v[206:209], v[20:23]
	v_mfma_f32_16x16x32_bf16 v[20:23], v[158:161], v[210:213], v[20:23]
	v_mfma_f32_16x16x32_bf16 v[12:15], v[146:149], v[214:217], v[12:15]
	v_mfma_f32_16x16x32_bf16 v[12:15], v[150:153], v[218:221], v[12:15]
	v_mfma_f32_16x16x32_bf16 v[4:7], v[154:157], v[214:217], v[4:7]
	v_mfma_f32_16x16x32_bf16 v[4:7], v[158:161], v[218:221], v[4:7]
	v_mfma_f32_16x16x32_bf16 v[56:59], v[162:165], v[190:193], v[56:59]
	v_mfma_f32_16x16x32_bf16 v[56:59], v[178:181], v[194:197], v[56:59]
	v_mfma_f32_16x16x32_bf16 v[48:51], v[182:185], v[190:193], v[48:51]
	v_mfma_f32_16x16x32_bf16 v[48:51], v[186:189], v[194:197], v[48:51]
	v_mfma_f32_16x16x32_bf16 v[40:43], v[162:165], v[198:201], v[40:43]
	v_mfma_f32_16x16x32_bf16 v[40:43], v[178:181], v[202:205], v[40:43]
	v_mfma_f32_16x16x32_bf16 v[32:35], v[182:185], v[198:201], v[32:35]
	v_mfma_f32_16x16x32_bf16 v[32:35], v[186:189], v[202:205], v[32:35]
	v_mfma_f32_16x16x32_bf16 v[24:27], v[162:165], v[206:209], v[24:27]
	v_mfma_f32_16x16x32_bf16 v[24:27], v[178:181], v[210:213], v[24:27]
	v_mfma_f32_16x16x32_bf16 v[16:19], v[182:185], v[206:209], v[16:19]
	v_mfma_f32_16x16x32_bf16 v[16:19], v[186:189], v[210:213], v[16:19]
	s_setprio 3
	s_barrier
	v_mfma_f32_16x16x32_bf16 v[8:11], v[162:165], v[214:217], v[8:11]
	v_mfma_f32_16x16x32_bf16 v[8:11], v[178:181], v[218:221], v[8:11]
	v_mfma_f32_16x16x32_bf16 v[0:3], v[182:185], v[214:217], v[0:3]
	v_mfma_f32_16x16x32_bf16 v[0:3], v[186:189], v[218:221], v[0:3]
	s_setprio 0
	s_add_i32 s74, 0, 0x18000
	s_add_i32 s75, 0, 0x1c000
	v_add_u32_e32 v158, s74, v171
	v_add_u32_e32 v186, s75, v171
	ds_read_b128 v[146:149], v158
	ds_read_b128 v[150:153], v158 offset:1024
	ds_read_b128 v[154:157], v158 offset:2048
	ds_read_b128 v[158:161], v158 offset:3072
	ds_read_b128 v[162:165], v186
	ds_read_b128 v[178:181], v186 offset:1024
	ds_read_b128 v[182:185], v186 offset:2048
	ds_read_b128 v[186:189], v186 offset:3072
	s_add_u32 s72, s72, 0x40000
	s_addc_u32 s73, s73, 0
	s_mov_b32 m0, s19
	v_lshl_add_u64 v[228:229], s[72:73], 0, v[134:135]
	ds_read_b128 v[190:193], v176 offset:32768
	ds_read_b128 v[194:197], v176 offset:33792
	ds_read_b128 v[198:201], v176 offset:34816
	ds_read_b128 v[202:205], v176 offset:35840
	ds_read_b128 v[206:209], v176 offset:36864
	ds_read_b128 v[210:213], v176 offset:37888
	ds_read_b128 v[214:217], v176 offset:38912
	ds_read_b128 v[218:221], v176 offset:39936
	global_load_lds_dwordx4 v[228:229], off
	v_lshl_add_u64 v[228:229], s[72:73], 0, v[130:131]
	s_mov_b32 m0, s20
	s_nop 0
	global_load_lds_dwordx4 v[228:229], off
	s_waitcnt vmcnt(8)
	s_waitcnt lgkmcnt(0)
	s_barrier
	s_setprio 1
	v_mfma_f32_16x16x32_bf16 v[124:127], v[146:149], v[190:193], v[124:127]
	v_mfma_f32_16x16x32_bf16 v[124:127], v[150:153], v[194:197], v[124:127]
	v_mfma_f32_16x16x32_bf16 v[116:119], v[154:157], v[190:193], v[116:119]
	v_mfma_f32_16x16x32_bf16 v[116:119], v[158:161], v[194:197], v[116:119]
	v_mfma_f32_16x16x32_bf16 v[108:111], v[146:149], v[198:201], v[108:111]
	v_mfma_f32_16x16x32_bf16 v[108:111], v[150:153], v[202:205], v[108:111]
	v_mfma_f32_16x16x32_bf16 v[100:103], v[154:157], v[198:201], v[100:103]
	v_mfma_f32_16x16x32_bf16 v[100:103], v[158:161], v[202:205], v[100:103]
	v_mfma_f32_16x16x32_bf16 v[92:95], v[146:149], v[206:209], v[92:95]
	v_mfma_f32_16x16x32_bf16 v[92:95], v[150:153], v[210:213], v[92:95]
	v_mfma_f32_16x16x32_bf16 v[84:87], v[154:157], v[206:209], v[84:87]
	v_mfma_f32_16x16x32_bf16 v[84:87], v[158:161], v[210:213], v[84:87]
	v_mfma_f32_16x16x32_bf16 v[76:79], v[146:149], v[214:217], v[76:79]
	v_mfma_f32_16x16x32_bf16 v[76:79], v[150:153], v[218:221], v[76:79]
	v_mfma_f32_16x16x32_bf16 v[68:71], v[154:157], v[214:217], v[68:71]
	v_mfma_f32_16x16x32_bf16 v[68:71], v[158:161], v[218:221], v[68:71]
	v_mfma_f32_16x16x32_bf16 v[120:123], v[162:165], v[190:193], v[120:123]
	v_mfma_f32_16x16x32_bf16 v[120:123], v[178:181], v[194:197], v[120:123]
	v_mfma_f32_16x16x32_bf16 v[112:115], v[182:185], v[190:193], v[112:115]
	v_mfma_f32_16x16x32_bf16 v[112:115], v[186:189], v[194:197], v[112:115]
	v_mfma_f32_16x16x32_bf16 v[104:107], v[162:165], v[198:201], v[104:107]
	v_mfma_f32_16x16x32_bf16 v[104:107], v[178:181], v[202:205], v[104:107]
	v_mfma_f32_16x16x32_bf16 v[96:99], v[182:185], v[198:201], v[96:99]
	v_mfma_f32_16x16x32_bf16 v[96:99], v[186:189], v[202:205], v[96:99]
	v_mfma_f32_16x16x32_bf16 v[88:91], v[162:165], v[206:209], v[88:91]
	v_mfma_f32_16x16x32_bf16 v[88:91], v[178:181], v[210:213], v[88:91]
	v_mfma_f32_16x16x32_bf16 v[80:83], v[182:185], v[206:209], v[80:83]
	v_mfma_f32_16x16x32_bf16 v[80:83], v[186:189], v[210:213], v[80:83]
	s_setprio 3
	s_barrier
	v_mfma_f32_16x16x32_bf16 v[72:75], v[162:165], v[214:217], v[72:75]
	v_mfma_f32_16x16x32_bf16 v[72:75], v[178:181], v[218:221], v[72:75]
	v_mfma_f32_16x16x32_bf16 v[64:67], v[182:185], v[214:217], v[64:67]
	v_mfma_f32_16x16x32_bf16 v[64:67], v[186:189], v[218:221], v[64:67]
	s_setprio 0
	s_add_i32 s72, s74, s16
	v_lshl_add_u64 v[166:167], v[166:167], 0, s[10:11]
	s_mov_b32 m0, s72
	ds_read_b128 v[190:193], v176 offset:49152
	ds_read_b128 v[194:197], v176 offset:50176
	ds_read_b128 v[198:201], v176 offset:51200
	ds_read_b128 v[202:205], v176 offset:52224
	ds_read_b128 v[206:209], v176 offset:53248
	ds_read_b128 v[210:213], v176 offset:54272
	ds_read_b128 v[214:217], v176 offset:55296
	ds_read_b128 v[218:221], v176 offset:56320
	global_load_lds_dwordx4 v[166:167], off
	s_add_i32 m0, s72, 0x2000
	s_add_u32 s70, s70, 0x40080
	v_lshl_add_u64 v[166:167], v[222:223], 0, s[10:11]
	s_addc_u32 s71, s71, 0
	s_add_i32 s72, s75, s16
	global_load_lds_dwordx4 v[166:167], off
	v_lshl_add_u64 v[166:167], s[70:71], 0, v[132:133]
	s_mov_b32 m0, s72
	s_nop 0
	global_load_lds_dwordx4 v[166:167], off
	v_lshl_add_u64 v[166:167], s[70:71], 0, v[128:129]
	s_add_i32 m0, s72, 0x2000
	s_nop 0
	global_load_lds_dwordx4 v[166:167], off
	v_lshl_add_u64 v[166:167], v[224:225], 0, s[10:11]
	s_mov_b32 m0, s23
	s_nop 0
	global_load_lds_dwordx4 v[166:167], off
	v_lshl_add_u64 v[166:167], v[226:227], 0, s[10:11]
	s_mov_b32 m0, s24
	s_nop 0
	global_load_lds_dwordx4 v[166:167], off
	s_waitcnt vmcnt(8)
	s_waitcnt lgkmcnt(0)
	s_barrier
	s_setprio 1
	v_mfma_f32_16x16x32_bf16 v[60:63], v[146:149], v[190:193], v[60:63]
	v_mfma_f32_16x16x32_bf16 v[60:63], v[150:153], v[194:197], v[60:63]
	v_mfma_f32_16x16x32_bf16 v[52:55], v[154:157], v[190:193], v[52:55]
	v_mfma_f32_16x16x32_bf16 v[52:55], v[158:161], v[194:197], v[52:55]
	v_mfma_f32_16x16x32_bf16 v[44:47], v[146:149], v[198:201], v[44:47]
	v_mfma_f32_16x16x32_bf16 v[44:47], v[150:153], v[202:205], v[44:47]
	v_mfma_f32_16x16x32_bf16 v[36:39], v[154:157], v[198:201], v[36:39]
	v_mfma_f32_16x16x32_bf16 v[36:39], v[158:161], v[202:205], v[36:39]
	v_mfma_f32_16x16x32_bf16 v[28:31], v[146:149], v[206:209], v[28:31]
	v_mfma_f32_16x16x32_bf16 v[28:31], v[150:153], v[210:213], v[28:31]
	v_mfma_f32_16x16x32_bf16 v[20:23], v[154:157], v[206:209], v[20:23]
	v_mfma_f32_16x16x32_bf16 v[20:23], v[158:161], v[210:213], v[20:23]
	v_mfma_f32_16x16x32_bf16 v[12:15], v[146:149], v[214:217], v[12:15]
	v_mfma_f32_16x16x32_bf16 v[12:15], v[150:153], v[218:221], v[12:15]
	v_mfma_f32_16x16x32_bf16 v[4:7], v[154:157], v[214:217], v[4:7]
	v_mfma_f32_16x16x32_bf16 v[4:7], v[158:161], v[218:221], v[4:7]
	v_mfma_f32_16x16x32_bf16 v[56:59], v[162:165], v[190:193], v[56:59]
	v_mfma_f32_16x16x32_bf16 v[56:59], v[178:181], v[194:197], v[56:59]
	v_mfma_f32_16x16x32_bf16 v[48:51], v[182:185], v[190:193], v[48:51]
	v_mfma_f32_16x16x32_bf16 v[48:51], v[186:189], v[194:197], v[48:51]
	v_mfma_f32_16x16x32_bf16 v[40:43], v[162:165], v[198:201], v[40:43]
	v_mfma_f32_16x16x32_bf16 v[40:43], v[178:181], v[202:205], v[40:43]
	v_mfma_f32_16x16x32_bf16 v[32:35], v[182:185], v[198:201], v[32:35]
	v_mfma_f32_16x16x32_bf16 v[32:35], v[186:189], v[202:205], v[32:35]
	v_mfma_f32_16x16x32_bf16 v[24:27], v[162:165], v[206:209], v[24:27]
	v_mfma_f32_16x16x32_bf16 v[24:27], v[178:181], v[210:213], v[24:27]
	v_mfma_f32_16x16x32_bf16 v[16:19], v[182:185], v[206:209], v[16:19]
	v_mfma_f32_16x16x32_bf16 v[16:19], v[186:189], v[210:213], v[16:19]
	s_setprio 3
	s_barrier
	v_mfma_f32_16x16x32_bf16 v[8:11], v[162:165], v[214:217], v[8:11]
	v_mfma_f32_16x16x32_bf16 v[8:11], v[178:181], v[218:221], v[8:11]
	v_mfma_f32_16x16x32_bf16 v[0:3], v[182:185], v[214:217], v[0:3]
	v_mfma_f32_16x16x32_bf16 v[0:3], v[186:189], v[218:221], v[0:3]
	s_setprio 0
	s_add_i32 s69, s69, 2
	s_add_u32 s58, s58, 0x100
	s_addc_u32 s59, s59, 0
	s_add_u32 s67, s67, 0x100
	s_addc_u32 s68, s68, 0
	s_cmp_gt_u32 s69, 13
	s_cbranch_scc0 .LBB0_2192
	s_and_b64 vcc, exec, s[42:43]
	s_cbranch_vccz .LBB0_2195
	s_barrier

.LBB0_2341:
	ds_read_b128 v[128:131], v197
	ds_read_b128 v[132:135], v197 offset:1024
	ds_read_b128 v[136:139], v197 offset:2048
	ds_read_b128 v[140:143], v197 offset:3072
	ds_read_b128 v[144:147], v198
	ds_read_b128 v[148:151], v198 offset:1024
	ds_read_b128 v[152:155], v198 offset:2048
	ds_read_b128 v[156:159], v198 offset:3072
	s_add_u32 s18, s16, 0xfff50080
	s_addc_u32 s19, s17, -1
	s_cmp_eq_u32 s45, 40
	s_cselect_b32 s21, s5, s19
	s_cselect_b32 s20, s4, s18
	s_cselect_b32 s19, s15, s44
	s_cselect_b32 s18, s14, s43
	v_lshl_add_u64 v[192:193], s[16:17], 0, v[172:173]
	s_add_i32 m0, s25, 0xc000
	ds_read_b128 v[160:163], v199
	ds_read_b128 v[180:183], v199 offset:1024
	ds_read_b128 v[184:187], v199 offset:2048
	ds_read_b128 v[188:191], v199 offset:3072
	ds_read_b128 v[200:203], v199 offset:4096
	ds_read_b128 v[204:207], v199 offset:5120
	ds_read_b128 v[208:211], v199 offset:6144
	ds_read_b128 v[212:215], v199 offset:7168
	global_load_lds_dwordx4 v[192:193], off
	v_lshl_add_u64 v[192:193], s[16:17], 0, v[174:175]
	s_add_i32 m0, s25, 0xe000
	s_nop 0
	global_load_lds_dwordx4 v[192:193], off
	s_waitcnt vmcnt(8)
	s_waitcnt lgkmcnt(0)
	s_barrier
	s_setprio 1
	v_mfma_f32_16x16x32_bf16 v[124:127], v[128:131], v[160:163], v[124:127]
	v_mfma_f32_16x16x32_bf16 v[124:127], v[132:135], v[180:183], v[124:127]
	v_mfma_f32_16x16x32_bf16 v[120:123], v[136:139], v[160:163], v[120:123]
	v_mfma_f32_16x16x32_bf16 v[120:123], v[140:143], v[180:183], v[120:123]
	v_mfma_f32_16x16x32_bf16 v[108:111], v[128:131], v[184:187], v[108:111]
	v_mfma_f32_16x16x32_bf16 v[108:111], v[132:135], v[188:191], v[108:111]
	v_mfma_f32_16x16x32_bf16 v[104:107], v[136:139], v[184:187], v[104:107]
	v_mfma_f32_16x16x32_bf16 v[104:107], v[140:143], v[188:191], v[104:107]
	v_mfma_f32_16x16x32_bf16 v[96:99], v[128:131], v[200:203], v[96:99]
	v_mfma_f32_16x16x32_bf16 v[96:99], v[132:135], v[204:207], v[96:99]
	v_mfma_f32_16x16x32_bf16 v[88:91], v[136:139], v[200:203], v[88:91]
	v_mfma_f32_16x16x32_bf16 v[88:91], v[140:143], v[204:207], v[88:91]
	v_mfma_f32_16x16x32_bf16 v[80:83], v[128:131], v[208:211], v[80:83]
	v_mfma_f32_16x16x32_bf16 v[80:83], v[132:135], v[212:215], v[80:83]
	v_mfma_f32_16x16x32_bf16 v[72:75], v[136:139], v[208:211], v[72:75]
	v_mfma_f32_16x16x32_bf16 v[72:75], v[140:143], v[212:215], v[72:75]
	v_mfma_f32_16x16x32_bf16 v[116:119], v[144:147], v[160:163], v[116:119]
	v_mfma_f32_16x16x32_bf16 v[116:119], v[148:151], v[180:183], v[116:119]
	v_mfma_f32_16x16x32_bf16 v[112:115], v[152:155], v[160:163], v[112:115]
	v_mfma_f32_16x16x32_bf16 v[112:115], v[156:159], v[180:183], v[112:115]
	v_mfma_f32_16x16x32_bf16 v[100:103], v[144:147], v[184:187], v[100:103]
	v_mfma_f32_16x16x32_bf16 v[100:103], v[148:151], v[188:191], v[100:103]
	v_mfma_f32_16x16x32_bf16 v[92:95], v[152:155], v[184:187], v[92:95]
	v_mfma_f32_16x16x32_bf16 v[92:95], v[156:159], v[188:191], v[92:95]
	v_mfma_f32_16x16x32_bf16 v[84:87], v[144:147], v[200:203], v[84:87]
	v_mfma_f32_16x16x32_bf16 v[84:87], v[148:151], v[204:207], v[84:87]
	v_mfma_f32_16x16x32_bf16 v[76:79], v[152:155], v[200:203], v[76:79]
	v_mfma_f32_16x16x32_bf16 v[76:79], v[156:159], v[204:207], v[76:79]
	s_setprio 3
	s_barrier
	v_mfma_f32_16x16x32_bf16 v[68:71], v[144:147], v[208:211], v[68:71]
	v_mfma_f32_16x16x32_bf16 v[68:71], v[148:151], v[212:215], v[68:71]
	v_mfma_f32_16x16x32_bf16 v[64:67], v[152:155], v[208:211], v[64:67]
	v_mfma_f32_16x16x32_bf16 v[64:67], v[156:159], v[212:215], v[64:67]
	s_setprio 0
	s_add_i32 s46, s37, s24
	v_lshl_add_u64 v[192:193], s[18:19], 0, v[166:167]
	s_mov_b32 m0, s46
	ds_read_b128 v[160:163], v199 offset:16384
	ds_read_b128 v[180:183], v199 offset:17408
	ds_read_b128 v[184:187], v199 offset:18432
	ds_read_b128 v[188:191], v199 offset:19456
	ds_read_b128 v[200:203], v199 offset:20480
	ds_read_b128 v[204:207], v199 offset:21504
	ds_read_b128 v[208:211], v199 offset:22528
	ds_read_b128 v[212:215], v199 offset:23552
	global_load_lds_dwordx4 v[192:193], off
	s_add_i32 m0, s46, 0x2000
	s_add_u32 s46, s18, 0xb0000
	v_lshl_add_u64 v[216:217], s[18:19], 0, v[170:171]
	s_addc_u32 s47, s19, 0
	s_add_i32 s48, s38, s24
	global_load_lds_dwordx4 v[216:217], off
	v_lshl_add_u64 v[218:219], s[46:47], 0, v[166:167]
	s_mov_b32 m0, s48
	v_lshl_add_u64 v[220:221], s[20:21], 0, v[168:169]
	global_load_lds_dwordx4 v[218:219], off
	v_lshl_add_u64 v[218:219], s[46:47], 0, v[170:171]
	s_add_i32 m0, s48, 0x2000
	s_nop 0
	global_load_lds_dwordx4 v[218:219], off
	v_lshl_add_u64 v[218:219], s[20:21], 0, v[164:165]
	s_mov_b32 m0, s25
	s_nop 0
	global_load_lds_dwordx4 v[218:219], off
	s_mov_b32 m0, s26
	s_nop 0
	global_load_lds_dwordx4 v[220:221], off
	s_waitcnt vmcnt(8)
	s_waitcnt lgkmcnt(0)
	s_barrier
	s_setprio 1
	v_mfma_f32_16x16x32_bf16 v[60:63], v[128:131], v[160:163], v[60:63]
	v_mfma_f32_16x16x32_bf16 v[60:63], v[132:135], v[180:183], v[60:63]
	v_mfma_f32_16x16x32_bf16 v[56:59], v[136:139], v[160:163], v[56:59]
	v_mfma_f32_16x16x32_bf16 v[56:59], v[140:143], v[180:183], v[56:59]
	v_mfma_f32_16x16x32_bf16 v[48:51], v[128:131], v[184:187], v[48:51]
	v_mfma_f32_16x16x32_bf16 v[48:51], v[132:135], v[188:191], v[48:51]
	v_mfma_f32_16x16x32_bf16 v[40:43], v[136:139], v[184:187], v[40:43]
	v_mfma_f32_16x16x32_bf16 v[40:43], v[140:143], v[188:191], v[40:43]
	v_mfma_f32_16x16x32_bf16 v[32:35], v[128:131], v[200:203], v[32:35]
	v_mfma_f32_16x16x32_bf16 v[32:35], v[132:135], v[204:207], v[32:35]
	v_mfma_f32_16x16x32_bf16 v[24:27], v[136:139], v[200:203], v[24:27]
	v_mfma_f32_16x16x32_bf16 v[24:27], v[140:143], v[204:207], v[24:27]
	v_mfma_f32_16x16x32_bf16 v[16:19], v[128:131], v[208:211], v[16:19]
	v_mfma_f32_16x16x32_bf16 v[16:19], v[132:135], v[212:215], v[16:19]
	v_mfma_f32_16x16x32_bf16 v[8:11], v[136:139], v[208:211], v[8:11]
	v_mfma_f32_16x16x32_bf16 v[8:11], v[140:143], v[212:215], v[8:11]
	v_mfma_f32_16x16x32_bf16 v[52:55], v[144:147], v[160:163], v[52:55]
	v_mfma_f32_16x16x32_bf16 v[52:55], v[148:151], v[180:183], v[52:55]
	v_mfma_f32_16x16x32_bf16 v[44:47], v[152:155], v[160:163], v[44:47]
	v_mfma_f32_16x16x32_bf16 v[44:47], v[156:159], v[180:183], v[44:47]
	v_mfma_f32_16x16x32_bf16 v[36:39], v[144:147], v[184:187], v[36:39]
	v_mfma_f32_16x16x32_bf16 v[36:39], v[148:151], v[188:191], v[36:39]
	v_mfma_f32_16x16x32_bf16 v[28:31], v[152:155], v[184:187], v[28:31]
	v_mfma_f32_16x16x32_bf16 v[28:31], v[156:159], v[188:191], v[28:31]
	v_mfma_f32_16x16x32_bf16 v[20:23], v[144:147], v[200:203], v[20:23]
	v_mfma_f32_16x16x32_bf16 v[20:23], v[148:151], v[204:207], v[20:23]
	v_mfma_f32_16x16x32_bf16 v[12:15], v[152:155], v[200:203], v[12:15]
	v_mfma_f32_16x16x32_bf16 v[12:15], v[156:159], v[204:207], v[12:15]
	s_setprio 3
	s_barrier
	v_mfma_f32_16x16x32_bf16 v[4:7], v[144:147], v[208:211], v[4:7]
	v_mfma_f32_16x16x32_bf16 v[4:7], v[148:151], v[212:215], v[4:7]
	v_mfma_f32_16x16x32_bf16 v[0:3], v[152:155], v[208:211], v[0:3]
	v_mfma_f32_16x16x32_bf16 v[0:3], v[156:159], v[212:215], v[0:3]
	s_setprio 0
	s_add_i32 s46, 0, 0x18000
	s_add_i32 s47, 0, 0x1c000
	v_add_u32_e32 v140, s46, v195
	v_add_u32_e32 v156, s47, v195
	ds_read_b128 v[128:131], v140
	ds_read_b128 v[132:135], v140 offset:1024
	ds_read_b128 v[136:139], v140 offset:2048
	ds_read_b128 v[140:143], v140 offset:3072
	ds_read_b128 v[144:147], v156
	ds_read_b128 v[148:151], v156 offset:1024
	ds_read_b128 v[152:155], v156 offset:2048
	ds_read_b128 v[156:159], v156 offset:3072
	s_add_u32 s20, s20, 0xb0000
	s_addc_u32 s21, s21, 0
	s_mov_b32 m0, s27
	v_lshl_add_u64 v[222:223], s[20:21], 0, v[164:165]
	ds_read_b128 v[160:163], v199 offset:32768
	ds_read_b128 v[180:183], v199 offset:33792
	ds_read_b128 v[184:187], v199 offset:34816
	ds_read_b128 v[188:191], v199 offset:35840
	ds_read_b128 v[200:203], v199 offset:36864
	ds_read_b128 v[204:207], v199 offset:37888
	ds_read_b128 v[208:211], v199 offset:38912
	ds_read_b128 v[212:215], v199 offset:39936
	global_load_lds_dwordx4 v[222:223], off
	v_lshl_add_u64 v[222:223], s[20:21], 0, v[168:169]
	s_mov_b32 m0, s28
	s_nop 0
	global_load_lds_dwordx4 v[222:223], off
	s_waitcnt vmcnt(8)
	s_waitcnt lgkmcnt(0)
	s_barrier
	s_setprio 1
	v_mfma_f32_16x16x32_bf16 v[124:127], v[128:131], v[160:163], v[124:127]
	v_mfma_f32_16x16x32_bf16 v[124:127], v[132:135], v[180:183], v[124:127]
	v_mfma_f32_16x16x32_bf16 v[120:123], v[136:139], v[160:163], v[120:123]
	v_mfma_f32_16x16x32_bf16 v[120:123], v[140:143], v[180:183], v[120:123]
	v_mfma_f32_16x16x32_bf16 v[108:111], v[128:131], v[184:187], v[108:111]
	v_mfma_f32_16x16x32_bf16 v[108:111], v[132:135], v[188:191], v[108:111]
	v_mfma_f32_16x16x32_bf16 v[104:107], v[136:139], v[184:187], v[104:107]
	v_mfma_f32_16x16x32_bf16 v[104:107], v[140:143], v[188:191], v[104:107]
	v_mfma_f32_16x16x32_bf16 v[96:99], v[128:131], v[200:203], v[96:99]
	v_mfma_f32_16x16x32_bf16 v[96:99], v[132:135], v[204:207], v[96:99]
	v_mfma_f32_16x16x32_bf16 v[88:91], v[136:139], v[200:203], v[88:91]
	v_mfma_f32_16x16x32_bf16 v[88:91], v[140:143], v[204:207], v[88:91]
	v_mfma_f32_16x16x32_bf16 v[80:83], v[128:131], v[208:211], v[80:83]
	v_mfma_f32_16x16x32_bf16 v[80:83], v[132:135], v[212:215], v[80:83]
	v_mfma_f32_16x16x32_bf16 v[72:75], v[136:139], v[208:211], v[72:75]
	v_mfma_f32_16x16x32_bf16 v[72:75], v[140:143], v[212:215], v[72:75]
	v_mfma_f32_16x16x32_bf16 v[116:119], v[144:147], v[160:163], v[116:119]
	v_mfma_f32_16x16x32_bf16 v[116:119], v[148:151], v[180:183], v[116:119]
	v_mfma_f32_16x16x32_bf16 v[112:115], v[152:155], v[160:163], v[112:115]
	v_mfma_f32_16x16x32_bf16 v[112:115], v[156:159], v[180:183], v[112:115]
	v_mfma_f32_16x16x32_bf16 v[100:103], v[144:147], v[184:187], v[100:103]
	v_mfma_f32_16x16x32_bf16 v[100:103], v[148:151], v[188:191], v[100:103]
	v_mfma_f32_16x16x32_bf16 v[92:95], v[152:155], v[184:187], v[92:95]
	v_mfma_f32_16x16x32_bf16 v[92:95], v[156:159], v[188:191], v[92:95]
	v_mfma_f32_16x16x32_bf16 v[84:87], v[144:147], v[200:203], v[84:87]
	v_mfma_f32_16x16x32_bf16 v[84:87], v[148:151], v[204:207], v[84:87]
	v_mfma_f32_16x16x32_bf16 v[76:79], v[152:155], v[200:203], v[76:79]
	v_mfma_f32_16x16x32_bf16 v[76:79], v[156:159], v[204:207], v[76:79]
	s_setprio 3
	s_barrier
	v_mfma_f32_16x16x32_bf16 v[68:71], v[144:147], v[208:211], v[68:71]
	v_mfma_f32_16x16x32_bf16 v[68:71], v[148:151], v[212:215], v[68:71]
	v_mfma_f32_16x16x32_bf16 v[64:67], v[152:155], v[208:211], v[64:67]
	v_mfma_f32_16x16x32_bf16 v[64:67], v[156:159], v[212:215], v[64:67]
	s_setprio 0
	s_add_i32 s20, s46, s24
	v_lshl_add_u64 v[192:193], v[192:193], 0, s[8:9]
	s_mov_b32 m0, s20
	ds_read_b128 v[160:163], v199 offset:49152
	ds_read_b128 v[180:183], v199 offset:50176
	ds_read_b128 v[184:187], v199 offset:51200
	ds_read_b128 v[188:191], v199 offset:52224
	ds_read_b128 v[200:203], v199 offset:53248
	ds_read_b128 v[204:207], v199 offset:54272
	ds_read_b128 v[208:211], v199 offset:55296
	ds_read_b128 v[212:215], v199 offset:56320
	global_load_lds_dwordx4 v[192:193], off
	s_add_i32 m0, s20, 0x2000
	s_add_u32 s18, s18, 0xb0080
	v_lshl_add_u64 v[192:193], v[216:217], 0, s[8:9]
	s_addc_u32 s19, s19, 0
	s_add_i32 s20, s47, s24
	global_load_lds_dwordx4 v[192:193], off
	v_lshl_add_u64 v[192:193], s[18:19], 0, v[166:167]
	s_mov_b32 m0, s20
	s_nop 0
	global_load_lds_dwordx4 v[192:193], off
	v_lshl_add_u64 v[192:193], s[18:19], 0, v[170:171]
	s_add_i32 m0, s20, 0x2000
	s_nop 0
	global_load_lds_dwordx4 v[192:193], off
	v_lshl_add_u64 v[192:193], v[218:219], 0, s[8:9]
	s_mov_b32 m0, s33
	s_nop 0
	global_load_lds_dwordx4 v[192:193], off
	v_lshl_add_u64 v[192:193], v[220:221], 0, s[8:9]
	s_mov_b32 m0, s35
	s_nop 0
	global_load_lds_dwordx4 v[192:193], off
	s_waitcnt vmcnt(8)
	s_waitcnt lgkmcnt(0)
	s_barrier
	s_setprio 1
	v_mfma_f32_16x16x32_bf16 v[60:63], v[128:131], v[160:163], v[60:63]
	v_mfma_f32_16x16x32_bf16 v[60:63], v[132:135], v[180:183], v[60:63]
	v_mfma_f32_16x16x32_bf16 v[56:59], v[136:139], v[160:163], v[56:59]
	v_mfma_f32_16x16x32_bf16 v[56:59], v[140:143], v[180:183], v[56:59]
	v_mfma_f32_16x16x32_bf16 v[48:51], v[128:131], v[184:187], v[48:51]
	v_mfma_f32_16x16x32_bf16 v[48:51], v[132:135], v[188:191], v[48:51]
	v_mfma_f32_16x16x32_bf16 v[40:43], v[136:139], v[184:187], v[40:43]
	v_mfma_f32_16x16x32_bf16 v[40:43], v[140:143], v[188:191], v[40:43]
	v_mfma_f32_16x16x32_bf16 v[32:35], v[128:131], v[200:203], v[32:35]
	v_mfma_f32_16x16x32_bf16 v[32:35], v[132:135], v[204:207], v[32:35]
	v_mfma_f32_16x16x32_bf16 v[24:27], v[136:139], v[200:203], v[24:27]
	v_mfma_f32_16x16x32_bf16 v[24:27], v[140:143], v[204:207], v[24:27]
	v_mfma_f32_16x16x32_bf16 v[16:19], v[128:131], v[208:211], v[16:19]
	v_mfma_f32_16x16x32_bf16 v[16:19], v[132:135], v[212:215], v[16:19]
	v_mfma_f32_16x16x32_bf16 v[8:11], v[136:139], v[208:211], v[8:11]
	v_mfma_f32_16x16x32_bf16 v[8:11], v[140:143], v[212:215], v[8:11]
	v_mfma_f32_16x16x32_bf16 v[52:55], v[144:147], v[160:163], v[52:55]
	v_mfma_f32_16x16x32_bf16 v[52:55], v[148:151], v[180:183], v[52:55]
	v_mfma_f32_16x16x32_bf16 v[44:47], v[152:155], v[160:163], v[44:47]
	v_mfma_f32_16x16x32_bf16 v[44:47], v[156:159], v[180:183], v[44:47]
	v_mfma_f32_16x16x32_bf16 v[36:39], v[144:147], v[184:187], v[36:39]
	v_mfma_f32_16x16x32_bf16 v[36:39], v[148:151], v[188:191], v[36:39]
	v_mfma_f32_16x16x32_bf16 v[28:31], v[152:155], v[184:187], v[28:31]
	v_mfma_f32_16x16x32_bf16 v[28:31], v[156:159], v[188:191], v[28:31]
	v_mfma_f32_16x16x32_bf16 v[20:23], v[144:147], v[200:203], v[20:23]
	v_mfma_f32_16x16x32_bf16 v[20:23], v[148:151], v[204:207], v[20:23]
	v_mfma_f32_16x16x32_bf16 v[12:15], v[152:155], v[200:203], v[12:15]
	v_mfma_f32_16x16x32_bf16 v[12:15], v[156:159], v[204:207], v[12:15]
	s_setprio 3
	s_barrier
	v_mfma_f32_16x16x32_bf16 v[4:7], v[144:147], v[208:211], v[4:7]
	v_mfma_f32_16x16x32_bf16 v[4:7], v[148:151], v[212:215], v[4:7]
	v_mfma_f32_16x16x32_bf16 v[0:3], v[152:155], v[208:211], v[0:3]
	v_mfma_f32_16x16x32_bf16 v[0:3], v[156:159], v[212:215], v[0:3]
	s_setprio 0
	s_add_i32 s45, s45, 2
	s_add_u32 s16, s16, 0x100
	s_addc_u32 s17, s17, 0
	s_add_u32 s43, s43, 0x100
	s_addc_u32 s44, s44, 0
	s_cmp_gt_u32 s45, 41
	s_cbranch_scc0 .LBB0_2341
	s_and_b64 vcc, exec, s[10:11]
	s_cbranch_vccz .LBB0_2344
	s_barrier
